# attention exact peepholes: redundant -1e30 floor of the local max folded (mrun already floors it), '0 + p0' start of the row-sum chain folded
# speedup vs baseline: 1.0058x; 1.0006x over previous
.LBB0_246:
	s_lshl_b32 s1, s71, 2
	s_and_b32 s22, s1, 0xffffff00
	s_lshr_b32 s0, s71, 3
	s_bfe_u32 s56, s71, 0x30003
	s_or_b32 s24, s22, s72
	s_cmp_lt_i32 s24, 0x8000
	s_movk_i32 s22, 0xfff
	s_cselect_b32 s75, s22, 0x1fff
	s_bfe_u32 s0, s0, 0x10002
	s_andn2_b32 s74, s1, s75
	s_mul_i32 s0, s0, 0x1800000
	s_add_u32 s0, s96, s0
	s_addc_u32 s1, s97, 0
	s_lshl_b32 s22, s71, 4
	s_and_b32 s22, s22, 0x180
	s_add_u32 s22, s0, s22
	v_or_b32_e32 v162, s24, v167
	s_addc_u32 s23, s1, 0
	v_ashrrev_i32_e32 v163, 31, v162
	v_lshl_add_u64 v[12:13], s[22:23], 0, v[158:159]
	v_lshlrev_b64 v[0:1], 9, v[162:163]
	v_lshl_add_u64 v[8:9], v[12:13], 0, v[0:1]
	global_load_dwordx4 v[0:3], v[8:9], off
	v_or_b32_e32 v160, 8, v162
	v_ashrrev_i32_e32 v161, 31, v160
	s_add_u32 s68, s22, 0x3000000
	s_addc_u32 s69, s23, 0
	s_lshl_b32 s98, s74, 9
	s_add_u32 s100, s68, s98
	s_addc_u32 s101, s69, 0
	s_add_u32 s98, s100, 0x3000000
	s_addc_u32 s99, s101, 0
	s_sub_i32 s76, s24, s74
	s_sub_i32 s0, s76, 64
	s_waitcnt vmcnt(7)
	v_add_u32_e32 v20, s0, v172
	v_min_i32_e32 v21, s75, v20
	s_waitcnt vmcnt(6)
	v_add_u32_e32 v24, s0, v173
	v_min_i32_e32 v25, s75, v24
	s_waitcnt vmcnt(5)
	v_add_u32_e32 v28, s0, v182
	v_min_i32_e32 v29, s75, v28
	s_waitcnt vmcnt(2)
	v_add_u32_e32 v40, s0, v166
	v_min_i32_e32 v32, s75, v40
	v_add_u32_e32 v41, 16, v40
	s_movk_i32 s1, 0xffef
	v_min_i32_e32 v41, s75, v41
	v_or_b32_e32 v128, 32, v166
	v_add_u32_e32 v56, s0, v128
	v_add_u32_e32 v149, s76, v155
	v_add_u32_e32 v150, s76, v172
	v_add_u32_e32 v151, s76, v173
	v_add_u32_e32 v252, s76, v182
	v_or_b32_e32 v251, s76, v167
	v_subrev_u32_e32 v250, s76, v251
	v_or_b32_e32 v144, 8, v251
	v_subrev_u32_e32 v249, s76, v144
	v_add_u32_e32 v196, 0x60, v155
	v_add_u32_e32 v168, 0x60, v172
	v_add_u32_e32 v193, 0x60, v173
	v_add_u32_e32 v194, 0x60, v182
	v_add_u32_e32 v186, s76, v206
	s_waitcnt vmcnt(0)
	v_lshlrev_b32_e32 v4, 16, v0
	v_and_b32_e32 v5, 0xffff0000, v0
	v_lshlrev_b32_e32 v0, 16, v1
	v_and_b32_e32 v1, 0xffff0000, v1
	v_pk_mul_f32 v[4:5], v[4:5], s[58:59] op_sel_hi:[1,0]
	v_pk_mul_f32 v[0:1], v[0:1], s[58:59] op_sel_hi:[1,0]
	v_cvt_pk_bf16_f32 v4, v4, v5
	v_cvt_pk_bf16_f32 v5, v0, v1
	v_lshlrev_b32_e32 v0, 16, v2
	v_and_b32_e32 v1, 0xffff0000, v2
	v_pk_mul_f32 v[0:1], v[0:1], s[58:59] op_sel_hi:[1,0]
	s_nop 0
	v_cvt_pk_bf16_f32 v6, v0, v1
	v_lshlrev_b32_e32 v0, 16, v3
	v_and_b32_e32 v1, 0xffff0000, v3
	v_pk_mul_f32 v[0:1], v[0:1], s[58:59] op_sel_hi:[1,0]
	s_nop 0
	v_cvt_pk_bf16_f32 v7, v0, v1
	global_load_dwordx4 v[0:3], v[8:9], off offset:64
	s_waitcnt vmcnt(0)
	v_lshlrev_b32_e32 v8, 16, v0
	v_and_b32_e32 v9, 0xffff0000, v0
	v_lshlrev_b32_e32 v0, 16, v1
	v_and_b32_e32 v1, 0xffff0000, v1
	v_pk_mul_f32 v[8:9], v[8:9], s[58:59] op_sel_hi:[1,0]
	v_pk_mul_f32 v[0:1], v[0:1], s[58:59] op_sel_hi:[1,0]
	v_cvt_pk_bf16_f32 v8, v8, v9
	v_cvt_pk_bf16_f32 v9, v0, v1
	v_lshlrev_b32_e32 v0, 16, v2
	v_and_b32_e32 v1, 0xffff0000, v2
	v_pk_mul_f32 v[0:1], v[0:1], s[58:59] op_sel_hi:[1,0]
	s_nop 0
	v_cvt_pk_bf16_f32 v10, v0, v1
	v_lshlrev_b32_e32 v0, 16, v3
	v_and_b32_e32 v1, 0xffff0000, v3
	v_pk_mul_f32 v[0:1], v[0:1], s[58:59] op_sel_hi:[1,0]
	s_nop 0
	v_cvt_pk_bf16_f32 v11, v0, v1
	v_lshlrev_b64 v[0:1], 9, v[160:161]
	v_lshl_add_u64 v[16:17], v[12:13], 0, v[0:1]
	global_load_dwordx4 v[0:3], v[16:17], off
	s_waitcnt vmcnt(0)
	v_lshlrev_b32_e32 v12, 16, v0
	v_and_b32_e32 v13, 0xffff0000, v0
	v_lshlrev_b32_e32 v0, 16, v1
	v_and_b32_e32 v1, 0xffff0000, v1
	v_pk_mul_f32 v[12:13], v[12:13], s[58:59] op_sel_hi:[1,0]
	v_pk_mul_f32 v[0:1], v[0:1], s[58:59] op_sel_hi:[1,0]
	v_cvt_pk_bf16_f32 v12, v12, v13
	v_cvt_pk_bf16_f32 v13, v0, v1
	v_lshlrev_b32_e32 v0, 16, v2
	v_and_b32_e32 v1, 0xffff0000, v2
	v_pk_mul_f32 v[0:1], v[0:1], s[58:59] op_sel_hi:[1,0]
	s_nop 0
	v_cvt_pk_bf16_f32 v14, v0, v1
	v_lshlrev_b32_e32 v0, 16, v3
	v_and_b32_e32 v1, 0xffff0000, v3
	v_pk_mul_f32 v[0:1], v[0:1], s[58:59] op_sel_hi:[1,0]
	s_nop 0
	v_cvt_pk_bf16_f32 v15, v0, v1
	global_load_dwordx4 v[0:3], v[16:17], off offset:64
	s_waitcnt vmcnt(0)
	v_lshlrev_b32_e32 v16, 16, v0
	v_and_b32_e32 v17, 0xffff0000, v0
	v_pk_mul_f32 v[16:17], v[16:17], s[58:59] op_sel_hi:[1,0]
	s_nop 0
	v_cvt_pk_bf16_f32 v0, v16, v17
	v_lshlrev_b32_e32 v16, 16, v1
	v_and_b32_e32 v17, 0xffff0000, v1
	v_pk_mul_f32 v[16:17], v[16:17], s[58:59] op_sel_hi:[1,0]
	s_nop 0
	v_cvt_pk_bf16_f32 v1, v16, v17
	v_lshlrev_b32_e32 v16, 16, v2
	v_and_b32_e32 v17, 0xffff0000, v2
	v_pk_mul_f32 v[16:17], v[16:17], s[58:59] op_sel_hi:[1,0]
	s_nop 0
	v_cvt_pk_bf16_f32 v2, v16, v17
	v_lshlrev_b32_e32 v16, 16, v3
	v_and_b32_e32 v17, 0xffff0000, v3
	v_pk_mul_f32 v[16:17], v[16:17], s[58:59] op_sel_hi:[1,0]
	s_nop 0
	v_cvt_pk_bf16_f32 v3, v16, v17
	s_mov_b64 s[22:23], 0x6000000
	v_add_u32_e32 v16, s0, v155
	s_sub_i32 s22, 0x80, s76
	s_nop 0
	v_med3_i32 v16, v16, 0, s75
	v_cmp_lt_i32_e32 vcc, -1, v20
	s_nop 1
	v_cndmask_b32_e32 v20, 0, v21, vcc
	v_cmp_lt_i32_e32 vcc, -1, v24
	s_nop 1
	v_cndmask_b32_e32 v24, 0, v25, vcc
	v_cmp_lt_i32_e32 vcc, -1, v28
	s_nop 1
	v_cndmask_b32_e32 v28, 0, v29, vcc
	v_lshl_add_u32 v16, v16, 9, v152
	global_load_dwordx4 v[16:19], v16, s[98:99]
	v_lshl_add_u32 v20, v20, 9, v152
	v_cmp_lt_i32_e32 vcc, -1, v40
	global_load_dwordx4 v[20:23], v20, s[98:99]
	v_lshl_add_u32 v24, v24, 9, v152
	v_cndmask_b32_e32 v32, 0, v32, vcc
	v_cmp_lt_i32_e32 vcc, s1, v40
	global_load_dwordx4 v[24:27], v24, s[98:99]
	v_lshl_add_u32 v28, v28, 9, v152
	v_cndmask_b32_e32 v40, 0, v41, vcc
	global_load_dwordx4 v[28:31], v28, s[98:99]
	v_lshl_add_u32 v36, v32, 9, v158
	v_lshl_add_u32 v40, v40, 9, v158
	s_sub_i32 s1, s76, 32
	global_load_dwordx4 v[32:35], v36, s[100:101]
	s_nop 0
	global_load_dwordx4 v[36:39], v36, s[100:101] offset:64
	s_nop 0
	global_load_dwordx4 v[48:51], v40, s[100:101]
	global_load_dwordx4 v[52:55], v40, s[100:101] offset:64
	v_add_u32_e32 v40, s1, v155
	v_med3_i32 v40, v40, 0, s75
	v_lshl_add_u32 v40, v40, 9, v152
	global_load_dwordx4 v[76:79], v40, s[98:99]
	v_add_u32_e32 v40, s1, v172
	v_med3_i32 v40, v40, 0, s75
	v_lshl_add_u32 v40, v40, 9, v152
	global_load_dwordx4 v[84:87], v40, s[98:99]
	v_add_u32_e32 v40, s1, v173
	v_med3_i32 v40, v40, 0, s75
	v_lshl_add_u32 v40, v40, 9, v152
	global_load_dwordx4 v[88:91], v40, s[98:99]
	v_add_u32_e32 v40, s1, v182
	s_min_i32 s1, s0, 0
	s_sub_i32 s1, 0, s1
	v_med3_i32 v40, v40, 0, s75
	v_lshl_add_u32 v40, v40, 9, v152
	global_load_dwordx4 v[92:95], v40, s[98:99]
	v_min_i32_e32 v40, s75, v56
	v_cmp_lt_i32_e32 vcc, -1, v56
	v_add_u32_e32 v56, 16, v56
	s_nop 0
	v_cndmask_b32_e32 v40, 0, v40, vcc
	v_med3_i32 v56, v56, 0, s75
	v_lshl_add_u32 v44, v40, 9, v158
	v_lshl_add_u32 v60, v56, 9, v158
	global_load_dwordx4 v[40:43], v44, s[100:101]
	s_nop 0
	global_load_dwordx4 v[44:47], v44, s[100:101] offset:64
	s_nop 0
	global_load_dwordx4 v[56:59], v60, s[100:101]
	s_nop 0
	global_load_dwordx4 v[60:63], v60, s[100:101] offset:64
	s_waitcnt vmcnt(15)
	ds_write_b128 v241, v[16:19]
	s_waitcnt vmcnt(14)
	ds_write_b128 v242, v[20:23]
	s_waitcnt vmcnt(13)
	ds_write_b128 v243, v[24:27]
	s_waitcnt vmcnt(12)
	ds_write_b128 v244, v[28:31]
	v_or_b32_e32 v24, 16, v166
	v_add_u32_e32 v24, s76, v24
	v_med3_i32 v16, v149, 0, s75
	v_lshl_add_u32 v16, v16, 9, v152
	global_load_dwordx4 v[64:67], v16, s[98:99]
	s_sub_i32 s0, s75, s0
	v_med3_i32 v16, v150, 0, s75
	v_lshl_add_u32 v16, v16, 9, v152
	global_load_dwordx4 v[68:71], v16, s[98:99]
	v_max_i32_e32 v147, s1, v250
	v_max_i32_e32 v148, s1, v249
	v_med3_i32 v16, v151, 0, s75
	v_lshl_add_u32 v16, v16, 9, v152
	global_load_dwordx4 v[72:75], v16, s[98:99]
	v_med3_i32 v16, v252, 0, s75
	v_lshl_add_u32 v16, v16, 9, v152
	global_load_dwordx4 v[80:83], v16, s[98:99]
	v_add_u32_e32 v16, s76, v166
	v_med3_i32 v16, v16, 0, s75
	v_med3_i32 v24, v24, 0, s75
	v_lshl_add_u32 v20, v16, 9, v158
	v_lshl_add_u32 v28, v24, 9, v158
	global_load_dwordx4 v[16:19], v20, s[100:101]
	s_nop 0
	global_load_dwordx4 v[20:23], v20, s[100:101] offset:64
	s_nop 0
	global_load_dwordx4 v[24:27], v28, s[100:101]
	s_nop 0
	global_load_dwordx4 v[28:31], v28, s[100:101] offset:64
	ds_read_b64_tr_b16 v[98:99], v169 offset:2304
	ds_read_b64_tr_b16 v[96:97], v169
	ds_read_b64_tr_b16 v[100:101], v169 offset:32
	ds_read_b64_tr_b16 v[102:103], v169 offset:2336
	ds_read_b64_tr_b16 v[116:117], v169 offset:64
	ds_read_b64_tr_b16 v[118:119], v169 offset:2368
	ds_read_b64_tr_b16 v[134:135], v169 offset:96
	ds_read_b64_tr_b16 v[136:137], v169 offset:2400
	s_waitcnt vmcnt(15)
	ds_write_b128 v241, v[76:79] offset:4608
	s_waitcnt vmcnt(14)
	ds_write_b128 v242, v[84:87] offset:4608
	s_waitcnt vmcnt(13)
	ds_write_b128 v243, v[88:91] offset:4608
	s_waitcnt vmcnt(12)
	ds_write_b128 v244, v[92:95] offset:4608
	v_mfma_f32_16x16x32_bf16 v[76:79], v[32:35], v[4:7], 0
	v_mfma_f32_16x16x32_bf16 v[32:35], v[32:35], v[12:15], 0
	v_mfma_f32_16x16x32_bf16 v[76:79], v[36:39], v[8:11], v[76:79]
	v_mfma_f32_16x16x32_bf16 v[84:87], v[48:51], v[4:7], 0
	v_mfma_f32_16x16x32_bf16 v[32:35], v[36:39], v[0:3], v[32:35]
	v_mfma_f32_16x16x32_bf16 v[36:39], v[48:51], v[12:15], 0
	v_add_u32_e32 v48, s22, v251
	v_min3_i32 v48, v48, s0, v245
	v_sub_u32_e32 v49, v154, v147
	v_sub_u32_e32 v146, v48, v147
	v_add_u32_e32 v48, s22, v144
	v_min3_i32 v48, v48, s0, v245
	v_add_u32_e32 v51, 1, v49
	v_sub_u32_e32 v145, v48, v148
	v_cmp_gt_u32_e64 s[0:1], v51, v146
	v_cmp_gt_u32_e32 vcc, v49, v146
	s_nop 0
	v_cndmask_b32_e64 v77, v77, v246, s[0:1]
	s_nop 0
	v_cndmask_b32_e32 v76, v76, v246, vcc
	v_mfma_f32_16x16x32_bf16 v[84:87], v[52:55], v[8:11], v[84:87]
	v_max_f32_e32 v48, v76, v77
	v_add_u32_e32 v51, 2, v49
	v_cmp_gt_u32_e64 s[22:23], v51, v146
	v_mfma_f32_16x16x32_bf16 v[36:39], v[52:55], v[0:3], v[36:39]
	v_add_u32_e32 v52, 3, v49
	v_cmp_gt_u32_e64 s[24:25], v52, v146
	v_cndmask_b32_e64 v78, v78, v246, s[22:23]
	v_sub_u32_e32 v50, v154, v148
	v_cndmask_b32_e64 v79, v79, v246, s[24:25]
	v_max3_f32 v48, v48, v78, v79
	v_add_u32_e32 v51, 16, v49
	v_add_u32_e32 v52, 17, v49
	v_cmp_gt_u32_e64 s[26:27], v51, v146
	v_cmp_gt_u32_e64 s[28:29], v52, v146
	v_cmp_gt_u32_e64 s[38:39], v50, v145
	v_cndmask_b32_e64 v84, v84, v246, s[26:27]
	v_cndmask_b32_e64 v85, v85, v246, s[28:29]
	v_max3_f32 v48, v48, v84, v85
	v_add_u32_e32 v51, 18, v49
	v_add_u32_e32 v49, 19, v49
	v_cmp_gt_u32_e64 s[30:31], v51, v146
	v_cmp_gt_u32_e64 s[34:35], v49, v146
	v_add_u32_e32 v52, 3, v50
	v_cndmask_b32_e64 v86, v86, v246, s[30:31]
	v_cndmask_b32_e64 v87, v87, v246, s[34:35]
	v_max3_f32 v48, v48, v86, v87
	v_add_u32_e32 v51, 1, v50
	v_cmp_gt_u32_e64 s[40:41], v51, v145
	v_cndmask_b32_e64 v32, v32, v246, s[38:39]
	s_nop 0
	v_cndmask_b32_e64 v33, v33, v246, s[40:41]
	v_max_f32_e32 v49, v32, v33
	v_add_u32_e32 v51, 2, v50
	v_cmp_gt_u32_e64 s[42:43], v51, v145
	v_cmp_gt_u32_e64 s[44:45], v52, v145
	s_nop 0
	v_cndmask_b32_e64 v34, v34, v246, s[42:43]
	v_cndmask_b32_e64 v35, v35, v246, s[44:45]
	v_max3_f32 v49, v49, v34, v35
	v_add_u32_e32 v51, 16, v50
	v_add_u32_e32 v52, 17, v50
	v_cmp_gt_u32_e64 s[46:47], v51, v145
	v_cmp_gt_u32_e64 s[48:49], v52, v145
	s_nop 0
	v_cndmask_b32_e64 v36, v36, v246, s[46:47]
	v_cndmask_b32_e64 v37, v37, v246, s[48:49]
	v_max3_f32 v49, v49, v36, v37
	v_add_u32_e32 v51, 18, v50
	v_add_u32_e32 v50, 19, v50
	v_cmp_gt_u32_e64 s[50:51], v51, v145
	v_cmp_gt_u32_e64 s[52:53], v50, v145
	s_nop 0
	v_cndmask_b32_e64 v38, v38, v246, s[50:51]
	v_cndmask_b32_e64 v39, v39, v246, s[52:53]
	v_max3_f32 v49, v49, v38, v39
	v_mov_b32_e32 v50, v48
	s_nop 1
	v_permlane32_swap_b32_e32 v50, v48
	v_max_f32_e32 v48, v48, v50
	v_mov_b32_e32 v50, v49
	s_nop 1
	v_permlane32_swap_b32_e32 v50, v49
	v_max_f32_e32 v49, v49, v50
	v_mov_b32_e32 v50, v48
	s_nop 1
	v_permlane16_swap_b32_e32 v50, v48
	v_max_f32_e32 v48, v48, v50
	v_mov_b32_e32 v50, v49
	s_nop 1
	v_permlane16_swap_b32_e32 v50, v49
	v_max_f32_e32 v129, s73, v48
	v_sub_f32_e32 v48, 0xf149f2ca, v129
	v_max_f32_e32 v49, v49, v50
	v_exp_f32_e32 v50, v48
	v_sub_f32_e32 v48, v76, v129
	v_exp_f32_e32 v48, v48
	v_sub_f32_e32 v52, v77, v129
	v_max_f32_e32 v131, s73, v49
	v_exp_f32_e32 v52, v52
	v_sub_f32_e32 v36, v36, v131
	v_sub_f32_e32 v53, v78, v129
	v_exp_f32_e32 v36, v36
	v_exp_f32_e32 v53, v53
	v_sub_f32_e32 v54, v79, v129
	v_cndmask_b32_e64 v51, v48, 0, vcc
	v_exp_f32_e32 v54, v54
	v_sub_f32_e32 v55, v84, v129
	v_exp_f32_e32 v55, v55
	v_sub_f32_e32 v76, v85, v129
	v_add_f32_e32 v48, v52, v51
	v_exp_f32_e32 v76, v76
	v_sub_f32_e32 v77, v86, v129
	v_cvt_pk_bf16_f32 v52, v51, v52
	v_cndmask_b32_e64 v51, v36, 0, s[46:47]
	v_sub_f32_e32 v36, v37, v131
	v_exp_f32_e32 v77, v77
	v_sub_f32_e32 v78, v87, v129
	v_exp_f32_e32 v36, v36
	v_add_f32_e32 v48, v53, v48
	v_exp_f32_e32 v78, v78
	v_add_f32_e32 v48, v54, v48
	v_sub_f32_e32 v32, v32, v131
	v_add_f32_e32 v48, v55, v48
	v_exp_f32_e32 v32, v32
	v_sub_f32_e32 v33, v33, v131
	v_add_f32_e32 v48, v76, v48
	v_cvt_pk_bf16_f32 v53, v53, v54
	v_cvt_pk_bf16_f32 v54, v55, v76
	v_exp_f32_e32 v33, v33
	v_sub_f32_e32 v34, v34, v131
	v_cndmask_b32_e64 v76, v36, 0, s[48:49]
	v_sub_f32_e32 v36, v38, v131
	v_add_f32_e32 v48, v77, v48
	v_exp_f32_e32 v34, v34
	v_sub_f32_e32 v35, v35, v131
	v_exp_f32_e32 v36, v36
	v_add_f32_e32 v130, v78, v48
	v_exp_f32_e32 v35, v35
	v_mul_f32_e32 v48, 0, v50
	v_fmac_f32_e32 v130, 0, v50
	v_cndmask_b32_e64 v50, v32, 0, s[38:39]
	v_cvt_pk_bf16_f32 v55, v77, v78
	v_add_f32_e32 v32, v33, v50
	v_cndmask_b32_e64 v77, v36, 0, s[50:51]
	v_sub_f32_e32 v36, v39, v131
	v_sub_f32_e32 v49, 0xf149f2ca, v131
	v_add_f32_e32 v32, v34, v32
	v_exp_f32_e32 v36, v36
	v_exp_f32_e32 v49, v49
	v_add_f32_e32 v32, v35, v32
	v_add_f32_e32 v32, v51, v32
	v_add_f32_e32 v32, v76, v32
	v_add_f32_e32 v32, v77, v32
	v_cndmask_b32_e64 v39, v36, 0, s[52:53]
	v_add_f32_e32 v132, v39, v32
	v_mul_f32_e32 v32, 0, v49
	v_fmac_f32_e32 v132, 0, v49
	v_cvt_pk_bf16_f32 v36, v50, v33
	v_cvt_pk_bf16_f32 v37, v34, v35
	v_cvt_pk_bf16_f32 v38, v51, v76
	v_cvt_pk_bf16_f32 v39, v77, v39
	v_mov_b32_e32 v49, v48
	v_mov_b32_e32 v50, v48
	v_mov_b32_e32 v51, v48
	v_mov_b32_e32 v33, v32
	v_mov_b32_e32 v34, v32
	v_mov_b32_e32 v35, v32
	s_waitcnt lgkmcnt(6)
	v_mfma_f32_16x16x32_bf16 v[112:115], v[116:119], v[52:55], v[48:51]
	v_mfma_f32_16x16x32_bf16 v[124:127], v[96:99], v[36:39], v[32:35]
	v_mfma_f32_16x16x32_bf16 v[108:111], v[100:103], v[36:39], v[32:35]
	v_mfma_f32_16x16x32_bf16 v[116:119], v[116:119], v[36:39], v[32:35]
	s_waitcnt lgkmcnt(4)
	v_mfma_f32_16x16x32_bf16 v[88:91], v[134:137], v[36:39], v[32:35]
	s_nop 2
	v_add_u32_e32 v32, 32, v155
	v_add_u32_e32 v32, s76, v32
	v_mfma_f32_16x16x32_bf16 v[120:123], v[96:99], v[52:55], v[48:51]
	s_nop 0
	v_med3_i32 v32, v32, 0, s75
	v_lshl_add_u32 v32, v32, 9, v152
	global_load_dwordx4 v[76:79], v32, s[98:99]
	v_add_u32_e32 v32, 32, v172
	v_add_u32_e32 v32, s76, v32
	v_mfma_f32_16x16x32_bf16 v[104:107], v[100:103], v[52:55], v[48:51]
	s_nop 0
	v_med3_i32 v32, v32, 0, s75
	v_lshl_add_u32 v32, v32, 9, v152
	global_load_dwordx4 v[84:87], v32, s[98:99]
	v_add_u32_e32 v32, 32, v173
	v_add_u32_e32 v32, s76, v32
	v_mfma_f32_16x16x32_bf16 v[96:99], v[134:137], v[52:55], v[48:51]
	s_nop 0
	v_med3_i32 v32, v32, 0, s75
	v_lshl_add_u32 v32, v32, 9, v152
	global_load_dwordx4 v[92:95], v32, s[98:99]
	v_add_u32_e32 v32, 32, v182
	v_add_u32_e32 v32, s76, v32
	v_or_b32_e32 v48, 48, v166
	v_add_u32_e32 v48, s76, v48
	v_med3_i32 v32, v32, 0, s75
	v_lshl_add_u32 v32, v32, 9, v152
	global_load_dwordx4 v[100:103], v32, s[98:99]
	v_add_u32_e32 v32, s76, v128
	s_nop 0
	v_med3_i32 v32, v32, 0, s75
	v_med3_i32 v48, v48, 0, s75
	v_lshl_add_u32 v36, v32, 9, v158
	v_lshl_add_u32 v52, v48, 9, v158
	global_load_dwordx4 v[32:35], v36, s[100:101]
	s_nop 0
	global_load_dwordx4 v[36:39], v36, s[100:101] offset:64
	s_nop 0
	global_load_dwordx4 v[48:51], v52, s[100:101]
	s_nop 0
	global_load_dwordx4 v[52:55], v52, s[100:101] offset:64
	ds_read_b64_tr_b16 v[136:137], v169 offset:6912
	ds_read_b64_tr_b16 v[134:135], v169 offset:4608
	ds_read_b64_tr_b16 v[138:139], v169 offset:4640
	ds_read_b64_tr_b16 v[140:141], v169 offset:6944
	ds_read_b64_tr_b16 v[176:177], v169 offset:4672
	ds_read_b64_tr_b16 v[178:179], v169 offset:6976
	ds_read_b64_tr_b16 v[188:189], v169 offset:4704
	ds_read_b64_tr_b16 v[190:191], v169 offset:7008
	s_waitcnt vmcnt(15)
	ds_write_b128 v241, v[64:67]
	s_waitcnt vmcnt(14)
	ds_write_b128 v242, v[68:71]
	s_waitcnt vmcnt(13)
	ds_write_b128 v243, v[72:75]
	s_waitcnt vmcnt(12)
	ds_write_b128 v244, v[80:83]
	v_mfma_f32_16x16x32_bf16 v[64:67], v[40:43], v[4:7], 0
	v_mfma_f32_16x16x32_bf16 v[40:43], v[40:43], v[12:15], 0
	v_mfma_f32_16x16x32_bf16 v[64:67], v[44:47], v[8:11], v[64:67]
	v_mfma_f32_16x16x32_bf16 v[68:71], v[56:59], v[4:7], 0
	v_mfma_f32_16x16x32_bf16 v[40:43], v[44:47], v[0:3], v[40:43]
	v_mfma_f32_16x16x32_bf16 v[44:47], v[56:59], v[12:15], 0
	v_sub_u32_e32 v56, v187, v147
	v_add_u32_e32 v59, 1, v56
	s_nop 2
	v_cmp_gt_u32_e64 s[0:1], v59, v146
	v_cmp_gt_u32_e32 vcc, v56, v146
	s_nop 0
	v_cndmask_b32_e64 v65, v65, v246, s[0:1]
	s_nop 0
	v_cndmask_b32_e32 v64, v64, v246, vcc
	v_mfma_f32_16x16x32_bf16 v[68:71], v[60:63], v[8:11], v[68:71]
	v_max_f32_e32 v58, v64, v65
	v_add_u32_e32 v59, 2, v56
	v_cmp_gt_u32_e64 s[22:23], v59, v146
	v_mfma_f32_16x16x32_bf16 v[44:47], v[60:63], v[0:3], v[44:47]
	v_add_u32_e32 v60, 3, v56
	v_cmp_gt_u32_e64 s[24:25], v60, v146
	v_cndmask_b32_e64 v66, v66, v246, s[22:23]
	v_sub_u32_e32 v57, v187, v148
	v_cndmask_b32_e64 v67, v67, v246, s[24:25]
	v_max3_f32 v58, v58, v66, v67
	v_add_u32_e32 v59, 16, v56
	v_add_u32_e32 v60, 17, v56
	v_cmp_gt_u32_e64 s[26:27], v59, v146
	v_cmp_gt_u32_e64 s[28:29], v60, v146
	v_cmp_gt_u32_e64 s[38:39], v57, v145
	v_cndmask_b32_e64 v68, v68, v246, s[26:27]
	v_cndmask_b32_e64 v69, v69, v246, s[28:29]
	v_max3_f32 v58, v58, v68, v69
	v_add_u32_e32 v59, 18, v56
	v_add_u32_e32 v56, 19, v56
	v_cmp_gt_u32_e64 s[30:31], v59, v146
	v_cmp_gt_u32_e64 s[34:35], v56, v146
	v_add_u32_e32 v60, 3, v57
	v_cndmask_b32_e64 v70, v70, v246, s[30:31]
	v_cndmask_b32_e64 v71, v71, v246, s[34:35]
	v_max3_f32 v56, v58, v70, v71
	v_add_u32_e32 v59, 1, v57
	v_cmp_gt_u32_e64 s[40:41], v59, v145
	v_cndmask_b32_e64 v40, v40, v246, s[38:39]
	s_nop 0
	v_cndmask_b32_e64 v41, v41, v246, s[40:41]
	v_max_f32_e32 v58, v40, v41
	v_add_u32_e32 v59, 2, v57
	v_cmp_gt_u32_e64 s[42:43], v59, v145
	v_cmp_gt_u32_e64 s[44:45], v60, v145
	s_nop 0
	v_cndmask_b32_e64 v42, v42, v246, s[42:43]
	v_cndmask_b32_e64 v43, v43, v246, s[44:45]
	v_max3_f32 v58, v58, v42, v43
	v_add_u32_e32 v59, 16, v57
	v_add_u32_e32 v60, 17, v57
	v_cmp_gt_u32_e64 s[46:47], v59, v145
	v_cmp_gt_u32_e64 s[48:49], v60, v145
	s_nop 0
	v_cndmask_b32_e64 v44, v44, v246, s[46:47]
	v_cndmask_b32_e64 v45, v45, v246, s[48:49]
	v_max3_f32 v58, v58, v44, v45
	v_add_u32_e32 v59, 18, v57
	v_add_u32_e32 v57, 19, v57
	v_cmp_gt_u32_e64 s[50:51], v59, v145
	v_cmp_gt_u32_e64 s[52:53], v57, v145
	s_nop 0
	v_cndmask_b32_e64 v46, v46, v246, s[50:51]
	v_cndmask_b32_e64 v47, v47, v246, s[52:53]
	v_max3_f32 v57, v58, v46, v47
	v_mov_b32_e32 v58, v56
	s_nop 1
	v_permlane32_swap_b32_e32 v58, v56
	v_max_f32_e32 v56, v56, v58
	v_mov_b32_e32 v58, v57
	s_nop 1
	v_permlane32_swap_b32_e32 v58, v57
	v_max_f32_e32 v57, v57, v58
	v_mov_b32_e32 v58, v56
	s_nop 1
	v_permlane16_swap_b32_e32 v58, v56
	v_max_f32_e32 v56, v56, v58
	v_mov_b32_e32 v58, v57
	v_mov_b32_e32 v61, v57
	v_max_f32_e32 v128, v129, v56
	s_nop 0
	v_permlane16_swap_b32_e32 v58, v61
	v_sub_f32_e32 v56, v129, v128
	v_exp_f32_e32 v60, v56
	v_sub_f32_e32 v56, v64, v128
	v_max_f32_e32 v62, v57, v58
	v_exp_f32_e32 v56, v56
	v_sub_f32_e32 v58, v65, v128
	v_exp_f32_e32 v58, v58
	v_sub_f32_e32 v59, v66, v128
	v_exp_f32_e32 v59, v59
	v_sub_f32_e32 v63, v67, v128
	v_exp_f32_e32 v63, v63
	v_sub_f32_e32 v64, v68, v128
	v_exp_f32_e32 v64, v64
	v_sub_f32_e32 v65, v69, v128
	v_exp_f32_e32 v65, v65
	v_sub_f32_e32 v66, v70, v128
	v_add_f32_e32 v57, v58, v56
	v_exp_f32_e32 v66, v66
	v_sub_f32_e32 v67, v71, v128
	v_add_f32_e32 v57, v59, v57
	v_exp_f32_e32 v67, v67
	v_add_f32_e32 v57, v63, v57
	v_add_f32_e32 v57, v64, v57
	v_add_f32_e32 v57, v65, v57
	v_add_f32_e32 v57, v66, v57
	v_add_f32_e32 v129, v67, v57
	v_fmac_f32_e32 v129, v130, v60
	v_max3_f32 v130, v131, v62, v61
	v_sub_f32_e32 v40, v40, v130
	v_exp_f32_e32 v40, v40
	v_sub_f32_e32 v41, v41, v130
	v_exp_f32_e32 v41, v41
	v_sub_f32_e32 v42, v42, v130
	v_exp_f32_e32 v42, v42
	v_sub_f32_e32 v43, v43, v130
	v_exp_f32_e32 v43, v43
	v_sub_f32_e32 v44, v44, v130
	v_sub_f32_e32 v61, v131, v130
	v_exp_f32_e32 v44, v44
	v_sub_f32_e32 v45, v45, v130
	v_exp_f32_e32 v62, v61
	v_exp_f32_e32 v45, v45
	v_sub_f32_e32 v46, v46, v130
	v_add_f32_e32 v61, v41, v40
	v_exp_f32_e32 v46, v46
	v_sub_f32_e32 v47, v47, v130
	v_add_f32_e32 v61, v42, v61
	v_exp_f32_e32 v47, v47
	v_add_f32_e32 v61, v43, v61
	v_add_f32_e32 v61, v44, v61
	v_add_f32_e32 v61, v45, v61
	v_add_f32_e32 v61, v46, v61
	v_cvt_pk_bf16_f32 v56, v56, v58
	v_cvt_pk_bf16_f32 v57, v59, v63
	v_cvt_pk_bf16_f32 v58, v64, v65
	v_cvt_pk_bf16_f32 v59, v66, v67
	v_add_f32_e32 v131, v47, v61
	v_cvt_pk_bf16_f32 v40, v40, v41
	v_cvt_pk_bf16_f32 v41, v42, v43
	v_cvt_pk_bf16_f32 v42, v44, v45
	v_cvt_pk_bf16_f32 v43, v46, v47
	v_pk_mul_f32 v[46:47], v[122:123], v[60:61] op_sel_hi:[1,0]
	v_pk_mul_f32 v[44:45], v[120:121], v[60:61] op_sel_hi:[1,0]
	v_fmac_f32_e32 v131, v132, v62
	s_waitcnt lgkmcnt(10)
	v_mfma_f32_16x16x32_bf16 v[64:67], v[134:137], v[56:59], v[44:47]
	s_nop 2
	v_mul_f32_e64 v46, v126, v62
	v_mul_f32_e64 v47, v127, v62
	v_pk_mul_f32 v[44:45], v[124:125], v[62:63] op_sel_hi:[1,0]
	s_nop 1
	v_mfma_f32_16x16x32_bf16 v[68:71], v[134:137], v[40:43], v[44:47]
	s_nop 2
	v_mul_f32_e64 v46, v106, v60
	v_mul_f32_e64 v47, v107, v60
	v_pk_mul_f32 v[44:45], v[104:105], v[60:61] op_sel_hi:[1,0]
	s_waitcnt lgkmcnt(8)
	s_nop 0
	v_mfma_f32_16x16x32_bf16 v[104:107], v[138:141], v[56:59], v[44:47]
	s_nop 2
	v_mul_f32_e64 v46, v110, v62
	v_mul_f32_e64 v47, v111, v62
	v_pk_mul_f32 v[44:45], v[108:109], v[62:63] op_sel_hi:[1,0]
	s_nop 1
	v_mfma_f32_16x16x32_bf16 v[108:111], v[138:141], v[40:43], v[44:47]
	s_nop 2
	v_mul_f32_e64 v46, v114, v60
	v_mul_f32_e64 v47, v115, v60
	v_pk_mul_f32 v[44:45], v[112:113], v[60:61] op_sel_hi:[1,0]
	s_waitcnt lgkmcnt(6)
	s_nop 0
	v_mfma_f32_16x16x32_bf16 v[112:115], v[176:179], v[56:59], v[44:47]
	s_nop 2
	v_mul_f32_e64 v46, v118, v62
	v_mul_f32_e64 v47, v119, v62
	v_pk_mul_f32 v[44:45], v[116:117], v[62:63] op_sel_hi:[1,0]
	s_nop 1
	v_mfma_f32_16x16x32_bf16 v[116:119], v[176:179], v[40:43], v[44:47]
	s_nop 2
	v_mul_f32_e64 v46, v98, v60
	v_mul_f32_e64 v47, v99, v60
	v_pk_mul_f32 v[44:45], v[96:97], v[60:61] op_sel_hi:[1,0]
	s_waitcnt lgkmcnt(4)
	s_nop 0
	v_mfma_f32_16x16x32_bf16 v[120:123], v[188:191], v[56:59], v[44:47]
	v_or_b32_e32 v56, 0x50, v166
	v_add_u32_e32 v56, s76, v56
	s_nop 0
	v_pk_mul_f32 v[46:47], v[90:91], v[62:63] op_sel_hi:[1,0]
	v_pk_mul_f32 v[44:45], v[88:89], v[62:63] op_sel_hi:[1,0]
	s_nop 1
	v_mfma_f32_16x16x32_bf16 v[124:127], v[188:191], v[40:43], v[44:47]
	v_add_u32_e32 v40, 64, v155
	v_add_u32_e32 v40, s76, v40
	v_med3_i32 v40, v40, 0, s75
	v_lshl_add_u32 v40, v40, 9, v152
	global_load_dwordx4 v[72:75], v40, s[98:99]
	v_add_u32_e32 v40, 64, v172
	v_add_u32_e32 v40, s76, v40
	v_med3_i32 v40, v40, 0, s75
	v_lshl_add_u32 v40, v40, 9, v152
	global_load_dwordx4 v[80:83], v40, s[98:99]
	v_add_u32_e32 v40, 64, v173
	v_add_u32_e32 v40, s76, v40
	v_med3_i32 v40, v40, 0, s75
	v_lshl_add_u32 v40, v40, 9, v152
	global_load_dwordx4 v[88:91], v40, s[98:99]
	v_add_u32_e32 v40, 64, v182
	v_add_u32_e32 v40, s76, v40
	v_med3_i32 v40, v40, 0, s75
	v_lshl_add_u32 v40, v40, 9, v152
	global_load_dwordx4 v[96:99], v40, s[98:99]
	v_or_b32_e32 v40, 64, v166
	v_add_u32_e32 v40, s76, v40
	v_med3_i32 v40, v40, 0, s75
	v_med3_i32 v56, v56, 0, s75
	v_lshl_add_u32 v44, v40, 9, v158
	v_lshl_add_u32 v60, v56, 9, v158
	global_load_dwordx4 v[40:43], v44, s[100:101]
	s_nop 0
	global_load_dwordx4 v[44:47], v44, s[100:101] offset:64
	s_nop 0
	global_load_dwordx4 v[56:59], v60, s[100:101]
	s_nop 0
	global_load_dwordx4 v[60:63], v60, s[100:101] offset:64
	ds_read_b64_tr_b16 v[136:137], v169 offset:2304
	ds_read_b64_tr_b16 v[134:135], v169
	ds_read_b64_tr_b16 v[138:139], v169 offset:32
	ds_read_b64_tr_b16 v[140:141], v169 offset:2336
	ds_read_b64_tr_b16 v[176:177], v169 offset:64
	ds_read_b64_tr_b16 v[178:179], v169 offset:2368
	ds_read_b64_tr_b16 v[188:189], v169 offset:96
	ds_read_b64_tr_b16 v[190:191], v169 offset:2400
	s_waitcnt vmcnt(15)
	ds_write_b128 v241, v[76:79] offset:4608
	s_waitcnt vmcnt(14)
	ds_write_b128 v242, v[84:87] offset:4608
	s_waitcnt vmcnt(13)
	ds_write_b128 v243, v[92:95] offset:4608
	s_waitcnt vmcnt(12)
	ds_write_b128 v244, v[100:103] offset:4608
	v_mfma_f32_16x16x32_bf16 v[76:79], v[16:19], v[4:7], 0
	v_mfma_f32_16x16x32_bf16 v[16:19], v[16:19], v[12:15], 0
	v_mfma_f32_16x16x32_bf16 v[76:79], v[20:23], v[8:11], v[76:79]
	v_mfma_f32_16x16x32_bf16 v[84:87], v[24:27], v[4:7], 0
	v_mfma_f32_16x16x32_bf16 v[16:19], v[20:23], v[0:3], v[16:19]
	v_mfma_f32_16x16x32_bf16 v[20:23], v[24:27], v[12:15], 0
	v_sub_u32_e32 v24, v192, v147
	v_add_u32_e32 v27, 1, v24
	s_nop 2
	v_cmp_gt_u32_e64 s[0:1], v27, v146
	v_cmp_gt_u32_e32 vcc, v24, v146
	s_nop 0
	v_cndmask_b32_e64 v77, v77, v246, s[0:1]
	s_nop 0
	v_cndmask_b32_e32 v76, v76, v246, vcc
	v_mfma_f32_16x16x32_bf16 v[84:87], v[28:31], v[8:11], v[84:87]
	v_max_f32_e32 v26, v76, v77
	v_add_u32_e32 v27, 2, v24
	v_cmp_gt_u32_e64 s[22:23], v27, v146
	v_mfma_f32_16x16x32_bf16 v[20:23], v[28:31], v[0:3], v[20:23]
	v_add_u32_e32 v28, 3, v24
	v_cmp_gt_u32_e64 s[24:25], v28, v146
	v_cndmask_b32_e64 v78, v78, v246, s[22:23]
	v_sub_u32_e32 v25, v192, v148
	v_cndmask_b32_e64 v79, v79, v246, s[24:25]
	v_max3_f32 v26, v26, v78, v79
	v_add_u32_e32 v27, 16, v24
	v_add_u32_e32 v28, 17, v24
	v_cmp_gt_u32_e64 s[26:27], v27, v146
	v_cmp_gt_u32_e64 s[28:29], v28, v146
	v_cmp_gt_u32_e64 s[38:39], v25, v145
	v_cndmask_b32_e64 v84, v84, v246, s[26:27]
	v_cndmask_b32_e64 v85, v85, v246, s[28:29]
	v_max3_f32 v26, v26, v84, v85
	v_add_u32_e32 v27, 18, v24
	v_add_u32_e32 v24, 19, v24
	v_cmp_gt_u32_e64 s[30:31], v27, v146
	v_cmp_gt_u32_e64 s[34:35], v24, v146
	v_add_u32_e32 v28, 3, v25
	v_cndmask_b32_e64 v86, v86, v246, s[30:31]
	v_cndmask_b32_e64 v87, v87, v246, s[34:35]
	v_max3_f32 v24, v26, v86, v87
	v_add_u32_e32 v27, 1, v25
	v_cmp_gt_u32_e64 s[40:41], v27, v145
	v_cndmask_b32_e64 v16, v16, v246, s[38:39]
	s_nop 0
	v_cndmask_b32_e64 v17, v17, v246, s[40:41]
	v_max_f32_e32 v26, v16, v17
	v_add_u32_e32 v27, 2, v25
	v_cmp_gt_u32_e64 s[42:43], v27, v145
	v_cmp_gt_u32_e64 s[44:45], v28, v145
	s_nop 0
	v_cndmask_b32_e64 v18, v18, v246, s[42:43]
	v_cndmask_b32_e64 v19, v19, v246, s[44:45]
	v_max3_f32 v26, v26, v18, v19
	v_add_u32_e32 v27, 16, v25
	v_add_u32_e32 v28, 17, v25
	v_cmp_gt_u32_e64 s[46:47], v27, v145
	v_cmp_gt_u32_e64 s[48:49], v28, v145
	s_nop 0
	v_cndmask_b32_e64 v20, v20, v246, s[46:47]
	v_cndmask_b32_e64 v21, v21, v246, s[48:49]
	v_max3_f32 v26, v26, v20, v21
	v_add_u32_e32 v27, 18, v25
	v_add_u32_e32 v25, 19, v25
	v_cmp_gt_u32_e64 s[50:51], v27, v145
	v_cmp_gt_u32_e64 s[52:53], v25, v145
	s_nop 0
	v_cndmask_b32_e64 v22, v22, v246, s[50:51]
	v_cndmask_b32_e64 v23, v23, v246, s[52:53]
	v_max3_f32 v25, v26, v22, v23
	v_mov_b32_e32 v26, v24
	s_nop 1
	v_permlane32_swap_b32_e32 v26, v24
	v_max_f32_e32 v24, v24, v26
	v_mov_b32_e32 v26, v25
	s_nop 1
	v_permlane32_swap_b32_e32 v26, v25
	v_max_f32_e32 v25, v25, v26
	v_mov_b32_e32 v26, v24
	s_nop 1
	v_permlane16_swap_b32_e32 v26, v24
	v_max_f32_e32 v24, v24, v26
	v_mov_b32_e32 v26, v25
	v_mov_b32_e32 v28, v25
	v_max_f32_e32 v132, v128, v24
	s_nop 0
	v_permlane16_swap_b32_e32 v26, v28
	v_sub_f32_e32 v24, v128, v132
	v_exp_f32_e32 v92, v24
	v_sub_f32_e32 v24, v76, v132
	v_max_f32_e32 v29, v25, v26
	v_exp_f32_e32 v24, v24
	v_sub_f32_e32 v26, v77, v132
	v_exp_f32_e32 v26, v26
	v_sub_f32_e32 v27, v78, v132
	v_exp_f32_e32 v27, v27
	v_sub_f32_e32 v30, v79, v132
	v_exp_f32_e32 v30, v30
	v_sub_f32_e32 v31, v84, v132
	v_exp_f32_e32 v31, v31
	v_sub_f32_e32 v76, v85, v132
	v_exp_f32_e32 v76, v76
	v_sub_f32_e32 v77, v86, v132
	v_add_f32_e32 v25, v26, v24
	v_exp_f32_e32 v77, v77
	v_sub_f32_e32 v78, v87, v132
	v_add_f32_e32 v25, v27, v25
	v_exp_f32_e32 v78, v78
	v_add_f32_e32 v25, v30, v25
	v_add_f32_e32 v25, v31, v25
	v_add_f32_e32 v25, v76, v25
	v_add_f32_e32 v25, v77, v25
	v_add_f32_e32 v128, v78, v25
	v_fmac_f32_e32 v128, v129, v92
	v_max3_f32 v129, v130, v29, v28
	v_sub_f32_e32 v16, v16, v129
	v_exp_f32_e32 v16, v16
	v_sub_f32_e32 v17, v17, v129
	v_exp_f32_e32 v17, v17
	v_sub_f32_e32 v18, v18, v129
	v_exp_f32_e32 v18, v18
	v_sub_f32_e32 v19, v19, v129
	v_exp_f32_e32 v19, v19
	v_sub_f32_e32 v20, v20, v129
	v_sub_f32_e32 v28, v130, v129
	v_exp_f32_e32 v20, v20
	v_sub_f32_e32 v21, v21, v129
	v_cvt_pk_bf16_f32 v24, v24, v26
	v_cvt_pk_bf16_f32 v26, v31, v76
	v_exp_f32_e32 v76, v28
	v_exp_f32_e32 v21, v21
	v_sub_f32_e32 v22, v22, v129
	v_add_f32_e32 v28, v17, v16
	v_exp_f32_e32 v22, v22
	v_sub_f32_e32 v23, v23, v129
	v_add_f32_e32 v28, v18, v28
	v_exp_f32_e32 v23, v23
	v_add_f32_e32 v28, v19, v28
	v_add_f32_e32 v28, v20, v28
	v_add_f32_e32 v28, v21, v28
	v_add_f32_e32 v28, v22, v28
	v_cvt_pk_bf16_f32 v25, v27, v30
	v_cvt_pk_bf16_f32 v27, v77, v78
	v_add_f32_e32 v130, v23, v28
	v_cvt_pk_bf16_f32 v28, v16, v17
	v_cvt_pk_bf16_f32 v29, v18, v19
	v_pk_mul_f32 v[18:19], v[66:67], v[92:93] op_sel_hi:[1,0]
	v_pk_mul_f32 v[16:17], v[64:65], v[92:93] op_sel_hi:[1,0]
	v_pk_mul_f32 v[66:67], v[106:107], v[92:93] op_sel_hi:[1,0]
	v_pk_mul_f32 v[64:65], v[104:105], v[92:93] op_sel_hi:[1,0]
	v_cvt_pk_bf16_f32 v30, v20, v21
	v_cvt_pk_bf16_f32 v31, v22, v23
	s_waitcnt lgkmcnt(8)
	v_mfma_f32_16x16x32_bf16 v[104:107], v[138:141], v[24:27], v[64:67]
	v_fmac_f32_e32 v130, v131, v76
	v_pk_mul_f32 v[22:23], v[70:71], v[76:77] op_sel_hi:[1,0]
	v_pk_mul_f32 v[20:21], v[68:69], v[76:77] op_sel_hi:[1,0]
	v_pk_mul_f32 v[66:67], v[110:111], v[76:77] op_sel_hi:[1,0]
	v_pk_mul_f32 v[64:65], v[108:109], v[76:77] op_sel_hi:[1,0]
	v_mfma_f32_16x16x32_bf16 v[16:19], v[134:137], v[24:27], v[16:19]
	s_nop 0
	v_mfma_f32_16x16x32_bf16 v[108:111], v[138:141], v[28:31], v[64:67]
	s_nop 2
	v_mul_f32_e64 v66, v114, v92
	v_mul_f32_e64 v67, v115, v92
	v_pk_mul_f32 v[64:65], v[112:113], v[92:93] op_sel_hi:[1,0]
	v_mfma_f32_16x16x32_bf16 v[20:23], v[134:137], v[28:31], v[20:23]
	s_waitcnt lgkmcnt(6)
	v_mfma_f32_16x16x32_bf16 v[112:115], v[176:179], v[24:27], v[64:67]
	s_nop 2
	v_mul_f32_e64 v66, v118, v76
	v_mul_f32_e64 v67, v119, v76
	v_pk_mul_f32 v[64:65], v[116:117], v[76:77] op_sel_hi:[1,0]
	s_nop 1
	v_mfma_f32_16x16x32_bf16 v[116:119], v[176:179], v[28:31], v[64:67]
	s_nop 2
	v_mul_f32_e64 v66, v122, v92
	v_mul_f32_e64 v67, v123, v92
	v_pk_mul_f32 v[64:65], v[120:121], v[92:93] op_sel_hi:[1,0]
	s_waitcnt lgkmcnt(4)
	s_nop 0
	v_mfma_f32_16x16x32_bf16 v[120:123], v[188:191], v[24:27], v[64:67]
	v_mul_f32_e64 v26, v126, v76
	v_mul_f32_e64 v27, v127, v76
	v_pk_mul_f32 v[24:25], v[124:125], v[76:77] op_sel_hi:[1,0]
	v_or_b32_e32 v64, 0x70, v166
	s_nop 0
	v_mfma_f32_16x16x32_bf16 v[124:127], v[188:191], v[28:31], v[24:27]
	v_add_u32_e32 v64, s76, v64
	s_nop 0
	s_nop 0
	v_add_u32_e32 v24, s76, v196
	v_med3_i32 v24, v24, 0, s75
	v_lshl_add_u32 v24, v24, 9, v152
	global_load_dwordx4 v[76:79], v24, s[98:99]
	v_add_u32_e32 v24, s76, v168
	v_med3_i32 v24, v24, 0, s75
	v_lshl_add_u32 v24, v24, 9, v152
	global_load_dwordx4 v[84:87], v24, s[98:99]
	v_add_u32_e32 v24, s76, v193
	v_med3_i32 v24, v24, 0, s75
	v_lshl_add_u32 v24, v24, 9, v152
	global_load_dwordx4 v[92:95], v24, s[98:99]
	v_add_u32_e32 v24, s76, v194
	v_med3_i32 v24, v24, 0, s75
	v_lshl_add_u32 v24, v24, 9, v152
	global_load_dwordx4 v[100:103], v24, s[98:99]
	v_or_b32_e32 v24, 0x60, v166
	v_add_u32_e32 v24, s76, v24
	v_med3_i32 v24, v24, 0, s75
	v_med3_i32 v64, v64, 0, s75
	v_lshl_add_u32 v28, v24, 9, v158
	v_lshl_add_u32 v68, v64, 9, v158
	global_load_dwordx4 v[24:27], v28, s[100:101]
	s_nop 0
	global_load_dwordx4 v[28:31], v28, s[100:101] offset:64
	s_nop 0
	global_load_dwordx4 v[64:67], v68, s[100:101]
	s_nop 0
	global_load_dwordx4 v[68:71], v68, s[100:101] offset:64
	ds_read_b64_tr_b16 v[136:137], v169 offset:6912
	ds_read_b64_tr_b16 v[134:135], v169 offset:4608
	ds_read_b64_tr_b16 v[138:139], v169 offset:4640
	ds_read_b64_tr_b16 v[140:141], v169 offset:6944
	ds_read_b64_tr_b16 v[176:177], v169 offset:4672
	ds_read_b64_tr_b16 v[178:179], v169 offset:6976
	ds_read_b64_tr_b16 v[188:189], v169 offset:4704
	ds_read_b64_tr_b16 v[190:191], v169 offset:7008
	s_waitcnt vmcnt(15)
	ds_write_b128 v241, v[72:75]
	s_waitcnt vmcnt(14)
	ds_write_b128 v242, v[80:83]
	s_waitcnt vmcnt(13)
	ds_write_b128 v243, v[88:91]
	s_waitcnt vmcnt(12)
	ds_write_b128 v244, v[96:99]
	v_mfma_f32_16x16x32_bf16 v[72:75], v[32:35], v[4:7], 0
	v_mfma_f32_16x16x32_bf16 v[32:35], v[32:35], v[12:15], 0
	v_mfma_f32_16x16x32_bf16 v[72:75], v[36:39], v[8:11], v[72:75]
	v_mfma_f32_16x16x32_bf16 v[80:83], v[48:51], v[4:7], 0
	v_mfma_f32_16x16x32_bf16 v[32:35], v[36:39], v[0:3], v[32:35]
	v_mfma_f32_16x16x32_bf16 v[36:39], v[48:51], v[12:15], 0
	v_sub_u32_e32 v48, v197, v147
	v_add_u32_e32 v51, 1, v48
	s_nop 2
	v_cmp_gt_u32_e64 s[0:1], v51, v146
	v_cmp_gt_u32_e32 vcc, v48, v146
	s_nop 0
	v_cndmask_b32_e64 v73, v73, v246, s[0:1]
	s_nop 0
	v_cndmask_b32_e32 v72, v72, v246, vcc
	v_mfma_f32_16x16x32_bf16 v[80:83], v[52:55], v[8:11], v[80:83]
	v_max_f32_e32 v50, v72, v73
	v_add_u32_e32 v51, 2, v48
	v_cmp_gt_u32_e64 s[22:23], v51, v146
	v_mfma_f32_16x16x32_bf16 v[36:39], v[52:55], v[0:3], v[36:39]
	v_add_u32_e32 v52, 3, v48
	v_cmp_gt_u32_e64 s[24:25], v52, v146
	v_cndmask_b32_e64 v74, v74, v246, s[22:23]
	v_sub_u32_e32 v49, v197, v148
	v_cndmask_b32_e64 v75, v75, v246, s[24:25]
	v_max3_f32 v50, v50, v74, v75
	v_add_u32_e32 v51, 16, v48
	v_add_u32_e32 v52, 17, v48
	v_cmp_gt_u32_e64 s[26:27], v51, v146
	v_cmp_gt_u32_e64 s[28:29], v52, v146
	v_cmp_gt_u32_e64 s[38:39], v49, v145
	v_cndmask_b32_e64 v80, v80, v246, s[26:27]
	v_cndmask_b32_e64 v81, v81, v246, s[28:29]
	v_max3_f32 v50, v50, v80, v81
	v_add_u32_e32 v51, 18, v48
	v_add_u32_e32 v48, 19, v48
	v_cmp_gt_u32_e64 s[30:31], v51, v146
	v_cmp_gt_u32_e64 s[34:35], v48, v146
	v_add_u32_e32 v52, 3, v49
	v_cndmask_b32_e64 v82, v82, v246, s[30:31]
	v_cndmask_b32_e64 v83, v83, v246, s[34:35]
	v_max3_f32 v48, v50, v82, v83
	v_add_u32_e32 v51, 1, v49
	v_cmp_gt_u32_e64 s[40:41], v51, v145
	v_cndmask_b32_e64 v32, v32, v246, s[38:39]
	s_nop 0
	v_cndmask_b32_e64 v33, v33, v246, s[40:41]
	v_max_f32_e32 v50, v32, v33
	v_add_u32_e32 v51, 2, v49
	v_cmp_gt_u32_e64 s[42:43], v51, v145
	v_cmp_gt_u32_e64 s[44:45], v52, v145
	s_nop 0
	v_cndmask_b32_e64 v34, v34, v246, s[42:43]
	v_cndmask_b32_e64 v35, v35, v246, s[44:45]
	v_max3_f32 v50, v50, v34, v35
	v_add_u32_e32 v51, 16, v49
	v_add_u32_e32 v52, 17, v49
	v_cmp_gt_u32_e64 s[46:47], v51, v145
	v_cmp_gt_u32_e64 s[48:49], v52, v145
	s_nop 0
	v_cndmask_b32_e64 v36, v36, v246, s[46:47]
	v_cndmask_b32_e64 v37, v37, v246, s[48:49]
	v_max3_f32 v50, v50, v36, v37
	v_add_u32_e32 v51, 18, v49
	v_add_u32_e32 v49, 19, v49
	v_cmp_gt_u32_e64 s[50:51], v51, v145
	v_cmp_gt_u32_e64 s[52:53], v49, v145
	s_nop 0
	v_cndmask_b32_e64 v38, v38, v246, s[50:51]
	v_cndmask_b32_e64 v39, v39, v246, s[52:53]
	v_max3_f32 v49, v50, v38, v39
	v_mov_b32_e32 v50, v48
	s_nop 1
	v_permlane32_swap_b32_e32 v50, v48
	v_max_f32_e32 v48, v48, v50
	v_mov_b32_e32 v50, v49
	s_nop 1
	v_permlane32_swap_b32_e32 v50, v49
	v_max_f32_e32 v49, v49, v50
	v_mov_b32_e32 v50, v48
	s_nop 1
	v_permlane16_swap_b32_e32 v50, v48
	v_max_f32_e32 v48, v48, v50
	v_mov_b32_e32 v50, v49
	v_mov_b32_e32 v53, v49
	v_max_f32_e32 v131, v132, v48
	s_nop 0
	v_permlane16_swap_b32_e32 v50, v53
	v_sub_f32_e32 v48, v132, v131
	v_exp_f32_e32 v52, v48
	v_sub_f32_e32 v48, v72, v131
	v_max_f32_e32 v54, v49, v50
	v_exp_f32_e32 v48, v48
	v_sub_f32_e32 v50, v73, v131
	v_exp_f32_e32 v50, v50
	v_sub_f32_e32 v51, v74, v131
	v_exp_f32_e32 v51, v51
	v_sub_f32_e32 v55, v75, v131
	v_exp_f32_e32 v55, v55
	v_sub_f32_e32 v72, v80, v131
	v_exp_f32_e32 v72, v72
	v_sub_f32_e32 v73, v81, v131
	v_exp_f32_e32 v73, v73
	v_sub_f32_e32 v74, v82, v131
	v_add_f32_e32 v49, v50, v48
	v_exp_f32_e32 v74, v74
	v_sub_f32_e32 v75, v83, v131
	v_add_f32_e32 v49, v51, v49
	v_exp_f32_e32 v75, v75
	v_add_f32_e32 v49, v55, v49
	v_add_f32_e32 v49, v72, v49
	v_add_f32_e32 v49, v73, v49
	v_add_f32_e32 v49, v74, v49
	v_add_f32_e32 v132, v75, v49
	v_fmac_f32_e32 v132, v128, v52
	v_max3_f32 v128, v129, v54, v53
	v_sub_f32_e32 v32, v32, v128
	v_exp_f32_e32 v32, v32
	v_sub_f32_e32 v33, v33, v128
	v_exp_f32_e32 v33, v33
	v_sub_f32_e32 v34, v34, v128
	v_exp_f32_e32 v34, v34
	v_sub_f32_e32 v35, v35, v128
	v_exp_f32_e32 v35, v35
	v_sub_f32_e32 v36, v36, v128
	v_sub_f32_e32 v53, v129, v128
	v_exp_f32_e32 v36, v36
	v_sub_f32_e32 v37, v37, v128
	v_exp_f32_e32 v54, v53
	v_exp_f32_e32 v37, v37
	v_add_f32_e32 v53, v33, v32
	v_add_f32_e32 v53, v34, v53
	v_cvt_pk_bf16_f32 v49, v51, v55
	v_add_f32_e32 v53, v35, v53
	v_cndmask_b32_e64 v55, v36, 0, s[46:47]
	v_add_f32_e32 v36, v55, v53
	v_cndmask_b32_e64 v53, v37, 0, s[48:49]
	v_sub_f32_e32 v37, v38, v128
	v_exp_f32_e32 v37, v37
	v_cvt_pk_bf16_f32 v48, v48, v50
	v_cvt_pk_bf16_f32 v50, v72, v73
	v_add_f32_e32 v36, v53, v36
	v_cndmask_b32_e64 v72, v37, 0, s[50:51]
	v_sub_f32_e32 v37, v39, v128
	v_exp_f32_e32 v37, v37
	v_cvt_pk_bf16_f32 v51, v74, v75
	v_add_f32_e32 v36, v72, v36
	v_pk_mul_f32 v[18:19], v[18:19], v[52:53] op_sel_hi:[1,0]
	v_cndmask_b32_e64 v39, v37, 0, s[52:53]
	v_pk_mul_f32 v[16:17], v[16:17], v[52:53] op_sel_hi:[1,0]
	v_add_f32_e32 v129, v39, v36
	v_cvt_pk_bf16_f32 v36, v32, v33
	v_cvt_pk_bf16_f32 v37, v34, v35
	v_cvt_pk_bf16_f32 v38, v55, v53
	v_cvt_pk_bf16_f32 v39, v72, v39
	s_waitcnt lgkmcnt(10)
	v_mfma_f32_16x16x32_bf16 v[32:35], v[134:137], v[48:51], v[16:19]
	v_fmac_f32_e32 v129, v130, v54
	s_nop 1
	v_pk_mul_f32 v[18:19], v[22:23], v[54:55] op_sel_hi:[1,0]
	v_pk_mul_f32 v[16:17], v[20:21], v[54:55] op_sel_hi:[1,0]
	s_nop 1
	v_mfma_f32_16x16x32_bf16 v[96:99], v[134:137], v[36:39], v[16:19]
	s_nop 2
	v_mul_f32_e64 v18, v106, v52
	v_mul_f32_e64 v19, v107, v52
	v_pk_mul_f32 v[16:17], v[104:105], v[52:53] op_sel_hi:[1,0]
	s_waitcnt lgkmcnt(8)
	s_nop 0
	v_mfma_f32_16x16x32_bf16 v[104:107], v[138:141], v[48:51], v[16:19]
	s_nop 2
	v_mul_f32_e64 v18, v110, v54
	v_mul_f32_e64 v19, v111, v54
	v_pk_mul_f32 v[16:17], v[108:109], v[54:55] op_sel_hi:[1,0]
	s_nop 1
	v_mfma_f32_16x16x32_bf16 v[108:111], v[138:141], v[36:39], v[16:19]
	s_nop 2
	v_mul_f32_e64 v18, v114, v52
	v_mul_f32_e64 v19, v115, v52
	v_pk_mul_f32 v[16:17], v[112:113], v[52:53] op_sel_hi:[1,0]
	s_waitcnt lgkmcnt(6)
	s_nop 0
	v_mfma_f32_16x16x32_bf16 v[112:115], v[176:179], v[48:51], v[16:19]
	s_nop 2
	v_mul_f32_e64 v18, v118, v54
	v_mul_f32_e64 v19, v119, v54
	v_pk_mul_f32 v[16:17], v[116:117], v[54:55] op_sel_hi:[1,0]
	s_nop 1
	v_mfma_f32_16x16x32_bf16 v[116:119], v[176:179], v[36:39], v[16:19]
	s_nop 2
	v_mul_f32_e64 v18, v122, v52
	v_mul_f32_e64 v19, v123, v52
	v_pk_mul_f32 v[16:17], v[120:121], v[52:53] op_sel_hi:[1,0]
	s_waitcnt lgkmcnt(4)
	s_nop 0
	v_mfma_f32_16x16x32_bf16 v[120:123], v[188:191], v[48:51], v[16:19]
	v_or_b32_e32 v48, 0x90, v166
	v_add_u32_e32 v48, s76, v48
	s_nop 0
	v_pk_mul_f32 v[18:19], v[126:127], v[54:55] op_sel_hi:[1,0]
	v_pk_mul_f32 v[16:17], v[124:125], v[54:55] op_sel_hi:[1,0]
	s_nop 1
	v_mfma_f32_16x16x32_bf16 v[124:127], v[188:191], v[36:39], v[16:19]
	s_nop 2
	v_add_u32_e32 v16, 0x80, v149
	v_med3_i32 v16, v16, 0, s75
	v_lshl_add_u32 v16, v16, 9, v152
	global_load_dwordx4 v[36:39], v16, s[98:99]
	v_add_u32_e32 v16, 0x80, v150
	v_med3_i32 v16, v16, 0, s75
	v_lshl_add_u32 v16, v16, 9, v152
	global_load_dwordx4 v[72:75], v16, s[98:99]
	v_add_u32_e32 v16, 0x80, v151
	v_med3_i32 v16, v16, 0, s75
	v_lshl_add_u32 v16, v16, 9, v152
	global_load_dwordx4 v[80:83], v16, s[98:99]
	v_add_u32_e32 v16, 0x80, v252
	v_med3_i32 v16, v16, 0, s75
	v_lshl_add_u32 v16, v16, 9, v152
	global_load_dwordx4 v[88:91], v16, s[98:99]
	v_or_b32_e32 v16, 0x80, v166
	v_add_u32_e32 v16, s76, v16
	v_med3_i32 v16, v16, 0, s75
	v_med3_i32 v48, v48, 0, s75
	v_lshl_add_u32 v20, v16, 9, v158
	v_lshl_add_u32 v52, v48, 9, v158
	global_load_dwordx4 v[16:19], v20, s[100:101]
	s_nop 0
	global_load_dwordx4 v[20:23], v20, s[100:101] offset:64
	s_nop 0
	global_load_dwordx4 v[48:51], v52, s[100:101]
	s_nop 0
	global_load_dwordx4 v[52:55], v52, s[100:101] offset:64
	ds_read_b64_tr_b16 v[136:137], v169 offset:2304
	ds_read_b64_tr_b16 v[134:135], v169
	ds_read_b64_tr_b16 v[138:139], v169 offset:32
	ds_read_b64_tr_b16 v[140:141], v169 offset:2336
	ds_read_b64_tr_b16 v[188:189], v169 offset:64
	ds_read_b64_tr_b16 v[190:191], v169 offset:2368
	ds_read_b64_tr_b16 v[200:201], v169 offset:96
	ds_read_b64_tr_b16 v[202:203], v169 offset:2400
	s_waitcnt vmcnt(15)
	ds_write_b128 v241, v[76:79] offset:4608
	s_waitcnt vmcnt(14)
	ds_write_b128 v242, v[84:87] offset:4608
	s_waitcnt vmcnt(13)
	ds_write_b128 v243, v[92:95] offset:4608
	s_waitcnt vmcnt(12)
	ds_write_b128 v244, v[100:103] offset:4608
	v_mfma_f32_16x16x32_bf16 v[76:79], v[40:43], v[4:7], 0
	v_mfma_f32_16x16x32_bf16 v[40:43], v[40:43], v[12:15], 0
	v_mfma_f32_16x16x32_bf16 v[76:79], v[44:47], v[8:11], v[76:79]
	v_mfma_f32_16x16x32_bf16 v[84:87], v[56:59], v[4:7], 0
	v_mfma_f32_16x16x32_bf16 v[40:43], v[44:47], v[0:3], v[40:43]
	v_mfma_f32_16x16x32_bf16 v[44:47], v[56:59], v[12:15], 0
	v_sub_u32_e32 v56, v198, v147
	v_add_u32_e32 v59, 1, v56
	s_nop 2
	v_cmp_gt_u32_e64 s[0:1], v59, v146
	v_cmp_gt_u32_e32 vcc, v56, v146
	s_nop 0
	v_cndmask_b32_e64 v77, v77, v246, s[0:1]
	s_nop 0
	v_cndmask_b32_e32 v76, v76, v246, vcc
	v_mfma_f32_16x16x32_bf16 v[84:87], v[60:63], v[8:11], v[84:87]
	v_max_f32_e32 v58, v76, v77
	v_add_u32_e32 v59, 2, v56
	v_cmp_gt_u32_e64 s[22:23], v59, v146
	v_mfma_f32_16x16x32_bf16 v[44:47], v[60:63], v[0:3], v[44:47]
	v_add_u32_e32 v60, 3, v56
	v_cmp_gt_u32_e64 s[24:25], v60, v146
	v_cndmask_b32_e64 v78, v78, v246, s[22:23]
	v_sub_u32_e32 v57, v198, v148
	v_cndmask_b32_e64 v79, v79, v246, s[24:25]
	v_max3_f32 v58, v58, v78, v79
	v_add_u32_e32 v59, 16, v56
	v_add_u32_e32 v60, 17, v56
	v_cmp_gt_u32_e64 s[26:27], v59, v146
	v_cmp_gt_u32_e64 s[28:29], v60, v146
	v_cmp_gt_u32_e64 s[38:39], v57, v145
	v_cndmask_b32_e64 v84, v84, v246, s[26:27]
	v_cndmask_b32_e64 v85, v85, v246, s[28:29]
	v_max3_f32 v58, v58, v84, v85
	v_add_u32_e32 v59, 18, v56
	v_add_u32_e32 v56, 19, v56
	v_cmp_gt_u32_e64 s[30:31], v59, v146
	v_cmp_gt_u32_e64 s[34:35], v56, v146
	v_add_u32_e32 v60, 3, v57
	v_cndmask_b32_e64 v86, v86, v246, s[30:31]
	v_cndmask_b32_e64 v87, v87, v246, s[34:35]
	v_max3_f32 v56, v58, v86, v87
	v_add_u32_e32 v59, 1, v57
	v_cmp_gt_u32_e64 s[40:41], v59, v145
	v_cndmask_b32_e64 v40, v40, v246, s[38:39]
	s_nop 0
	v_cndmask_b32_e64 v41, v41, v246, s[40:41]
	v_max_f32_e32 v58, v40, v41
	v_add_u32_e32 v59, 2, v57
	v_cmp_gt_u32_e64 s[42:43], v59, v145
	v_cmp_gt_u32_e64 s[44:45], v60, v145
	s_nop 0
	v_cndmask_b32_e64 v42, v42, v246, s[42:43]
	v_cndmask_b32_e64 v43, v43, v246, s[44:45]
	v_max3_f32 v58, v58, v42, v43
	v_add_u32_e32 v59, 16, v57
	v_add_u32_e32 v60, 17, v57
	v_cmp_gt_u32_e64 s[46:47], v59, v145
	v_cmp_gt_u32_e64 s[48:49], v60, v145
	s_nop 0
	v_cndmask_b32_e64 v44, v44, v246, s[46:47]
	v_cndmask_b32_e64 v45, v45, v246, s[48:49]
	v_max3_f32 v58, v58, v44, v45
	v_add_u32_e32 v59, 18, v57
	v_add_u32_e32 v57, 19, v57
	v_cmp_gt_u32_e64 s[50:51], v59, v145
	v_cmp_gt_u32_e64 s[52:53], v57, v145
	s_nop 0
	v_cndmask_b32_e64 v46, v46, v246, s[50:51]
	v_cndmask_b32_e64 v47, v47, v246, s[52:53]
	v_max3_f32 v57, v58, v46, v47
	v_mov_b32_e32 v58, v56
	s_nop 1
	v_permlane32_swap_b32_e32 v58, v56
	v_max_f32_e32 v56, v56, v58
	v_mov_b32_e32 v58, v57
	s_nop 1
	v_permlane32_swap_b32_e32 v58, v57
	v_max_f32_e32 v57, v57, v58
	v_mov_b32_e32 v58, v56
	s_nop 1
	v_permlane16_swap_b32_e32 v58, v56
	v_max_f32_e32 v56, v56, v58
	v_mov_b32_e32 v58, v57
	s_nop 1
	v_permlane16_swap_b32_e32 v58, v57
	v_max_f32_e32 v175, v131, v56
	v_sub_f32_e32 v56, v131, v175
	v_max3_f32 v177, v128, v57, v58
	v_exp_f32_e32 v60, v56
	v_sub_f32_e32 v56, v76, v175
	v_sub_f32_e32 v40, v40, v177
	v_exp_f32_e32 v56, v56
	v_sub_f32_e32 v58, v77, v175
	v_exp_f32_e32 v40, v40
	v_sub_f32_e32 v41, v41, v177
	v_exp_f32_e32 v58, v58
	v_sub_f32_e32 v59, v78, v175
	v_exp_f32_e32 v41, v41
	v_sub_f32_e32 v42, v42, v177
	v_exp_f32_e32 v59, v59
	v_sub_f32_e32 v63, v79, v175
	v_exp_f32_e32 v42, v42
	v_sub_f32_e32 v43, v43, v177
	v_exp_f32_e32 v63, v63
	v_sub_f32_e32 v76, v84, v175
	v_exp_f32_e32 v43, v43
	v_sub_f32_e32 v44, v44, v177
	v_exp_f32_e32 v76, v76
	v_sub_f32_e32 v77, v85, v175
	v_sub_f32_e32 v61, v128, v177
	v_exp_f32_e32 v44, v44
	v_sub_f32_e32 v45, v45, v177
	v_exp_f32_e32 v77, v77
	v_sub_f32_e32 v78, v86, v175
	v_exp_f32_e32 v62, v61
	v_exp_f32_e32 v45, v45
	v_sub_f32_e32 v46, v46, v177
	v_add_f32_e32 v57, v58, v56
	v_exp_f32_e32 v78, v78
	v_sub_f32_e32 v79, v87, v175
	v_add_f32_e32 v61, v41, v40
	v_exp_f32_e32 v46, v46
	v_add_f32_e32 v57, v59, v57
	v_exp_f32_e32 v79, v79
	v_add_f32_e32 v61, v42, v61
	v_sub_f32_e32 v47, v47, v177
	v_add_f32_e32 v57, v63, v57
	v_add_f32_e32 v61, v43, v61
	v_exp_f32_e32 v47, v47
	v_add_f32_e32 v57, v76, v57
	v_add_f32_e32 v61, v44, v61
	v_add_f32_e32 v57, v77, v57
	v_add_f32_e32 v61, v45, v61
	v_add_f32_e32 v57, v78, v57
	v_add_f32_e32 v61, v46, v61
	v_add_f32_e32 v176, v79, v57
	v_cvt_pk_bf16_f32 v56, v56, v58
	v_cvt_pk_bf16_f32 v57, v59, v63
	v_cvt_pk_bf16_f32 v58, v76, v77
	v_cvt_pk_bf16_f32 v59, v78, v79
	v_pk_mul_f32 v[34:35], v[34:35], v[60:61] op_sel_hi:[1,0]
	v_pk_mul_f32 v[32:33], v[32:33], v[60:61] op_sel_hi:[1,0]
	v_add_f32_e32 v178, v47, v61
	v_cvt_pk_bf16_f32 v40, v40, v41
	v_cvt_pk_bf16_f32 v41, v42, v43
	v_cvt_pk_bf16_f32 v42, v44, v45
	v_cvt_pk_bf16_f32 v43, v46, v47
	s_waitcnt lgkmcnt(10)
	v_mfma_f32_16x16x32_bf16 v[44:47], v[134:137], v[56:59], v[32:35]
	v_fmac_f32_e32 v176, v132, v60
	v_fmac_f32_e32 v178, v129, v62
	s_nop 0
	v_pk_mul_f32 v[34:35], v[98:99], v[62:63] op_sel_hi:[1,0]
	v_pk_mul_f32 v[32:33], v[96:97], v[62:63] op_sel_hi:[1,0]
	s_nop 1
	v_mfma_f32_16x16x32_bf16 v[100:103], v[134:137], v[40:43], v[32:35]
	s_nop 2
	v_mul_f32_e64 v34, v106, v60
	v_mul_f32_e64 v35, v107, v60
	v_pk_mul_f32 v[32:33], v[104:105], v[60:61] op_sel_hi:[1,0]
	s_waitcnt lgkmcnt(8)
	s_nop 0
	v_mfma_f32_16x16x32_bf16 v[104:107], v[138:141], v[56:59], v[32:35]
	s_nop 2
	v_mul_f32_e64 v34, v110, v62
	v_mul_f32_e64 v35, v111, v62
	v_pk_mul_f32 v[32:33], v[108:109], v[62:63] op_sel_hi:[1,0]
	s_nop 1
	v_mfma_f32_16x16x32_bf16 v[108:111], v[138:141], v[40:43], v[32:35]
	s_nop 2
	v_mul_f32_e64 v34, v114, v60
	v_mul_f32_e64 v35, v115, v60
	v_pk_mul_f32 v[32:33], v[112:113], v[60:61] op_sel_hi:[1,0]
	s_waitcnt lgkmcnt(6)
	s_nop 0
	v_mfma_f32_16x16x32_bf16 v[112:115], v[188:191], v[56:59], v[32:35]
	s_nop 2
	v_mul_f32_e64 v34, v118, v62
	v_mul_f32_e64 v35, v119, v62
	v_pk_mul_f32 v[32:33], v[116:117], v[62:63] op_sel_hi:[1,0]
	s_nop 1
	v_mfma_f32_16x16x32_bf16 v[116:119], v[188:191], v[40:43], v[32:35]
	v_add_u32_e32 v188, s76, v207
	s_nop 1
	v_pk_mul_f32 v[34:35], v[122:123], v[60:61] op_sel_hi:[1,0]
	v_pk_mul_f32 v[32:33], v[120:121], v[60:61] op_sel_hi:[1,0]
	s_waitcnt lgkmcnt(4)
	s_nop 0
	v_mfma_f32_16x16x32_bf16 v[120:123], v[200:203], v[56:59], v[32:35]
	v_or_b32_e32 v56, 0xb0, v166
	v_add_u32_e32 v56, s76, v56
	s_nop 0
	v_pk_mul_f32 v[34:35], v[126:127], v[62:63] op_sel_hi:[1,0]
	v_pk_mul_f32 v[32:33], v[124:125], v[62:63] op_sel_hi:[1,0]
	s_nop 1
	v_mfma_f32_16x16x32_bf16 v[124:127], v[200:203], v[40:43], v[32:35]
	s_nop 2
	v_add_u32_e32 v32, 0xa0, v149
	v_med3_i32 v32, v32, 0, s75
	v_lshl_add_u32 v32, v32, 9, v152
	global_load_dwordx4 v[76:79], v32, s[98:99]
	v_add_u32_e32 v32, 0xa0, v150
	v_med3_i32 v32, v32, 0, s75
	v_lshl_add_u32 v32, v32, 9, v152
	global_load_dwordx4 v[84:87], v32, s[98:99]
	v_add_u32_e32 v32, 0xa0, v151
	v_med3_i32 v32, v32, 0, s75
	v_lshl_add_u32 v32, v32, 9, v152
	global_load_dwordx4 v[92:95], v32, s[98:99]
	v_add_u32_e32 v32, 0xa0, v252
	v_med3_i32 v32, v32, 0, s75
	v_lshl_add_u32 v32, v32, 9, v152
	global_load_dwordx4 v[96:99], v32, s[98:99]
	v_or_b32_e32 v32, 0xa0, v166
	v_add_u32_e32 v32, s76, v32
	v_med3_i32 v32, v32, 0, s75
	v_med3_i32 v56, v56, 0, s75
	v_lshl_add_u32 v40, v32, 9, v158
	v_lshl_add_u32 v60, v56, 9, v158
	global_load_dwordx4 v[32:35], v40, s[100:101]
	s_nop 0
	global_load_dwordx4 v[40:43], v40, s[100:101] offset:64
	s_nop 0
	global_load_dwordx4 v[56:59], v60, s[100:101]
	s_nop 0
	global_load_dwordx4 v[60:63], v60, s[100:101] offset:64
	ds_read_b64_tr_b16 v[142:143], v169 offset:6912
	ds_read_b64_tr_b16 v[140:141], v169 offset:4608
	ds_read_b64_tr_b16 v[136:137], v169 offset:4640
	ds_read_b64_tr_b16 v[138:139], v169 offset:6944
	ds_read_b64_tr_b16 v[132:133], v169 offset:4672
	ds_read_b64_tr_b16 v[134:135], v169 offset:6976
	ds_read_b64_tr_b16 v[128:129], v169 offset:4704
	ds_read_b64_tr_b16 v[130:131], v169 offset:7008
	s_waitcnt vmcnt(15)
	ds_write_b128 v241, v[36:39]
	s_waitcnt vmcnt(14)
	ds_write_b128 v242, v[72:75]
	s_waitcnt vmcnt(13)
	ds_write_b128 v243, v[80:83]
	s_waitcnt vmcnt(12)
	ds_write_b128 v244, v[88:91]
	v_mfma_f32_16x16x32_bf16 v[36:39], v[24:27], v[4:7], 0
	v_mfma_f32_16x16x32_bf16 v[24:27], v[24:27], v[12:15], 0
	v_mfma_f32_16x16x32_bf16 v[36:39], v[28:31], v[8:11], v[36:39]
	v_mfma_f32_16x16x32_bf16 v[72:75], v[64:67], v[4:7], 0
	v_mfma_f32_16x16x32_bf16 v[24:27], v[28:31], v[0:3], v[24:27]
	v_mfma_f32_16x16x32_bf16 v[28:31], v[64:67], v[12:15], 0
	v_sub_u32_e32 v64, v199, v147
	v_add_u32_e32 v67, 1, v64
	s_nop 2
	v_cmp_gt_u32_e64 s[0:1], v67, v146
	v_cmp_gt_u32_e32 vcc, v64, v146
	s_nop 0
	v_cndmask_b32_e64 v37, v37, v246, s[0:1]
	s_nop 0
	v_cndmask_b32_e32 v36, v36, v246, vcc
	v_mfma_f32_16x16x32_bf16 v[72:75], v[68:71], v[8:11], v[72:75]
	v_max_f32_e32 v66, v36, v37
	v_add_u32_e32 v67, 2, v64
	v_cmp_gt_u32_e64 s[22:23], v67, v146
	v_mfma_f32_16x16x32_bf16 v[28:31], v[68:71], v[0:3], v[28:31]
	v_add_u32_e32 v68, 3, v64
	v_cmp_gt_u32_e64 s[24:25], v68, v146
	v_cndmask_b32_e64 v38, v38, v246, s[22:23]
	v_sub_u32_e32 v65, v199, v148
	v_cndmask_b32_e64 v39, v39, v246, s[24:25]
	v_max3_f32 v66, v66, v38, v39
	v_add_u32_e32 v67, 16, v64
	v_add_u32_e32 v68, 17, v64
	v_cmp_gt_u32_e64 s[26:27], v67, v146
	v_cmp_gt_u32_e64 s[28:29], v68, v146
	v_cmp_gt_u32_e64 s[38:39], v65, v145
	v_cndmask_b32_e64 v72, v72, v246, s[26:27]
	v_cndmask_b32_e64 v73, v73, v246, s[28:29]
	v_max3_f32 v66, v66, v72, v73
	v_add_u32_e32 v67, 18, v64
	v_add_u32_e32 v64, 19, v64
	v_cmp_gt_u32_e64 s[30:31], v67, v146
	v_cmp_gt_u32_e64 s[34:35], v64, v146
	v_add_u32_e32 v68, 3, v65
	v_cndmask_b32_e64 v74, v74, v246, s[30:31]
	v_cndmask_b32_e64 v75, v75, v246, s[34:35]
	v_max3_f32 v64, v66, v74, v75
	v_add_u32_e32 v67, 1, v65
	v_cmp_gt_u32_e64 s[40:41], v67, v145
	v_cndmask_b32_e64 v24, v24, v246, s[38:39]
	s_nop 0
	v_cndmask_b32_e64 v25, v25, v246, s[40:41]
	v_max_f32_e32 v66, v24, v25
	v_add_u32_e32 v67, 2, v65
	v_cmp_gt_u32_e64 s[42:43], v67, v145
	v_cmp_gt_u32_e64 s[44:45], v68, v145
	s_nop 0
	v_cndmask_b32_e64 v26, v26, v246, s[42:43]
	v_cndmask_b32_e64 v27, v27, v246, s[44:45]
	v_max3_f32 v66, v66, v26, v27
	v_add_u32_e32 v67, 16, v65
	v_add_u32_e32 v68, 17, v65
	v_cmp_gt_u32_e64 s[46:47], v67, v145
	v_cmp_gt_u32_e64 s[48:49], v68, v145
	s_nop 0
	v_cndmask_b32_e64 v28, v28, v246, s[46:47]
	v_cndmask_b32_e64 v29, v29, v246, s[48:49]
	v_max3_f32 v66, v66, v28, v29
	v_add_u32_e32 v67, 18, v65
	v_add_u32_e32 v65, 19, v65
	v_cmp_gt_u32_e64 s[50:51], v67, v145
	v_cmp_gt_u32_e64 s[52:53], v65, v145
	s_nop 0
	v_cndmask_b32_e64 v30, v30, v246, s[50:51]
	v_cndmask_b32_e64 v31, v31, v246, s[52:53]
	v_max3_f32 v65, v66, v30, v31
	v_mov_b32_e32 v66, v64
	s_nop 1
	v_permlane32_swap_b32_e32 v66, v64
	v_max_f32_e32 v64, v64, v66
	v_mov_b32_e32 v66, v65
	s_nop 1
	v_permlane32_swap_b32_e32 v66, v65
	v_max_f32_e32 v65, v65, v66
	v_mov_b32_e32 v66, v64
	s_nop 1
	v_permlane16_swap_b32_e32 v66, v64
	v_max3_f32 v179, v175, v64, v66
	v_sub_f32_e32 v36, v36, v179
	v_exp_f32_e32 v36, v36
	v_sub_f32_e32 v37, v37, v179
	v_mov_b32_e32 v66, v65
	v_exp_f32_e32 v37, v37
	v_sub_f32_e32 v38, v38, v179
	v_permlane16_swap_b32_e32 v66, v65
	v_exp_f32_e32 v38, v38
	v_sub_f32_e32 v39, v39, v179
	v_exp_f32_e32 v39, v39
	v_sub_f32_e32 v67, v72, v179
	v_max_f32_e32 v65, v65, v66
	v_exp_f32_e32 v67, v67
	v_sub_f32_e32 v69, v73, v179
	v_exp_f32_e32 v69, v69
	v_sub_f32_e32 v70, v74, v179
	v_max_f32_e32 v181, v177, v65
	v_add_f32_e32 v66, v37, v36
	v_exp_f32_e32 v70, v70
	v_sub_f32_e32 v71, v75, v179
	v_sub_f32_e32 v24, v24, v181
	v_add_f32_e32 v66, v38, v66
	v_exp_f32_e32 v71, v71
	v_exp_f32_e32 v24, v24
	v_sub_f32_e32 v25, v25, v181
	v_add_f32_e32 v66, v39, v66
	v_exp_f32_e32 v25, v25
	v_sub_f32_e32 v26, v26, v181
	v_add_f32_e32 v66, v67, v66
	v_exp_f32_e32 v26, v26
	v_sub_f32_e32 v27, v27, v181
	v_add_f32_e32 v66, v69, v66
	v_exp_f32_e32 v27, v27
	v_sub_f32_e32 v28, v28, v181
	v_add_f32_e32 v66, v70, v66
	v_sub_f32_e32 v65, v177, v181
	v_exp_f32_e32 v28, v28
	v_sub_f32_e32 v29, v29, v181
	v_add_f32_e32 v180, v71, v66
	v_exp_f32_e32 v66, v65
	v_exp_f32_e32 v29, v29
	v_sub_f32_e32 v30, v30, v181
	v_add_f32_e32 v65, v25, v24
	v_exp_f32_e32 v30, v30
	v_sub_f32_e32 v31, v31, v181
	v_sub_f32_e32 v64, v175, v179
	v_add_f32_e32 v65, v26, v65
	v_exp_f32_e32 v31, v31
	v_exp_f32_e32 v64, v64
	v_add_f32_e32 v65, v27, v65
	v_add_f32_e32 v65, v28, v65
	v_add_f32_e32 v65, v29, v65
	v_add_f32_e32 v65, v30, v65
	v_cvt_pk_bf16_f32 v36, v36, v37
	v_cvt_pk_bf16_f32 v37, v38, v39
	v_cvt_pk_bf16_f32 v38, v67, v69
	v_cvt_pk_bf16_f32 v39, v70, v71
	v_add_f32_e32 v183, v31, v65
	v_cvt_pk_bf16_f32 v24, v24, v25
	v_cvt_pk_bf16_f32 v25, v26, v27
	v_cvt_pk_bf16_f32 v26, v28, v29
	v_cvt_pk_bf16_f32 v27, v30, v31
	v_pk_mul_f32 v[30:31], v[46:47], v[64:65] op_sel_hi:[1,0]
	v_pk_mul_f32 v[28:29], v[44:45], v[64:65] op_sel_hi:[1,0]
	v_fmac_f32_e32 v180, v176, v64
	v_fmac_f32_e32 v183, v178, v66
	s_waitcnt lgkmcnt(10)
	v_mfma_f32_16x16x32_bf16 v[68:71], v[140:143], v[36:39], v[28:31]
	s_nop 2
	v_mul_f32_e64 v30, v102, v66
	v_mul_f32_e64 v31, v103, v66
	v_pk_mul_f32 v[28:29], v[100:101], v[66:67] op_sel_hi:[1,0]
	s_nop 1
	v_mfma_f32_16x16x32_bf16 v[72:75], v[140:143], v[24:27], v[28:31]
	s_nop 2
	v_mul_f32_e64 v30, v106, v64
	v_mul_f32_e64 v31, v107, v64
	v_pk_mul_f32 v[28:29], v[104:105], v[64:65] op_sel_hi:[1,0]
	s_waitcnt lgkmcnt(8)
	s_nop 0
	v_mfma_f32_16x16x32_bf16 v[80:83], v[136:139], v[36:39], v[28:31]
	s_nop 2
	v_mul_f32_e64 v30, v110, v66
	v_mul_f32_e64 v31, v111, v66
	v_pk_mul_f32 v[28:29], v[108:109], v[66:67] op_sel_hi:[1,0]
	s_nop 1
	v_mfma_f32_16x16x32_bf16 v[108:111], v[136:139], v[24:27], v[28:31]
	s_nop 2
	v_mul_f32_e64 v30, v114, v64
	v_mul_f32_e64 v31, v115, v64
	v_pk_mul_f32 v[28:29], v[112:113], v[64:65] op_sel_hi:[1,0]
	s_waitcnt lgkmcnt(6)
	s_nop 0
	v_mfma_f32_16x16x32_bf16 v[112:115], v[132:135], v[36:39], v[28:31]
	s_nop 2
	v_mul_f32_e64 v30, v118, v66
	v_mul_f32_e64 v31, v119, v66
	v_pk_mul_f32 v[28:29], v[116:117], v[66:67] op_sel_hi:[1,0]
	s_nop 1
	v_mfma_f32_16x16x32_bf16 v[116:119], v[132:135], v[24:27], v[28:31]
	s_nop 2
	v_mul_f32_e64 v30, v122, v64
	v_mul_f32_e64 v31, v123, v64
	v_pk_mul_f32 v[28:29], v[120:121], v[64:65] op_sel_hi:[1,0]
	s_waitcnt lgkmcnt(4)
	s_nop 0
	v_mfma_f32_16x16x32_bf16 v[120:123], v[128:131], v[36:39], v[28:31]
	s_nop 2
	v_mul_f32_e64 v30, v126, v66
	v_mul_f32_e64 v31, v127, v66
	v_pk_mul_f32 v[28:29], v[124:125], v[66:67] op_sel_hi:[1,0]
	s_nop 1
	v_mfma_f32_16x16x32_bf16 v[124:127], v[128:131], v[24:27], v[28:31]
	v_add_u32_e32 v24, 0xc0, v149
	v_med3_i32 v24, v24, 0, s75
	v_lshl_add_u32 v24, v24, 9, v152
	global_load_dwordx4 v[64:67], v24, s[98:99]
	v_add_u32_e32 v24, 0xc0, v150
	v_med3_i32 v24, v24, 0, s75
	v_lshl_add_u32 v24, v24, 9, v152
	global_load_dwordx4 v[88:91], v24, s[98:99]
	v_add_u32_e32 v24, 0xc0, v151
	v_med3_i32 v24, v24, 0, s75
	v_lshl_add_u32 v24, v24, 9, v152
	global_load_dwordx4 v[100:103], v24, s[98:99]
	v_add_u32_e32 v24, 0xc0, v252
	v_med3_i32 v24, v24, 0, s75
	v_lshl_add_u32 v24, v24, 9, v152
	global_load_dwordx4 v[104:107], v24, s[98:99]
	v_or_b32_e32 v24, 0xc0, v166
	v_add_u32_e32 v24, s76, v24
	v_med3_i32 v24, v24, 0, s75
	v_lshl_add_u32 v24, v24, 9, v158
	global_load_dwordx4 v[36:39], v24, s[100:101]
	global_load_dwordx4 v[44:47], v24, s[100:101] offset:64
	v_or_b32_e32 v24, 0xd0, v166
	v_add_u32_e32 v24, s76, v24
	v_med3_i32 v24, v24, 0, s75
	v_lshl_add_u32 v28, v24, 9, v158
	global_load_dwordx4 v[24:27], v28, s[100:101]
	s_nop 0
	global_load_dwordx4 v[28:31], v28, s[100:101] offset:64
	ds_read_b64_tr_b16 v[142:143], v169 offset:2304
	ds_read_b64_tr_b16 v[140:141], v169
	ds_read_b64_tr_b16 v[136:137], v169 offset:32
	ds_read_b64_tr_b16 v[138:139], v169 offset:2336
	ds_read_b64_tr_b16 v[132:133], v169 offset:64
	ds_read_b64_tr_b16 v[134:135], v169 offset:2368
	ds_read_b64_tr_b16 v[128:129], v169 offset:96
	ds_read_b64_tr_b16 v[130:131], v169 offset:2400
	s_waitcnt vmcnt(15)
	ds_write_b128 v241, v[76:79] offset:4608
	s_waitcnt vmcnt(14)
	ds_write_b128 v242, v[84:87] offset:4608
	s_waitcnt vmcnt(13)
	ds_write_b128 v243, v[92:95] offset:4608
	s_waitcnt vmcnt(12)
	ds_write_b128 v244, v[96:99] offset:4608
	v_mfma_f32_16x16x32_bf16 v[76:79], v[16:19], v[4:7], 0
	v_mfma_f32_16x16x32_bf16 v[16:19], v[16:19], v[12:15], 0
	v_mfma_f32_16x16x32_bf16 v[76:79], v[20:23], v[8:11], v[76:79]
	v_mfma_f32_16x16x32_bf16 v[84:87], v[48:51], v[4:7], 0
	v_mfma_f32_16x16x32_bf16 v[16:19], v[20:23], v[0:3], v[16:19]
	v_mfma_f32_16x16x32_bf16 v[20:23], v[48:51], v[12:15], 0
	v_add_u32_e32 v49, 0xc0, v154
	v_sub_u32_e32 v48, v49, v147
	v_add_u32_e32 v51, 1, v48
	s_nop 1
	v_cmp_gt_u32_e64 s[0:1], v51, v146
	v_cmp_gt_u32_e32 vcc, v48, v146
	s_nop 0
	v_cndmask_b32_e64 v77, v77, v246, s[0:1]
	s_nop 0
	v_cndmask_b32_e32 v76, v76, v246, vcc
	v_mfma_f32_16x16x32_bf16 v[84:87], v[52:55], v[8:11], v[84:87]
	v_max_f32_e32 v50, v76, v77
	v_add_u32_e32 v51, 2, v48
	v_cmp_gt_u32_e64 s[22:23], v51, v146
	v_mfma_f32_16x16x32_bf16 v[20:23], v[52:55], v[0:3], v[20:23]
	v_add_u32_e32 v52, 3, v48
	v_cmp_gt_u32_e64 s[24:25], v52, v146
	v_cndmask_b32_e64 v78, v78, v246, s[22:23]
	v_sub_u32_e32 v49, v49, v148
	v_cndmask_b32_e64 v79, v79, v246, s[24:25]
	v_max3_f32 v50, v50, v78, v79
	v_add_u32_e32 v51, 16, v48
	v_add_u32_e32 v52, 17, v48
	v_cmp_gt_u32_e64 s[26:27], v51, v146
	v_cmp_gt_u32_e64 s[28:29], v52, v146
	v_cmp_gt_u32_e64 s[38:39], v49, v145
	v_cndmask_b32_e64 v84, v84, v246, s[26:27]
	v_cndmask_b32_e64 v85, v85, v246, s[28:29]
	v_max3_f32 v50, v50, v84, v85
	v_add_u32_e32 v51, 18, v48
	v_add_u32_e32 v48, 19, v48
	v_cmp_gt_u32_e64 s[30:31], v51, v146
	v_cmp_gt_u32_e64 s[34:35], v48, v146
	v_add_u32_e32 v52, 3, v49
	v_cndmask_b32_e64 v86, v86, v246, s[30:31]
	v_cndmask_b32_e64 v87, v87, v246, s[34:35]
	v_max3_f32 v48, v50, v86, v87
	v_add_u32_e32 v51, 1, v49
	v_cmp_gt_u32_e64 s[40:41], v51, v145
	v_cndmask_b32_e64 v16, v16, v246, s[38:39]
	s_nop 0
	v_cndmask_b32_e64 v17, v17, v246, s[40:41]
	v_max_f32_e32 v50, v16, v17
	v_add_u32_e32 v51, 2, v49
	v_cmp_gt_u32_e64 s[42:43], v51, v145
	v_cmp_gt_u32_e64 s[44:45], v52, v145
	s_nop 0
	v_cndmask_b32_e64 v18, v18, v246, s[42:43]
	v_cndmask_b32_e64 v19, v19, v246, s[44:45]
	v_max3_f32 v50, v50, v18, v19
	v_add_u32_e32 v51, 16, v49
	v_add_u32_e32 v52, 17, v49
	v_cmp_gt_u32_e64 s[46:47], v51, v145
	v_cmp_gt_u32_e64 s[48:49], v52, v145
	s_nop 0
	v_cndmask_b32_e64 v20, v20, v246, s[46:47]
	v_cndmask_b32_e64 v21, v21, v246, s[48:49]
	v_max3_f32 v50, v50, v20, v21
	v_add_u32_e32 v51, 18, v49
	v_add_u32_e32 v49, 19, v49
	v_cmp_gt_u32_e64 s[50:51], v51, v145
	v_cmp_gt_u32_e64 s[52:53], v49, v145
	s_nop 0
	v_cndmask_b32_e64 v22, v22, v246, s[50:51]
	v_cndmask_b32_e64 v23, v23, v246, s[52:53]
	v_max3_f32 v49, v50, v22, v23
	v_mov_b32_e32 v50, v48
	s_nop 1
	v_permlane32_swap_b32_e32 v50, v48
	v_max_f32_e32 v48, v48, v50
	v_mov_b32_e32 v50, v49
	s_nop 1
	v_permlane32_swap_b32_e32 v50, v49
	v_max_f32_e32 v49, v49, v50
	v_mov_b32_e32 v50, v48
	s_nop 1
	v_permlane16_swap_b32_e32 v50, v48
	v_max_f32_e32 v48, v48, v50
	v_mov_b32_e32 v50, v49
	s_nop 1
	v_permlane16_swap_b32_e32 v50, v49
	v_max_f32_e32 v175, v179, v48
	v_sub_f32_e32 v48, v179, v175
	v_max3_f32 v177, v181, v49, v50
	v_exp_f32_e32 v52, v48
	v_sub_f32_e32 v48, v76, v175
	v_sub_f32_e32 v16, v16, v177
	v_exp_f32_e32 v48, v48
	v_sub_f32_e32 v50, v77, v175
	v_exp_f32_e32 v16, v16
	v_sub_f32_e32 v17, v17, v177
	v_exp_f32_e32 v50, v50
	v_sub_f32_e32 v51, v78, v175
	v_exp_f32_e32 v17, v17
	v_sub_f32_e32 v18, v18, v177
	v_exp_f32_e32 v51, v51
	v_sub_f32_e32 v55, v79, v175
	v_exp_f32_e32 v18, v18
	v_sub_f32_e32 v19, v19, v177
	v_exp_f32_e32 v55, v55
	v_sub_f32_e32 v76, v84, v175
	v_exp_f32_e32 v19, v19
	v_sub_f32_e32 v20, v20, v177
	v_exp_f32_e32 v76, v76
	v_sub_f32_e32 v77, v85, v175
	v_sub_f32_e32 v53, v181, v177
	v_exp_f32_e32 v20, v20
	v_sub_f32_e32 v21, v21, v177
	v_exp_f32_e32 v77, v77
	v_sub_f32_e32 v78, v86, v175
	v_exp_f32_e32 v54, v53
	v_exp_f32_e32 v21, v21
	v_sub_f32_e32 v22, v22, v177
	v_add_f32_e32 v49, v50, v48
	v_exp_f32_e32 v78, v78
	v_sub_f32_e32 v79, v87, v175
	v_add_f32_e32 v53, v17, v16
	v_exp_f32_e32 v22, v22
	v_sub_f32_e32 v23, v23, v177
	v_add_f32_e32 v49, v51, v49
	v_exp_f32_e32 v79, v79
	v_add_f32_e32 v53, v18, v53
	v_exp_f32_e32 v23, v23
	v_add_f32_e32 v49, v55, v49
	v_add_f32_e32 v53, v19, v53
	v_add_f32_e32 v49, v76, v49
	v_add_f32_e32 v53, v20, v53
	v_add_f32_e32 v49, v77, v49
	v_add_f32_e32 v53, v21, v53
	v_add_f32_e32 v49, v78, v49
	v_add_f32_e32 v53, v22, v53
	v_add_f32_e32 v176, v79, v49
	v_cvt_pk_bf16_f32 v48, v48, v50
	v_cvt_pk_bf16_f32 v49, v51, v55
	v_cvt_pk_bf16_f32 v50, v76, v77
	v_cvt_pk_bf16_f32 v51, v78, v79
	v_add_f32_e32 v178, v23, v53
	v_cvt_pk_bf16_f32 v16, v16, v17
	v_cvt_pk_bf16_f32 v17, v18, v19
	v_cvt_pk_bf16_f32 v18, v20, v21
	v_cvt_pk_bf16_f32 v19, v22, v23
	v_pk_mul_f32 v[22:23], v[70:71], v[52:53] op_sel_hi:[1,0]
	v_pk_mul_f32 v[20:21], v[68:69], v[52:53] op_sel_hi:[1,0]
	v_fmac_f32_e32 v176, v180, v52
	v_fmac_f32_e32 v178, v183, v54
	s_waitcnt lgkmcnt(10)
	v_mfma_f32_16x16x32_bf16 v[76:79], v[140:143], v[48:51], v[20:23]
	v_add_u32_e32 v180, 0x100, v149
	v_add_u32_e32 v179, 0x100, v150
	s_nop 0
	v_pk_mul_f32 v[22:23], v[74:75], v[54:55] op_sel_hi:[1,0]
	v_pk_mul_f32 v[20:21], v[72:73], v[54:55] op_sel_hi:[1,0]
	s_nop 1
	v_mfma_f32_16x16x32_bf16 v[92:95], v[140:143], v[16:19], v[20:23]
	s_nop 2
	v_mul_f32_e64 v22, v82, v52
	v_mul_f32_e64 v23, v83, v52
	v_pk_mul_f32 v[20:21], v[80:81], v[52:53] op_sel_hi:[1,0]
	s_waitcnt lgkmcnt(8)
	s_nop 0
	v_mfma_f32_16x16x32_bf16 v[96:99], v[136:139], v[48:51], v[20:23]
	s_nop 2
	v_mul_f32_e64 v22, v110, v54
	v_mul_f32_e64 v23, v111, v54
	v_pk_mul_f32 v[20:21], v[108:109], v[54:55] op_sel_hi:[1,0]
	s_nop 1
	v_mfma_f32_16x16x32_bf16 v[108:111], v[136:139], v[16:19], v[20:23]
	s_nop 2
	v_mul_f32_e64 v22, v114, v52
	v_mul_f32_e64 v23, v115, v52
	v_pk_mul_f32 v[20:21], v[112:113], v[52:53] op_sel_hi:[1,0]
	s_waitcnt lgkmcnt(6)
	s_nop 0
	v_mfma_f32_16x16x32_bf16 v[112:115], v[132:135], v[48:51], v[20:23]
	s_nop 2
	v_mul_f32_e64 v22, v118, v54
	v_mul_f32_e64 v23, v119, v54
	v_pk_mul_f32 v[20:21], v[116:117], v[54:55] op_sel_hi:[1,0]
	s_nop 1
	v_mfma_f32_16x16x32_bf16 v[116:119], v[132:135], v[16:19], v[20:23]
	s_nop 2
	v_mul_f32_e64 v22, v122, v52
	v_mul_f32_e64 v23, v123, v52
	v_pk_mul_f32 v[20:21], v[120:121], v[52:53] op_sel_hi:[1,0]
	s_waitcnt lgkmcnt(4)
	s_nop 0
	v_mfma_f32_16x16x32_bf16 v[120:123], v[128:131], v[48:51], v[20:23]
	s_nop 2
	v_mul_f32_e64 v22, v126, v54
	v_mul_f32_e64 v23, v127, v54
	v_pk_mul_f32 v[20:21], v[124:125], v[54:55] op_sel_hi:[1,0]
	s_nop 1
	v_mfma_f32_16x16x32_bf16 v[124:127], v[128:131], v[16:19], v[20:23]
	v_add_u32_e32 v16, 0xe0, v149
	v_med3_i32 v16, v16, 0, s75
	v_lshl_add_u32 v16, v16, 9, v152
	global_load_dwordx4 v[68:71], v16, s[98:99]
	v_add_u32_e32 v16, 0xe0, v150
	v_med3_i32 v16, v16, 0, s75
	v_lshl_add_u32 v16, v16, 9, v152
	global_load_dwordx4 v[72:75], v16, s[98:99]
	v_add_u32_e32 v16, 0xe0, v151
	v_med3_i32 v16, v16, 0, s75
	v_lshl_add_u32 v16, v16, 9, v152
	global_load_dwordx4 v[80:83], v16, s[98:99]
	v_add_u32_e32 v16, 0xe0, v252
	v_med3_i32 v16, v16, 0, s75
	v_lshl_add_u32 v16, v16, 9, v152
	global_load_dwordx4 v[84:87], v16, s[98:99]
	v_or_b32_e32 v16, 0xe0, v166
	v_add_u32_e32 v16, s76, v16
	v_med3_i32 v16, v16, 0, s75
	v_lshl_add_u32 v16, v16, 9, v158
	global_load_dwordx4 v[48:51], v16, s[100:101]
	global_load_dwordx4 v[52:55], v16, s[100:101] offset:64
	v_or_b32_e32 v16, 0xf0, v166
	v_add_u32_e32 v16, s76, v16
	v_med3_i32 v16, v16, 0, s75
	v_lshl_add_u32 v20, v16, 9, v158
	global_load_dwordx4 v[16:19], v20, s[100:101]
	s_nop 0
	global_load_dwordx4 v[20:23], v20, s[100:101] offset:64
	ds_read_b64_tr_b16 v[142:143], v169 offset:6912
	ds_read_b64_tr_b16 v[140:141], v169 offset:4608
	ds_read_b64_tr_b16 v[136:137], v169 offset:4640
	ds_read_b64_tr_b16 v[138:139], v169 offset:6944
	ds_read_b64_tr_b16 v[132:133], v169 offset:4672
	ds_read_b64_tr_b16 v[134:135], v169 offset:6976
	ds_read_b64_tr_b16 v[128:129], v169 offset:4704
	ds_read_b64_tr_b16 v[130:131], v169 offset:7008
	s_waitcnt vmcnt(15)
	ds_write_b128 v241, v[64:67]
	s_waitcnt vmcnt(14)
	ds_write_b128 v242, v[88:91]
	s_waitcnt vmcnt(13)
	ds_write_b128 v243, v[100:103]
	s_waitcnt vmcnt(12)
	ds_write_b128 v244, v[104:107]
	v_mfma_f32_16x16x32_bf16 v[64:67], v[32:35], v[4:7], 0
	v_mfma_f32_16x16x32_bf16 v[32:35], v[32:35], v[12:15], 0
	v_mfma_f32_16x16x32_bf16 v[64:67], v[40:43], v[8:11], v[64:67]
	v_mfma_f32_16x16x32_bf16 v[88:91], v[56:59], v[4:7], 0
	v_mfma_f32_16x16x32_bf16 v[32:35], v[40:43], v[0:3], v[32:35]
	v_mfma_f32_16x16x32_bf16 v[40:43], v[56:59], v[12:15], 0
	v_add_u32_e32 v57, 0xe0, v154
	v_sub_u32_e32 v56, v57, v147
	v_add_u32_e32 v59, 1, v56
	s_nop 1
	v_cmp_gt_u32_e64 s[0:1], v59, v146
	v_cmp_gt_u32_e32 vcc, v56, v146
	s_nop 0
	v_cndmask_b32_e64 v65, v65, v246, s[0:1]
	s_nop 0
	v_cndmask_b32_e32 v64, v64, v246, vcc
	v_mfma_f32_16x16x32_bf16 v[88:91], v[60:63], v[8:11], v[88:91]
	v_max_f32_e32 v58, v64, v65
	v_add_u32_e32 v59, 2, v56
	v_cmp_gt_u32_e64 s[22:23], v59, v146
	v_mfma_f32_16x16x32_bf16 v[40:43], v[60:63], v[0:3], v[40:43]
	v_add_u32_e32 v60, 3, v56
	v_cmp_gt_u32_e64 s[24:25], v60, v146
	v_cndmask_b32_e64 v66, v66, v246, s[22:23]
	v_sub_u32_e32 v57, v57, v148
	v_cndmask_b32_e64 v67, v67, v246, s[24:25]
	v_max3_f32 v58, v58, v66, v67
	v_add_u32_e32 v59, 16, v56
	v_add_u32_e32 v60, 17, v56
	v_cmp_gt_u32_e64 s[26:27], v59, v146
	v_cmp_gt_u32_e64 s[28:29], v60, v146
	v_cmp_gt_u32_e64 s[38:39], v57, v145
	v_cndmask_b32_e64 v88, v88, v246, s[26:27]
	v_cndmask_b32_e64 v89, v89, v246, s[28:29]
	v_max3_f32 v58, v58, v88, v89
	v_add_u32_e32 v59, 18, v56
	v_add_u32_e32 v56, 19, v56
	v_cmp_gt_u32_e64 s[30:31], v59, v146
	v_cmp_gt_u32_e64 s[34:35], v56, v146
	v_add_u32_e32 v60, 3, v57
	v_cndmask_b32_e64 v90, v90, v246, s[30:31]
	v_cndmask_b32_e64 v91, v91, v246, s[34:35]
	v_max3_f32 v56, v58, v90, v91
	v_add_u32_e32 v59, 1, v57
	v_cmp_gt_u32_e64 s[40:41], v59, v145
	v_cndmask_b32_e64 v32, v32, v246, s[38:39]
	s_nop 0
	v_cndmask_b32_e64 v33, v33, v246, s[40:41]
	v_max_f32_e32 v58, v32, v33
	v_add_u32_e32 v59, 2, v57
	v_cmp_gt_u32_e64 s[42:43], v59, v145
	v_cmp_gt_u32_e64 s[44:45], v60, v145
	s_nop 0
	v_cndmask_b32_e64 v34, v34, v246, s[42:43]
	v_cndmask_b32_e64 v35, v35, v246, s[44:45]
	v_max3_f32 v58, v58, v34, v35
	v_add_u32_e32 v59, 16, v57
	v_add_u32_e32 v60, 17, v57
	v_cmp_gt_u32_e64 s[46:47], v59, v145
	v_cmp_gt_u32_e64 s[48:49], v60, v145
	s_nop 0
	v_cndmask_b32_e64 v40, v40, v246, s[46:47]
	v_cndmask_b32_e64 v41, v41, v246, s[48:49]
	v_max3_f32 v58, v58, v40, v41
	v_add_u32_e32 v59, 18, v57
	v_add_u32_e32 v57, 19, v57
	v_cmp_gt_u32_e64 s[50:51], v59, v145
	v_cmp_gt_u32_e64 s[52:53], v57, v145
	s_nop 0
	v_cndmask_b32_e64 v42, v42, v246, s[50:51]
	v_cndmask_b32_e64 v43, v43, v246, s[52:53]
	v_max3_f32 v57, v58, v42, v43
	v_mov_b32_e32 v58, v56
	s_nop 1
	v_permlane32_swap_b32_e32 v58, v56
	v_max_f32_e32 v56, v56, v58
	v_mov_b32_e32 v58, v57
	s_nop 1
	v_permlane32_swap_b32_e32 v58, v57
	v_max_f32_e32 v57, v57, v58
	v_mov_b32_e32 v58, v56
	s_nop 1
	v_permlane16_swap_b32_e32 v58, v56
	v_max_f32_e32 v56, v56, v58
	v_mov_b32_e32 v58, v57
	s_nop 1
	v_permlane16_swap_b32_e32 v58, v57
	v_max_f32_e32 v181, v175, v56
	v_sub_f32_e32 v56, v175, v181
	v_max3_f32 v184, v177, v57, v58
	v_exp_f32_e32 v60, v56
	v_sub_f32_e32 v56, v64, v181
	v_sub_f32_e32 v32, v32, v184
	v_exp_f32_e32 v56, v56
	v_sub_f32_e32 v58, v65, v181
	v_exp_f32_e32 v32, v32
	v_sub_f32_e32 v33, v33, v184
	v_exp_f32_e32 v58, v58
	v_sub_f32_e32 v59, v66, v181
	v_exp_f32_e32 v33, v33
	v_sub_f32_e32 v34, v34, v184
	v_exp_f32_e32 v59, v59
	v_sub_f32_e32 v63, v67, v181
	v_exp_f32_e32 v34, v34
	v_sub_f32_e32 v35, v35, v184
	v_exp_f32_e32 v63, v63
	v_sub_f32_e32 v64, v88, v181
	v_exp_f32_e32 v35, v35
	v_sub_f32_e32 v40, v40, v184
	v_exp_f32_e32 v64, v64
	v_sub_f32_e32 v65, v89, v181
	v_sub_f32_e32 v61, v177, v184
	v_exp_f32_e32 v40, v40
	v_sub_f32_e32 v41, v41, v184
	v_exp_f32_e32 v65, v65
	v_sub_f32_e32 v66, v90, v181
	v_exp_f32_e32 v62, v61
	v_exp_f32_e32 v41, v41
	v_sub_f32_e32 v42, v42, v184
	v_add_f32_e32 v57, v58, v56
	v_exp_f32_e32 v66, v66
	v_sub_f32_e32 v67, v91, v181
	v_add_f32_e32 v61, v33, v32
	v_exp_f32_e32 v42, v42
	v_sub_f32_e32 v43, v43, v184
	v_add_f32_e32 v57, v59, v57
	v_exp_f32_e32 v67, v67
	v_add_f32_e32 v61, v34, v61
	v_exp_f32_e32 v43, v43
	v_add_f32_e32 v57, v63, v57
	v_add_f32_e32 v61, v35, v61
	v_add_f32_e32 v57, v64, v57
	v_add_f32_e32 v61, v40, v61
	v_add_f32_e32 v57, v65, v57
	v_add_f32_e32 v61, v41, v61
	v_add_f32_e32 v57, v66, v57
	v_add_f32_e32 v61, v42, v61
	v_add_f32_e32 v183, v67, v57
	v_cvt_pk_bf16_f32 v56, v56, v58
	v_cvt_pk_bf16_f32 v57, v59, v63
	v_cvt_pk_bf16_f32 v58, v64, v65
	v_cvt_pk_bf16_f32 v59, v66, v67
	v_add_f32_e32 v185, v43, v61
	v_cvt_pk_bf16_f32 v32, v32, v33
	v_cvt_pk_bf16_f32 v33, v34, v35
	v_cvt_pk_bf16_f32 v34, v40, v41
	v_cvt_pk_bf16_f32 v35, v42, v43
	v_pk_mul_f32 v[42:43], v[78:79], v[60:61] op_sel_hi:[1,0]
	v_pk_mul_f32 v[40:41], v[76:77], v[60:61] op_sel_hi:[1,0]
	v_fmac_f32_e32 v185, v178, v62
	s_waitcnt lgkmcnt(10)
	v_mfma_f32_16x16x32_bf16 v[100:103], v[140:143], v[56:59], v[40:43]
	v_add_u32_e32 v178, 0x100, v151
	v_fmac_f32_e32 v183, v176, v60
	v_add_u32_e32 v177, 0x100, v252
	v_pk_mul_f32 v[42:43], v[94:95], v[62:63] op_sel_hi:[1,0]
	v_pk_mul_f32 v[40:41], v[92:93], v[62:63] op_sel_hi:[1,0]
	s_nop 1
	v_mfma_f32_16x16x32_bf16 v[92:95], v[140:143], v[32:35], v[40:43]
	s_nop 2
	v_mul_f32_e64 v42, v98, v60
	v_mul_f32_e64 v43, v99, v60
	v_pk_mul_f32 v[40:41], v[96:97], v[60:61] op_sel_hi:[1,0]
	s_waitcnt lgkmcnt(8)
	s_nop 0
	v_mfma_f32_16x16x32_bf16 v[104:107], v[136:139], v[56:59], v[40:43]
	s_nop 2
	v_mul_f32_e64 v42, v110, v62
	v_mul_f32_e64 v43, v111, v62
	v_pk_mul_f32 v[40:41], v[108:109], v[62:63] op_sel_hi:[1,0]
	s_nop 1
	v_mfma_f32_16x16x32_bf16 v[108:111], v[136:139], v[32:35], v[40:43]
	s_nop 2
	v_mul_f32_e64 v42, v114, v60
	v_mul_f32_e64 v43, v115, v60
	v_pk_mul_f32 v[40:41], v[112:113], v[60:61] op_sel_hi:[1,0]
	s_waitcnt lgkmcnt(6)
	s_nop 0
	v_mfma_f32_16x16x32_bf16 v[112:115], v[132:135], v[56:59], v[40:43]
	s_nop 2
	v_mul_f32_e64 v42, v118, v62
	v_mul_f32_e64 v43, v119, v62
	v_pk_mul_f32 v[40:41], v[116:117], v[62:63] op_sel_hi:[1,0]
	s_nop 1
	v_mfma_f32_16x16x32_bf16 v[116:119], v[132:135], v[32:35], v[40:43]
	s_nop 2
	v_mul_f32_e64 v42, v122, v60
	v_mul_f32_e64 v43, v123, v60
	v_pk_mul_f32 v[40:41], v[120:121], v[60:61] op_sel_hi:[1,0]
	s_waitcnt lgkmcnt(4)
	s_nop 0
	v_mfma_f32_16x16x32_bf16 v[120:123], v[128:131], v[56:59], v[40:43]
	s_nop 2
	v_mul_f32_e64 v42, v126, v62
	v_mul_f32_e64 v43, v127, v62
	v_pk_mul_f32 v[40:41], v[124:125], v[62:63] op_sel_hi:[1,0]
	s_nop 1
	v_mfma_f32_16x16x32_bf16 v[124:127], v[128:131], v[32:35], v[40:43]
	v_med3_i32 v32, v180, 0, s75
	v_lshl_add_u32 v32, v32, 9, v152
	global_load_dwordx4 v[56:59], v32, s[98:99]
	v_med3_i32 v32, v179, 0, s75
	v_lshl_add_u32 v32, v32, 9, v152
	global_load_dwordx4 v[60:63], v32, s[98:99]
	v_med3_i32 v32, v178, 0, s75
	v_lshl_add_u32 v32, v32, 9, v152
	global_load_dwordx4 v[88:91], v32, s[98:99]
	v_med3_i32 v32, v177, 0, s75
	v_lshl_add_u32 v32, v32, 9, v152
	global_load_dwordx4 v[96:99], v32, s[98:99]
	v_or_b32_e32 v32, 0x100, v166
	v_add_u32_e32 v32, s76, v32
	v_med3_i32 v32, v32, 0, s75
	v_lshl_add_u32 v32, v32, 9, v158
	global_load_dwordx4 v[76:79], v32, s[100:101]
	global_load_dwordx4 v[64:67], v32, s[100:101] offset:64
	v_or_b32_e32 v32, 0x110, v166
	v_add_u32_e32 v32, s76, v32
	v_med3_i32 v32, v32, 0, s75
	v_lshl_add_u32 v32, v32, 9, v158
	global_load_dwordx4 v[40:43], v32, s[100:101]
	s_nop 0
	global_load_dwordx4 v[32:35], v32, s[100:101] offset:64
	ds_read_b64_tr_b16 v[142:143], v169 offset:2304
	ds_read_b64_tr_b16 v[140:141], v169
	ds_read_b64_tr_b16 v[136:137], v169 offset:32
	ds_read_b64_tr_b16 v[138:139], v169 offset:2336
	ds_read_b64_tr_b16 v[132:133], v169 offset:64
	ds_read_b64_tr_b16 v[134:135], v169 offset:2368
	ds_read_b64_tr_b16 v[128:129], v169 offset:96
	ds_read_b64_tr_b16 v[130:131], v169 offset:2400
	s_waitcnt vmcnt(15)
	ds_write_b128 v241, v[68:71] offset:4608
	s_waitcnt vmcnt(14)
	ds_write_b128 v242, v[72:75] offset:4608
	s_waitcnt vmcnt(13)
	ds_write_b128 v243, v[80:83] offset:4608
	s_waitcnt vmcnt(12)
	ds_write_b128 v244, v[84:87] offset:4608
	v_mfma_f32_16x16x32_bf16 v[68:71], v[36:39], v[4:7], 0
	v_mfma_f32_16x16x32_bf16 v[72:75], v[24:27], v[4:7], 0
	v_mfma_f32_16x16x32_bf16 v[24:27], v[24:27], v[12:15], 0
	v_mfma_f32_16x16x32_bf16 v[68:71], v[44:47], v[8:11], v[68:71]
	v_mfma_f32_16x16x32_bf16 v[72:75], v[28:31], v[8:11], v[72:75]
	v_mfma_f32_16x16x32_bf16 v[24:27], v[28:31], v[0:3], v[24:27]
	v_add_u32_e32 v29, 0x100, v154
	v_sub_u32_e32 v28, v29, v147
	v_add_u32_e32 v31, 1, v28
	v_mfma_f32_16x16x32_bf16 v[36:39], v[36:39], v[12:15], 0
	s_nop 1
	v_cmp_gt_u32_e64 s[0:1], v31, v146
	v_cmp_gt_u32_e32 vcc, v28, v146
	s_nop 0
	v_cndmask_b32_e64 v69, v69, v246, s[0:1]
	s_nop 0
	v_cndmask_b32_e32 v68, v68, v246, vcc
	v_mfma_f32_16x16x32_bf16 v[36:39], v[44:47], v[0:3], v[36:39]
	v_max_f32_e32 v30, v68, v69
	v_add_u32_e32 v31, 2, v28
	v_add_u32_e32 v44, 3, v28
	v_cmp_gt_u32_e64 s[22:23], v31, v146
	v_cmp_gt_u32_e64 s[24:25], v44, v146
	v_sub_u32_e32 v29, v29, v148
	v_cndmask_b32_e64 v70, v70, v246, s[22:23]
	v_cndmask_b32_e64 v71, v71, v246, s[24:25]
	v_max3_f32 v30, v30, v70, v71
	v_add_u32_e32 v31, 16, v28
	v_add_u32_e32 v44, 17, v28
	v_cmp_gt_u32_e64 s[26:27], v31, v146
	v_cmp_gt_u32_e64 s[28:29], v44, v146
	v_cmp_gt_u32_e64 s[38:39], v29, v145
	v_cndmask_b32_e64 v72, v72, v246, s[26:27]
	v_cndmask_b32_e64 v73, v73, v246, s[28:29]
	v_max3_f32 v30, v30, v72, v73
	v_add_u32_e32 v31, 18, v28
	v_add_u32_e32 v28, 19, v28
	v_cmp_gt_u32_e64 s[30:31], v31, v146
	v_cmp_gt_u32_e64 s[34:35], v28, v146
	v_add_u32_e32 v44, 3, v29
	v_cndmask_b32_e64 v74, v74, v246, s[30:31]
	v_cndmask_b32_e64 v75, v75, v246, s[34:35]
	v_max3_f32 v28, v30, v74, v75
	v_add_u32_e32 v31, 1, v29
	v_cmp_gt_u32_e64 s[40:41], v31, v145
	v_cndmask_b32_e64 v36, v36, v246, s[38:39]
	s_nop 0
	v_cndmask_b32_e64 v37, v37, v246, s[40:41]
	v_max_f32_e32 v30, v36, v37
	v_add_u32_e32 v31, 2, v29
	v_cmp_gt_u32_e64 s[42:43], v31, v145
	v_cmp_gt_u32_e64 s[44:45], v44, v145
	s_nop 0
	v_cndmask_b32_e64 v38, v38, v246, s[42:43]
	v_cndmask_b32_e64 v39, v39, v246, s[44:45]
	v_max3_f32 v30, v30, v38, v39
	v_add_u32_e32 v31, 16, v29
	v_add_u32_e32 v44, 17, v29
	v_cmp_gt_u32_e64 s[46:47], v31, v145
	v_cmp_gt_u32_e64 s[48:49], v44, v145
	s_nop 0
	v_cndmask_b32_e64 v24, v24, v246, s[46:47]
	v_cndmask_b32_e64 v25, v25, v246, s[48:49]
	v_max3_f32 v30, v30, v24, v25
	v_add_u32_e32 v31, 18, v29
	v_add_u32_e32 v29, 19, v29
	v_cmp_gt_u32_e64 s[50:51], v31, v145
	v_cmp_gt_u32_e64 s[52:53], v29, v145
	s_nop 0
	v_cndmask_b32_e64 v26, v26, v246, s[50:51]
	v_cndmask_b32_e64 v27, v27, v246, s[52:53]
	v_max3_f32 v29, v30, v26, v27
	v_mov_b32_e32 v30, v28
	s_nop 1
	v_permlane32_swap_b32_e32 v30, v28
	v_max_f32_e32 v28, v28, v30
	v_mov_b32_e32 v30, v29
	s_nop 1
	v_permlane32_swap_b32_e32 v30, v29
	v_max_f32_e32 v29, v29, v30
	v_mov_b32_e32 v30, v28
	s_nop 1
	v_permlane16_swap_b32_e32 v30, v28
	v_max_f32_e32 v28, v28, v30
	v_mov_b32_e32 v30, v29
	v_max_f32_e32 v175, v181, v28
	s_nop 0
	v_permlane16_swap_b32_e32 v30, v29
	v_sub_f32_e32 v28, v181, v175
	v_exp_f32_e32 v44, v28
	v_sub_f32_e32 v28, v68, v175
	v_max_f32_e32 v46, v29, v30
	v_exp_f32_e32 v28, v28
	v_sub_f32_e32 v30, v69, v175
	v_exp_f32_e32 v30, v30
	v_sub_f32_e32 v31, v70, v175
	v_exp_f32_e32 v31, v31
	v_sub_f32_e32 v47, v71, v175
	v_max_f32_e32 v181, v184, v46
	v_exp_f32_e32 v47, v47
	v_sub_f32_e32 v68, v72, v175
	v_sub_f32_e32 v36, v36, v181
	v_exp_f32_e32 v68, v68
	v_sub_f32_e32 v69, v73, v175
	v_exp_f32_e32 v36, v36
	v_sub_f32_e32 v37, v37, v181
	v_exp_f32_e32 v69, v69
	v_sub_f32_e32 v70, v74, v175
	v_exp_f32_e32 v37, v37
	v_sub_f32_e32 v38, v38, v181
	v_add_f32_e32 v29, v30, v28
	v_exp_f32_e32 v70, v70
	v_sub_f32_e32 v71, v75, v175
	v_exp_f32_e32 v38, v38
	v_sub_f32_e32 v39, v39, v181
	v_add_f32_e32 v29, v31, v29
	v_exp_f32_e32 v71, v71
	v_exp_f32_e32 v39, v39
	v_sub_f32_e32 v24, v24, v181
	v_add_f32_e32 v29, v47, v29
	v_sub_f32_e32 v45, v184, v181
	v_exp_f32_e32 v24, v24
	v_sub_f32_e32 v25, v25, v181
	v_add_f32_e32 v29, v68, v29
	v_exp_f32_e32 v46, v45
	v_exp_f32_e32 v25, v25
	v_add_f32_e32 v29, v69, v29
	v_add_f32_e32 v45, v37, v36
	v_add_f32_e32 v29, v70, v29
	v_add_f32_e32 v45, v38, v45
	v_add_f32_e32 v176, v71, v29
	v_cvt_pk_bf16_f32 v29, v31, v47
	v_add_f32_e32 v45, v39, v45
	v_cndmask_b32_e64 v47, v24, 0, s[46:47]
	v_add_f32_e32 v24, v47, v45
	v_cndmask_b32_e64 v45, v25, 0, s[48:49]
	v_sub_f32_e32 v25, v26, v181
	v_exp_f32_e32 v25, v25
	v_cvt_pk_bf16_f32 v28, v28, v30
	v_cvt_pk_bf16_f32 v30, v68, v69
	v_add_f32_e32 v24, v45, v24
	v_cndmask_b32_e64 v68, v25, 0, s[50:51]
	v_sub_f32_e32 v25, v27, v181
	v_exp_f32_e32 v25, v25
	v_add_f32_e32 v24, v68, v24
	v_fmac_f32_e32 v176, v183, v44
	v_cvt_pk_bf16_f32 v31, v70, v71
	v_cndmask_b32_e64 v27, v25, 0, s[52:53]
	v_add_f32_e32 v183, v27, v24
	v_cvt_pk_bf16_f32 v24, v36, v37
	v_cvt_pk_bf16_f32 v25, v38, v39
	v_pk_mul_f32 v[38:39], v[102:103], v[44:45] op_sel_hi:[1,0]
	v_pk_mul_f32 v[36:37], v[100:101], v[44:45] op_sel_hi:[1,0]
	v_cvt_pk_bf16_f32 v26, v47, v45
	v_cvt_pk_bf16_f32 v27, v68, v27
	s_waitcnt lgkmcnt(10)
	v_mfma_f32_16x16x32_bf16 v[80:83], v[140:143], v[28:31], v[36:39]
	v_fmac_f32_e32 v183, v185, v46
	v_add_u32_e32 v184, s76, v204
	v_add_u32_e32 v185, s76, v205
	v_pk_mul_f32 v[38:39], v[94:95], v[46:47] op_sel_hi:[1,0]
	v_pk_mul_f32 v[36:37], v[92:93], v[46:47] op_sel_hi:[1,0]
	s_nop 1
	v_mfma_f32_16x16x32_bf16 v[84:87], v[140:143], v[24:27], v[36:39]
	s_nop 2
	v_mul_f32_e64 v38, v106, v44
	v_mul_f32_e64 v39, v107, v44
	v_pk_mul_f32 v[36:37], v[104:105], v[44:45] op_sel_hi:[1,0]
	s_waitcnt lgkmcnt(8)
	s_nop 0
	v_mfma_f32_16x16x32_bf16 v[104:107], v[136:139], v[28:31], v[36:39]
	s_nop 2
	v_mul_f32_e64 v38, v110, v46
	v_mul_f32_e64 v39, v111, v46
	v_pk_mul_f32 v[36:37], v[108:109], v[46:47] op_sel_hi:[1,0]
	s_nop 1
	v_mfma_f32_16x16x32_bf16 v[108:111], v[136:139], v[24:27], v[36:39]
	s_nop 2
	v_mul_f32_e64 v38, v114, v44
	v_mul_f32_e64 v39, v115, v44
	v_pk_mul_f32 v[36:37], v[112:113], v[44:45] op_sel_hi:[1,0]
	s_waitcnt lgkmcnt(6)
	s_nop 0
	v_mfma_f32_16x16x32_bf16 v[112:115], v[132:135], v[28:31], v[36:39]
	s_nop 2
	v_mul_f32_e64 v38, v118, v46
	v_mul_f32_e64 v39, v119, v46
	v_pk_mul_f32 v[36:37], v[116:117], v[46:47] op_sel_hi:[1,0]
	s_nop 1
	v_mfma_f32_16x16x32_bf16 v[116:119], v[132:135], v[24:27], v[36:39]
	s_nop 2
	v_mul_f32_e64 v38, v122, v44
	v_mul_f32_e64 v39, v123, v44
	v_pk_mul_f32 v[36:37], v[120:121], v[44:45] op_sel_hi:[1,0]
	s_waitcnt lgkmcnt(4)
	s_nop 0
	v_mfma_f32_16x16x32_bf16 v[120:123], v[128:131], v[28:31], v[36:39]
	v_mul_f32_e64 v30, v126, v46
	v_mul_f32_e64 v31, v127, v46
	v_pk_mul_f32 v[28:29], v[124:125], v[46:47] op_sel_hi:[1,0]
	s_nop 1
	v_mfma_f32_16x16x32_bf16 v[124:127], v[128:131], v[24:27], v[28:31]
	v_add_u32_e32 v24, 0x120, v149
	v_med3_i32 v24, v24, 0, s75
	v_lshl_add_u32 v24, v24, 9, v152
	global_load_dwordx4 v[28:31], v24, s[98:99]
	v_add_u32_e32 v24, 0x120, v150
	v_med3_i32 v24, v24, 0, s75
	v_lshl_add_u32 v24, v24, 9, v152
	global_load_dwordx4 v[44:47], v24, s[98:99]
	v_add_u32_e32 v24, 0x120, v151
	v_med3_i32 v24, v24, 0, s75
	v_lshl_add_u32 v24, v24, 9, v152
	global_load_dwordx4 v[92:95], v24, s[98:99]
	v_add_u32_e32 v24, 0x120, v252
	v_med3_i32 v24, v24, 0, s75
	v_lshl_add_u32 v24, v24, 9, v152
	global_load_dwordx4 v[100:103], v24, s[98:99]
	v_or_b32_e32 v24, 0x120, v166
	v_add_u32_e32 v24, s76, v24
	v_med3_i32 v24, v24, 0, s75
	v_lshl_add_u32 v24, v24, 9, v158
	global_load_dwordx4 v[72:75], v24, s[100:101]
	global_load_dwordx4 v[68:71], v24, s[100:101] offset:64
	v_or_b32_e32 v24, 0x130, v166
	v_add_u32_e32 v24, s76, v24
	v_med3_i32 v24, v24, 0, s75
	v_lshl_add_u32 v24, v24, 9, v158
	global_load_dwordx4 v[36:39], v24, s[100:101]
	s_nop 0
	global_load_dwordx4 v[24:27], v24, s[100:101] offset:64
	ds_read_b64_tr_b16 v[142:143], v169 offset:6912
	ds_read_b64_tr_b16 v[140:141], v169 offset:4608
	ds_read_b64_tr_b16 v[136:137], v169 offset:4640
	ds_read_b64_tr_b16 v[138:139], v169 offset:6944
	ds_read_b64_tr_b16 v[132:133], v169 offset:4672
	ds_read_b64_tr_b16 v[134:135], v169 offset:6976
	ds_read_b64_tr_b16 v[128:129], v169 offset:4704
	ds_read_b64_tr_b16 v[130:131], v169 offset:7008
	s_waitcnt vmcnt(15)
	ds_write_b128 v241, v[56:59]
	s_waitcnt vmcnt(14)
	ds_write_b128 v242, v[60:63]
	s_waitcnt vmcnt(13)
	ds_write_b128 v243, v[88:91]
	s_waitcnt vmcnt(12)
	ds_write_b128 v244, v[96:99]
	v_mfma_f32_16x16x32_bf16 v[56:59], v[48:51], v[4:7], 0
	v_mfma_f32_16x16x32_bf16 v[60:63], v[16:19], v[4:7], 0
	v_mfma_f32_16x16x32_bf16 v[16:19], v[16:19], v[12:15], 0
	v_mfma_f32_16x16x32_bf16 v[56:59], v[52:55], v[8:11], v[56:59]
	v_mfma_f32_16x16x32_bf16 v[60:63], v[20:23], v[8:11], v[60:63]
	v_mfma_f32_16x16x32_bf16 v[16:19], v[20:23], v[0:3], v[16:19]
	v_sub_u32_e32 v20, v195, v147
	v_add_u32_e32 v23, 1, v20
	s_nop 3
	v_mfma_f32_16x16x32_bf16 v[48:51], v[48:51], v[12:15], 0
	v_cmp_gt_u32_e64 s[0:1], v23, v146
	v_cmp_gt_u32_e32 vcc, v20, v146
	s_nop 0
	v_cndmask_b32_e64 v57, v57, v246, s[0:1]
	s_nop 0
	v_cndmask_b32_e32 v56, v56, v246, vcc
	v_mfma_f32_16x16x32_bf16 v[48:51], v[52:55], v[0:3], v[48:51]
	v_max_f32_e32 v22, v56, v57
	v_add_u32_e32 v23, 2, v20
	v_add_u32_e32 v52, 3, v20
	v_cmp_gt_u32_e64 s[22:23], v23, v146
	v_cmp_gt_u32_e64 s[24:25], v52, v146
	v_sub_u32_e32 v21, v195, v148
	v_cndmask_b32_e64 v58, v58, v246, s[22:23]
	v_cndmask_b32_e64 v59, v59, v246, s[24:25]
	v_max3_f32 v22, v22, v58, v59
	v_add_u32_e32 v23, 16, v20
	v_add_u32_e32 v52, 17, v20
	v_cmp_gt_u32_e64 s[26:27], v23, v146
	v_cmp_gt_u32_e64 s[28:29], v52, v146
	v_cmp_gt_u32_e64 s[38:39], v21, v145
	v_cndmask_b32_e64 v60, v60, v246, s[26:27]
	v_cndmask_b32_e64 v61, v61, v246, s[28:29]
	v_max3_f32 v22, v22, v60, v61
	v_add_u32_e32 v23, 18, v20
	v_add_u32_e32 v20, 19, v20
	v_cmp_gt_u32_e64 s[30:31], v23, v146
	v_cmp_gt_u32_e64 s[34:35], v20, v146
	v_add_u32_e32 v52, 3, v21
	v_cndmask_b32_e64 v62, v62, v246, s[30:31]
	v_cndmask_b32_e64 v63, v63, v246, s[34:35]
	v_max3_f32 v20, v22, v62, v63
	v_add_u32_e32 v23, 1, v21
	v_cmp_gt_u32_e64 s[40:41], v23, v145
	v_cndmask_b32_e64 v48, v48, v246, s[38:39]
	s_nop 0
	v_cndmask_b32_e64 v49, v49, v246, s[40:41]
	v_max_f32_e32 v22, v48, v49
	v_add_u32_e32 v23, 2, v21
	v_cmp_gt_u32_e64 s[42:43], v23, v145
	v_cmp_gt_u32_e64 s[44:45], v52, v145
	s_nop 0
	v_cndmask_b32_e64 v50, v50, v246, s[42:43]
	v_cndmask_b32_e64 v51, v51, v246, s[44:45]
	v_max3_f32 v22, v22, v50, v51
	v_add_u32_e32 v23, 16, v21
	v_add_u32_e32 v52, 17, v21
	v_cmp_gt_u32_e64 s[46:47], v23, v145
	v_cmp_gt_u32_e64 s[48:49], v52, v145
	s_nop 0
	v_cndmask_b32_e64 v16, v16, v246, s[46:47]
	v_cndmask_b32_e64 v17, v17, v246, s[48:49]
	v_max3_f32 v22, v22, v16, v17
	v_add_u32_e32 v23, 18, v21
	v_add_u32_e32 v21, 19, v21
	v_cmp_gt_u32_e64 s[50:51], v23, v145
	v_cmp_gt_u32_e64 s[52:53], v21, v145
	s_nop 0
	v_cndmask_b32_e64 v18, v18, v246, s[50:51]
	v_cndmask_b32_e64 v19, v19, v246, s[52:53]
	v_max3_f32 v21, v22, v18, v19
	v_mov_b32_e32 v22, v20
	s_nop 1
	v_permlane32_swap_b32_e32 v22, v20
	v_max_f32_e32 v20, v20, v22
	v_mov_b32_e32 v22, v21
	s_nop 1
	v_permlane32_swap_b32_e32 v22, v21
	v_max_f32_e32 v21, v21, v22
	v_mov_b32_e32 v22, v20
	s_nop 1
	v_permlane16_swap_b32_e32 v22, v20
	v_max3_f32 v149, v175, v20, v22
	v_sub_f32_e32 v20, v175, v149
	v_exp_f32_e32 v88, v20
	v_sub_f32_e32 v20, v56, v149
	v_sub_f32_e32 v56, v61, v149
	v_exp_f32_e32 v56, v56
	v_exp_f32_e32 v20, v20
	v_sub_f32_e32 v23, v57, v149
	v_exp_f32_e32 v23, v23
	v_sub_f32_e32 v53, v58, v149
	v_cndmask_b32_e64 v58, v56, 0, s[28:29]
	v_sub_f32_e32 v56, v62, v149
	v_mov_b32_e32 v22, v21
	v_exp_f32_e32 v53, v53
	v_sub_f32_e32 v54, v59, v149
	v_exp_f32_e32 v56, v56
	v_permlane16_swap_b32_e32 v22, v21
	v_exp_f32_e32 v54, v54
	v_sub_f32_e32 v55, v60, v149
	v_exp_f32_e32 v55, v55
	v_max_f32_e32 v21, v21, v22
	v_add_f32_e32 v22, v23, v20
	v_cndmask_b32_e64 v59, v56, 0, s[30:31]
	v_sub_f32_e32 v56, v63, v149
	v_add_f32_e32 v22, v53, v22
	v_exp_f32_e32 v56, v56
	v_add_f32_e32 v22, v54, v22
	v_add_f32_e32 v22, v55, v22
	v_add_f32_e32 v22, v58, v22
	v_max_f32_e32 v151, v181, v21
	v_add_f32_e32 v22, v59, v22
	v_cndmask_b32_e64 v60, v56, 0, s[34:35]
	v_cvt_pk_bf16_f32 v56, v20, v23
	v_sub_f32_e32 v20, v181, v151
	v_add_f32_e32 v150, v60, v22
	v_cvt_pk_bf16_f32 v59, v59, v60
	v_exp_f32_e32 v60, v20
	v_sub_f32_e32 v20, v48, v151
	v_exp_f32_e32 v20, v20
	v_sub_f32_e32 v22, v49, v151
	v_exp_f32_e32 v22, v22
	v_sub_f32_e32 v23, v50, v151
	v_exp_f32_e32 v23, v23
	v_sub_f32_e32 v48, v51, v151
	v_exp_f32_e32 v48, v48
	v_sub_f32_e32 v16, v16, v151
	v_exp_f32_e32 v16, v16
	v_sub_f32_e32 v17, v17, v151
	v_exp_f32_e32 v17, v17
	v_add_f32_e32 v21, v22, v20
	v_add_f32_e32 v21, v23, v21
	v_add_f32_e32 v21, v48, v21
	v_cndmask_b32_e64 v49, v16, 0, s[46:47]
	v_add_f32_e32 v16, v49, v21
	v_cndmask_b32_e64 v21, v17, 0, s[48:49]
	v_sub_f32_e32 v17, v18, v151
	v_exp_f32_e32 v17, v17
	v_add_f32_e32 v16, v21, v16
	v_cvt_pk_bf16_f32 v18, v49, v21
	v_cvt_pk_bf16_f32 v57, v53, v54
	v_cndmask_b32_e64 v50, v17, 0, s[50:51]
	v_sub_f32_e32 v17, v19, v151
	v_exp_f32_e32 v17, v17
	v_add_f32_e32 v16, v50, v16
	v_cvt_pk_bf16_f32 v58, v55, v58
	v_fmac_f32_e32 v150, v176, v88
	v_cndmask_b32_e64 v19, v17, 0, s[52:53]
	v_add_f32_e32 v175, v19, v16
	v_cvt_pk_bf16_f32 v16, v20, v22
	v_cvt_pk_bf16_f32 v17, v23, v48
	v_cvt_pk_bf16_f32 v19, v50, v19
	v_pk_mul_f32 v[50:51], v[86:87], v[60:61] op_sel_hi:[1,0]
	v_pk_mul_f32 v[48:49], v[84:85], v[60:61] op_sel_hi:[1,0]
	v_pk_mul_f32 v[22:23], v[82:83], v[88:89] op_sel_hi:[1,0]
	v_pk_mul_f32 v[20:21], v[80:81], v[88:89] op_sel_hi:[1,0]
	s_waitcnt lgkmcnt(10)
	v_mfma_f32_16x16x32_bf16 v[52:55], v[140:143], v[16:19], v[48:51]
	v_fmac_f32_e32 v175, v183, v60
	s_nop 1
	v_pk_mul_f32 v[50:51], v[106:107], v[88:89] op_sel_hi:[1,0]
	v_pk_mul_f32 v[48:49], v[104:105], v[88:89] op_sel_hi:[1,0]
	v_mfma_f32_16x16x32_bf16 v[20:23], v[140:143], v[56:59], v[20:23]
	s_waitcnt lgkmcnt(8)
	v_mfma_f32_16x16x32_bf16 v[104:107], v[136:139], v[56:59], v[48:51]
	s_nop 2
	v_mul_f32_e64 v50, v110, v60
	v_mul_f32_e64 v51, v111, v60
	v_pk_mul_f32 v[48:49], v[108:109], v[60:61] op_sel_hi:[1,0]
	s_nop 1
	v_mfma_f32_16x16x32_bf16 v[108:111], v[136:139], v[16:19], v[48:51]
	s_nop 2
	v_mul_f32_e64 v50, v114, v88
	v_mul_f32_e64 v51, v115, v88
	v_pk_mul_f32 v[48:49], v[112:113], v[88:89] op_sel_hi:[1,0]
	s_waitcnt lgkmcnt(6)
	s_nop 0
	v_mfma_f32_16x16x32_bf16 v[112:115], v[132:135], v[56:59], v[48:51]
	s_nop 2
	v_mul_f32_e64 v50, v118, v60
	v_mul_f32_e64 v51, v119, v60
	v_pk_mul_f32 v[48:49], v[116:117], v[60:61] op_sel_hi:[1,0]
	s_nop 1
	v_mfma_f32_16x16x32_bf16 v[116:119], v[132:135], v[16:19], v[48:51]
	s_nop 2
	v_mul_f32_e64 v50, v122, v88
	v_mul_f32_e64 v51, v123, v88
	v_pk_mul_f32 v[48:49], v[120:121], v[88:89] op_sel_hi:[1,0]
	s_waitcnt lgkmcnt(4)
	s_nop 0
	v_mfma_f32_16x16x32_bf16 v[120:123], v[128:131], v[56:59], v[48:51]
	v_add_u32_e32 v56, 0xffffff00, v206
	v_add_u32_e32 v56, s76, v56
	s_nop 0
	v_pk_mul_f32 v[50:51], v[126:127], v[60:61] op_sel_hi:[1,0]
	v_pk_mul_f32 v[48:49], v[124:125], v[60:61] op_sel_hi:[1,0]
	s_nop 1
	v_mfma_f32_16x16x32_bf16 v[124:127], v[128:131], v[16:19], v[48:51]
	v_add_u32_e32 v16, 0xffffff00, v204
	v_add_u32_e32 v16, s76, v16
	s_nop 0
	v_add_u32_e32 v48, 0xffffff00, v205
	v_add_u32_e32 v48, s76, v48
	v_med3_i32 v16, v16, 0, s75
	v_med3_i32 v48, v48, 0, s75
	v_med3_i32 v56, v56, 0, s75
	v_lshl_add_u32 v56, v56, 9, v152
	global_load_dwordx4 v[88:91], v56, s[98:99]
	v_add_u32_e32 v56, 0xffffff00, v207
	v_add_u32_e32 v56, s76, v56
	v_med3_i32 v56, v56, 0, s75
	v_lshl_add_u32 v56, v56, 9, v152
	global_load_dwordx4 v[96:99], v56, s[98:99]
	v_add_u32_e32 v56, s76, v208
	v_lshl_add_u32 v16, v16, 9, v152
	v_lshl_add_u32 v48, v48, 9, v152
	v_med3_i32 v56, v56, 0, s75
	v_lshl_add_u32 v56, v56, 9, v158
	global_load_dwordx4 v[16:19], v16, s[98:99]
	s_nop 0
	global_load_dwordx4 v[48:51], v48, s[98:99]
	s_nop 0
	global_load_dwordx4 v[84:87], v56, s[100:101]
	global_load_dwordx4 v[80:83], v56, s[100:101] offset:64
	v_or_b32_e32 v56, 0xffffff40, v209
	v_add_u32_e32 v56, s76, v56
	v_med3_i32 v56, v56, 0, s75
	v_lshl_add_u32 v56, v56, 9, v158
	global_load_dwordx4 v[60:63], v56, s[100:101]
	s_nop 0
	global_load_dwordx4 v[56:59], v56, s[100:101] offset:64
	ds_read_b64_tr_b16 v[142:143], v169 offset:2304
	ds_read_b64_tr_b16 v[140:141], v169
	ds_read_b64_tr_b16 v[136:137], v169 offset:32
	ds_read_b64_tr_b16 v[138:139], v169 offset:2336
	ds_read_b64_tr_b16 v[132:133], v169 offset:64
	ds_read_b64_tr_b16 v[134:135], v169 offset:2368
	ds_read_b64_tr_b16 v[128:129], v169 offset:96
	ds_read_b64_tr_b16 v[130:131], v169 offset:2400
	s_waitcnt vmcnt(15)
	ds_write_b128 v241, v[28:31] offset:4608
	s_waitcnt vmcnt(14)
	ds_write_b128 v242, v[44:47] offset:4608
	s_waitcnt vmcnt(13)
	ds_write_b128 v243, v[92:95] offset:4608
	s_waitcnt vmcnt(12)
	ds_write_b128 v244, v[100:103] offset:4608
	v_mfma_f32_16x16x32_bf16 v[28:31], v[76:79], v[4:7], 0
	v_mfma_f32_16x16x32_bf16 v[44:47], v[40:43], v[4:7], 0
	v_mfma_f32_16x16x32_bf16 v[40:43], v[40:43], v[12:15], 0
	v_mfma_f32_16x16x32_bf16 v[28:31], v[64:67], v[8:11], v[28:31]
	v_mfma_f32_16x16x32_bf16 v[44:47], v[32:35], v[8:11], v[44:47]
	v_mfma_f32_16x16x32_bf16 v[32:35], v[32:35], v[0:3], v[40:43]
	s_nop 4
	v_sub_u32_e32 v40, v210, v147
	v_mfma_f32_16x16x32_bf16 v[76:79], v[76:79], v[12:15], 0
	v_add_u32_e32 v43, 1, v40
	v_cmp_gt_u32_e64 s[0:1], v43, v146
	v_cmp_gt_u32_e32 vcc, v40, v146
	s_nop 0
	v_cndmask_b32_e64 v29, v29, v246, s[0:1]
	s_nop 0
	v_cndmask_b32_e32 v28, v28, v246, vcc
	v_mfma_f32_16x16x32_bf16 v[64:67], v[64:67], v[0:3], v[76:79]
	v_max_f32_e32 v42, v28, v29
	v_add_u32_e32 v43, 2, v40
	v_cmp_gt_u32_e64 s[22:23], v43, v146
	v_add_u32_e32 v76, 3, v40
	v_cmp_gt_u32_e64 s[24:25], v76, v146
	v_cndmask_b32_e64 v30, v30, v246, s[22:23]
	v_sub_u32_e32 v41, v210, v148
	v_cndmask_b32_e64 v31, v31, v246, s[24:25]
	v_max3_f32 v42, v42, v30, v31
	v_add_u32_e32 v43, 16, v40
	v_add_u32_e32 v76, 17, v40
	v_cmp_gt_u32_e64 s[26:27], v43, v146
	v_cmp_gt_u32_e64 s[28:29], v76, v146
	v_cmp_gt_u32_e64 s[38:39], v41, v145
	v_cndmask_b32_e64 v44, v44, v246, s[26:27]
	v_cndmask_b32_e64 v45, v45, v246, s[28:29]
	v_max3_f32 v42, v42, v44, v45
	v_add_u32_e32 v43, 18, v40
	v_add_u32_e32 v40, 19, v40
	v_cmp_gt_u32_e64 s[30:31], v43, v146
	v_cmp_gt_u32_e64 s[34:35], v40, v146
	v_add_u32_e32 v76, 3, v41
	v_cndmask_b32_e64 v46, v46, v246, s[30:31]
	v_cndmask_b32_e64 v47, v47, v246, s[34:35]
	v_max3_f32 v40, v42, v46, v47
	v_add_u32_e32 v43, 1, v41
	v_cmp_gt_u32_e64 s[40:41], v43, v145
	v_cndmask_b32_e64 v64, v64, v246, s[38:39]
	s_nop 0
	v_cndmask_b32_e64 v65, v65, v246, s[40:41]
	v_max_f32_e32 v42, v64, v65
	v_add_u32_e32 v43, 2, v41
	v_cmp_gt_u32_e64 s[42:43], v43, v145
	v_cmp_gt_u32_e64 s[44:45], v76, v145
	s_nop 0
	v_cndmask_b32_e64 v66, v66, v246, s[42:43]
	v_cndmask_b32_e64 v67, v67, v246, s[44:45]
	v_max3_f32 v42, v42, v66, v67
	v_add_u32_e32 v43, 16, v41
	v_add_u32_e32 v76, 17, v41
	v_cmp_gt_u32_e64 s[46:47], v43, v145
	v_cmp_gt_u32_e64 s[48:49], v76, v145
	s_nop 0
	v_cndmask_b32_e64 v32, v32, v246, s[46:47]
	v_cndmask_b32_e64 v33, v33, v246, s[48:49]
	v_max3_f32 v42, v42, v32, v33
	v_add_u32_e32 v43, 18, v41
	v_add_u32_e32 v41, 19, v41
	v_cmp_gt_u32_e64 s[50:51], v43, v145
	v_cmp_gt_u32_e64 s[52:53], v41, v145
	s_nop 0
	v_cndmask_b32_e64 v34, v34, v246, s[50:51]
	v_cndmask_b32_e64 v35, v35, v246, s[52:53]
	v_max3_f32 v41, v42, v34, v35
	v_mov_b32_e32 v42, v40
	s_nop 1
	v_permlane32_swap_b32_e32 v42, v40
	v_max_f32_e32 v40, v40, v42
	v_mov_b32_e32 v42, v41
	s_nop 1
	v_permlane32_swap_b32_e32 v42, v41
	v_max_f32_e32 v41, v41, v42
	v_mov_b32_e32 v42, v40
	s_nop 1
	v_permlane16_swap_b32_e32 v42, v40
	v_max3_f32 v176, v149, v40, v42
	v_sub_f32_e32 v28, v28, v176
	v_mov_b32_e32 v42, v41
	v_exp_f32_e32 v28, v28
	v_sub_f32_e32 v29, v29, v176
	v_permlane16_swap_b32_e32 v42, v41
	v_exp_f32_e32 v29, v29
	v_sub_f32_e32 v30, v30, v176
	v_exp_f32_e32 v30, v30
	v_sub_f32_e32 v31, v31, v176
	v_max_f32_e32 v41, v41, v42
	v_exp_f32_e32 v31, v31
	v_sub_f32_e32 v42, v44, v176
	v_sub_f32_e32 v40, v149, v176
	v_exp_f32_e32 v42, v42
	v_sub_f32_e32 v43, v45, v176
	v_exp_f32_e32 v76, v40
	v_exp_f32_e32 v43, v43
	v_sub_f32_e32 v44, v46, v176
	v_add_f32_e32 v40, v29, v28
	v_exp_f32_e32 v44, v44
	v_sub_f32_e32 v45, v47, v176
	v_add_f32_e32 v40, v30, v40
	v_exp_f32_e32 v45, v45
	v_add_f32_e32 v40, v31, v40
	v_add_f32_e32 v40, v42, v40
	v_add_f32_e32 v40, v43, v40
	v_add_f32_e32 v40, v44, v40
	v_add_f32_e32 v149, v45, v40
	v_fmac_f32_e32 v149, v150, v76
	v_max_f32_e32 v150, v151, v41
	v_sub_f32_e32 v40, v151, v150
	v_cvt_pk_bf16_f32 v28, v28, v29
	v_cvt_pk_bf16_f32 v29, v30, v31
	v_cvt_pk_bf16_f32 v31, v44, v45
	v_exp_f32_e32 v44, v40
	v_sub_f32_e32 v40, v64, v150
	v_cvt_pk_bf16_f32 v30, v42, v43
	v_exp_f32_e32 v40, v40
	v_sub_f32_e32 v42, v65, v150
	v_exp_f32_e32 v42, v42
	v_sub_f32_e32 v43, v66, v150
	v_exp_f32_e32 v43, v43
	v_sub_f32_e32 v45, v67, v150
	v_exp_f32_e32 v45, v45
	v_sub_f32_e32 v32, v32, v150
	v_exp_f32_e32 v32, v32
	v_sub_f32_e32 v33, v33, v150
	v_exp_f32_e32 v33, v33
	v_add_f32_e32 v41, v42, v40
	v_add_f32_e32 v41, v43, v41
	v_add_f32_e32 v41, v45, v41
	v_cndmask_b32_e64 v46, v32, 0, s[46:47]
	v_add_f32_e32 v32, v46, v41
	v_cndmask_b32_e64 v41, v33, 0, s[48:49]
	v_sub_f32_e32 v33, v34, v150
	v_exp_f32_e32 v33, v33
	v_add_f32_e32 v32, v41, v32
	v_pk_mul_f32 v[22:23], v[22:23], v[76:77] op_sel_hi:[1,0]
	v_pk_mul_f32 v[20:21], v[20:21], v[76:77] op_sel_hi:[1,0]
	v_cndmask_b32_e64 v47, v33, 0, s[50:51]
	v_sub_f32_e32 v33, v35, v150
	v_exp_f32_e32 v33, v33
	v_add_f32_e32 v32, v47, v32
	v_cvt_pk_bf16_f32 v34, v46, v41
	v_cndmask_b32_e64 v35, v33, 0, s[52:53]
	v_add_f32_e32 v151, v35, v32
	v_cvt_pk_bf16_f32 v32, v40, v42
	v_cvt_pk_bf16_f32 v33, v43, v45
	v_cvt_pk_bf16_f32 v35, v47, v35
	s_waitcnt lgkmcnt(10)
	v_mfma_f32_16x16x32_bf16 v[40:43], v[140:143], v[28:31], v[20:23]
	v_fmac_f32_e32 v151, v175, v44
	s_nop 1
	v_pk_mul_f32 v[22:23], v[54:55], v[44:45] op_sel_hi:[1,0]
	v_pk_mul_f32 v[20:21], v[52:53], v[44:45] op_sel_hi:[1,0]
	s_nop 1
	v_mfma_f32_16x16x32_bf16 v[92:95], v[140:143], v[32:35], v[20:23]
	s_nop 2
	v_mul_f32_e64 v22, v106, v76
	v_mul_f32_e64 v23, v107, v76
	v_pk_mul_f32 v[20:21], v[104:105], v[76:77] op_sel_hi:[1,0]
	s_waitcnt lgkmcnt(8)
	s_nop 0
	v_mfma_f32_16x16x32_bf16 v[104:107], v[136:139], v[28:31], v[20:23]
	s_nop 2
	v_mul_f32_e64 v22, v110, v44
	v_mul_f32_e64 v23, v111, v44
	v_pk_mul_f32 v[20:21], v[108:109], v[44:45] op_sel_hi:[1,0]
	s_nop 1
	v_mfma_f32_16x16x32_bf16 v[108:111], v[136:139], v[32:35], v[20:23]
	s_nop 2
	v_mul_f32_e64 v22, v114, v76
	v_mul_f32_e64 v23, v115, v76
	v_pk_mul_f32 v[20:21], v[112:113], v[76:77] op_sel_hi:[1,0]
	s_waitcnt lgkmcnt(6)
	s_nop 0
	v_mfma_f32_16x16x32_bf16 v[112:115], v[132:135], v[28:31], v[20:23]
	s_nop 2
	v_mul_f32_e64 v22, v118, v44
	v_mul_f32_e64 v23, v119, v44
	v_pk_mul_f32 v[20:21], v[116:117], v[44:45] op_sel_hi:[1,0]
	s_nop 1
	v_mfma_f32_16x16x32_bf16 v[116:119], v[132:135], v[32:35], v[20:23]
	s_nop 2
	v_mul_f32_e64 v22, v122, v76
	v_mul_f32_e64 v23, v123, v76
	v_pk_mul_f32 v[20:21], v[120:121], v[76:77] op_sel_hi:[1,0]
	s_waitcnt lgkmcnt(4)
	s_nop 0
	v_mfma_f32_16x16x32_bf16 v[120:123], v[128:131], v[28:31], v[20:23]
	s_nop 2
	v_mul_f32_e64 v22, v126, v44
	v_mul_f32_e64 v23, v127, v44
	v_pk_mul_f32 v[20:21], v[124:125], v[44:45] op_sel_hi:[1,0]
	s_nop 1
	v_mfma_f32_16x16x32_bf16 v[124:127], v[128:131], v[32:35], v[20:23]
	s_nop 2
	v_add_u32_e32 v20, 0xffffff80, v204
	v_add_u32_e32 v20, s76, v20
	v_med3_i32 v20, v20, 0, s75
	v_lshl_add_u32 v20, v20, 9, v152
	global_load_dwordx4 v[32:35], v20, s[98:99]
	v_add_u32_e32 v20, 0xffffff80, v205
	v_add_u32_e32 v20, s76, v20
	v_med3_i32 v20, v20, 0, s75
	v_lshl_add_u32 v20, v20, 9, v152
	global_load_dwordx4 v[64:67], v20, s[98:99]
	v_add_u32_e32 v20, 0xffffff80, v206
	v_add_u32_e32 v20, s76, v20
	v_med3_i32 v20, v20, 0, s75
	v_lshl_add_u32 v20, v20, 9, v152
	global_load_dwordx4 v[76:79], v20, s[98:99]
	v_add_u32_e32 v20, 0xffffff80, v207
	v_add_u32_e32 v20, s76, v20
	v_med3_i32 v20, v20, 0, s75
	v_lshl_add_u32 v20, v20, 9, v152
	global_load_dwordx4 v[100:103], v20, s[98:99]
	v_or_b32_e32 v20, 0xffffff80, v209
	v_add_u32_e32 v20, s76, v20
	v_med3_i32 v20, v20, 0, s75
	v_lshl_add_u32 v20, v20, 9, v158
	global_load_dwordx4 v[52:55], v20, s[100:101]
	global_load_dwordx4 v[44:47], v20, s[100:101] offset:64
	v_add_u32_e32 v20, s76, v211
	v_med3_i32 v20, v20, 0, s75
	v_lshl_add_u32 v20, v20, 9, v158
	global_load_dwordx4 v[28:31], v20, s[100:101]
	s_nop 0
	global_load_dwordx4 v[20:23], v20, s[100:101] offset:64
	ds_read_b64_tr_b16 v[142:143], v169 offset:6912
	ds_read_b64_tr_b16 v[140:141], v169 offset:4608
	ds_read_b64_tr_b16 v[136:137], v169 offset:4640
	ds_read_b64_tr_b16 v[138:139], v169 offset:6944
	ds_read_b64_tr_b16 v[132:133], v169 offset:4672
	ds_read_b64_tr_b16 v[134:135], v169 offset:6976
	ds_read_b64_tr_b16 v[128:129], v169 offset:4704
	ds_read_b64_tr_b16 v[130:131], v169 offset:7008
	s_waitcnt vmcnt(13)
	ds_write_b128 v241, v[16:19]
	s_waitcnt vmcnt(12)
	ds_write_b128 v242, v[48:51]
	ds_write_b128 v243, v[88:91]
	ds_write_b128 v244, v[96:99]
	v_mfma_f32_16x16x32_bf16 v[16:19], v[72:75], v[4:7], 0
	v_mfma_f32_16x16x32_bf16 v[48:51], v[36:39], v[4:7], 0
	v_mfma_f32_16x16x32_bf16 v[36:39], v[36:39], v[12:15], 0
	v_mfma_f32_16x16x32_bf16 v[16:19], v[68:71], v[8:11], v[16:19]
	v_mfma_f32_16x16x32_bf16 v[48:51], v[24:27], v[8:11], v[48:51]
	v_mfma_f32_16x16x32_bf16 v[24:27], v[24:27], v[0:3], v[36:39]
	s_nop 4
	v_sub_u32_e32 v36, v212, v147
	v_mfma_f32_16x16x32_bf16 v[72:75], v[72:75], v[12:15], 0
	v_add_u32_e32 v39, 1, v36
	v_cmp_gt_u32_e64 s[0:1], v39, v146
	v_cmp_gt_u32_e32 vcc, v36, v146
	s_nop 0
	v_cndmask_b32_e64 v17, v17, v246, s[0:1]
	s_nop 0
	v_cndmask_b32_e32 v16, v16, v246, vcc
	v_mfma_f32_16x16x32_bf16 v[68:71], v[68:71], v[0:3], v[72:75]
	v_max_f32_e32 v38, v16, v17
	v_add_u32_e32 v39, 2, v36
	v_cmp_gt_u32_e64 s[22:23], v39, v146
	v_add_u32_e32 v72, 3, v36
	v_cmp_gt_u32_e64 s[24:25], v72, v146
	v_cndmask_b32_e64 v18, v18, v246, s[22:23]
	v_sub_u32_e32 v37, v212, v148
	v_cndmask_b32_e64 v19, v19, v246, s[24:25]
	v_max3_f32 v38, v38, v18, v19
	v_add_u32_e32 v39, 16, v36
	v_add_u32_e32 v72, 17, v36
	v_cmp_gt_u32_e64 s[26:27], v39, v146
	v_cmp_gt_u32_e64 s[28:29], v72, v146
	v_cmp_gt_u32_e64 s[38:39], v37, v145
	v_cndmask_b32_e64 v48, v48, v246, s[26:27]
	v_cndmask_b32_e64 v49, v49, v246, s[28:29]
	v_max3_f32 v38, v38, v48, v49
	v_add_u32_e32 v39, 18, v36
	v_add_u32_e32 v36, 19, v36
	v_cmp_gt_u32_e64 s[30:31], v39, v146
	v_cmp_gt_u32_e64 s[34:35], v36, v146
	v_add_u32_e32 v72, 3, v37
	v_cndmask_b32_e64 v50, v50, v246, s[30:31]
	v_cndmask_b32_e64 v51, v51, v246, s[34:35]
	v_max3_f32 v36, v38, v50, v51
	v_add_u32_e32 v39, 1, v37
	v_cmp_gt_u32_e64 s[40:41], v39, v145
	v_cndmask_b32_e64 v68, v68, v246, s[38:39]
	s_nop 0
	v_cndmask_b32_e64 v69, v69, v246, s[40:41]
	v_max_f32_e32 v38, v68, v69
	v_add_u32_e32 v39, 2, v37
	v_cmp_gt_u32_e64 s[42:43], v39, v145
	v_cmp_gt_u32_e64 s[44:45], v72, v145
	s_nop 0
	v_cndmask_b32_e64 v70, v70, v246, s[42:43]
	v_cndmask_b32_e64 v71, v71, v246, s[44:45]
	v_max3_f32 v38, v38, v70, v71
	v_add_u32_e32 v39, 16, v37
	v_add_u32_e32 v72, 17, v37
	v_cmp_gt_u32_e64 s[46:47], v39, v145
	v_cmp_gt_u32_e64 s[48:49], v72, v145
	s_nop 0
	v_cndmask_b32_e64 v24, v24, v246, s[46:47]
	v_cndmask_b32_e64 v25, v25, v246, s[48:49]
	v_max3_f32 v38, v38, v24, v25
	v_add_u32_e32 v39, 18, v37
	v_add_u32_e32 v37, 19, v37
	v_cmp_gt_u32_e64 s[50:51], v39, v145
	v_cmp_gt_u32_e64 s[52:53], v37, v145
	s_nop 0
	v_cndmask_b32_e64 v26, v26, v246, s[50:51]
	v_cndmask_b32_e64 v27, v27, v246, s[52:53]
	v_max3_f32 v37, v38, v26, v27
	v_mov_b32_e32 v38, v36
	s_nop 1
	v_permlane32_swap_b32_e32 v38, v36
	v_max_f32_e32 v36, v36, v38
	v_mov_b32_e32 v38, v37
	s_nop 1
	v_permlane32_swap_b32_e32 v38, v37
	v_max_f32_e32 v37, v37, v38
	v_mov_b32_e32 v38, v36
	s_nop 1
	v_permlane16_swap_b32_e32 v38, v36
	v_max3_f32 v145, v176, v36, v38
	v_sub_f32_e32 v16, v16, v145
	v_mov_b32_e32 v38, v37
	v_exp_f32_e32 v16, v16
	v_sub_f32_e32 v17, v17, v145
	v_permlane16_swap_b32_e32 v38, v37
	v_exp_f32_e32 v17, v17
	v_sub_f32_e32 v18, v18, v145
	v_exp_f32_e32 v18, v18
	v_sub_f32_e32 v19, v19, v145
	v_max_f32_e32 v37, v37, v38
	v_exp_f32_e32 v19, v19
	v_sub_f32_e32 v38, v48, v145
	v_sub_f32_e32 v36, v176, v145
	v_exp_f32_e32 v38, v38
	v_sub_f32_e32 v39, v49, v145
	v_exp_f32_e32 v88, v36
	v_exp_f32_e32 v39, v39
	v_sub_f32_e32 v48, v50, v145
	v_add_f32_e32 v36, v17, v16
	v_exp_f32_e32 v48, v48
	v_sub_f32_e32 v49, v51, v145
	v_add_f32_e32 v36, v18, v36
	v_exp_f32_e32 v49, v49
	v_add_f32_e32 v36, v19, v36
	v_add_f32_e32 v36, v38, v36
	v_add_f32_e32 v36, v39, v36
	v_add_f32_e32 v36, v48, v36
	v_max_f32_e32 v147, v150, v37
	v_add_f32_e32 v146, v49, v36
	v_sub_f32_e32 v36, v150, v147
	v_cvt_pk_bf16_f32 v16, v16, v17
	v_cvt_pk_bf16_f32 v17, v18, v19
	v_cvt_pk_bf16_f32 v19, v48, v49
	v_exp_f32_e32 v48, v36
	v_sub_f32_e32 v36, v68, v147
	v_cvt_pk_bf16_f32 v18, v38, v39
	v_exp_f32_e32 v36, v36
	v_sub_f32_e32 v38, v69, v147
	v_exp_f32_e32 v38, v38
	v_sub_f32_e32 v39, v70, v147
	v_exp_f32_e32 v39, v39
	v_sub_f32_e32 v49, v71, v147
	v_exp_f32_e32 v49, v49
	v_sub_f32_e32 v24, v24, v147
	v_exp_f32_e32 v24, v24
	v_sub_f32_e32 v25, v25, v147
	v_exp_f32_e32 v25, v25
	v_add_f32_e32 v37, v38, v36
	v_add_f32_e32 v37, v39, v37
	v_add_f32_e32 v37, v49, v37
	v_cndmask_b32_e64 v50, v24, 0, s[46:47]
	v_add_f32_e32 v24, v50, v37
	v_cndmask_b32_e64 v37, v25, 0, s[48:49]
	v_sub_f32_e32 v25, v26, v147
	v_exp_f32_e32 v25, v25
	v_add_f32_e32 v24, v37, v24
	v_cvt_pk_bf16_f32 v26, v50, v37
	v_cmp_lt_i32_e32 vcc, -1, v184
	v_cndmask_b32_e64 v51, v25, 0, s[50:51]
	v_sub_f32_e32 v25, v27, v147
	v_exp_f32_e32 v25, v25
	v_add_f32_e32 v24, v51, v24
	v_fmac_f32_e32 v146, v149, v88
	s_add_i32 s0, s76, 0xffffff00
	v_cndmask_b32_e64 v27, v25, 0, s[52:53]
	v_add_f32_e32 v183, v27, v24
	v_cvt_pk_bf16_f32 v24, v36, v38
	v_cvt_pk_bf16_f32 v25, v39, v49
	v_cvt_pk_bf16_f32 v27, v51, v27
	v_pk_mul_f32 v[38:39], v[42:43], v[88:89] op_sel_hi:[1,0]
	v_pk_mul_f32 v[36:37], v[40:41], v[88:89] op_sel_hi:[1,0]
	v_pk_mul_f32 v[42:43], v[94:95], v[48:49] op_sel_hi:[1,0]
	v_pk_mul_f32 v[40:41], v[92:93], v[48:49] op_sel_hi:[1,0]
	s_waitcnt lgkmcnt(10)
	v_mfma_f32_16x16x32_bf16 v[36:39], v[140:143], v[16:19], v[36:39]
	v_fmac_f32_e32 v183, v151, v48
	s_min_i32 s1, s0, 0
	s_sub_i32 s1, 3, s1
	v_mfma_f32_16x16x32_bf16 v[68:71], v[140:143], v[24:27], v[40:43]
	s_ashr_i32 s1, s1, 2
	s_sub_i32 s22, 0x200, s76
	s_sub_i32 s0, s75, s0
	v_pk_mul_f32 v[42:43], v[106:107], v[88:89] op_sel_hi:[1,0]
	v_pk_mul_f32 v[40:41], v[104:105], v[88:89] op_sel_hi:[1,0]
	s_ashr_i32 s0, s0, 2
	s_cmp_lt_i32 s76, 0
	s_waitcnt lgkmcnt(8)
	v_mfma_f32_16x16x32_bf16 v[72:75], v[136:139], v[16:19], v[40:43]
	s_nop 2
	v_mul_f32_e64 v42, v110, v48
	v_mul_f32_e64 v43, v111, v48
	v_pk_mul_f32 v[40:41], v[108:109], v[48:49] op_sel_hi:[1,0]
	s_nop 1
	v_mfma_f32_16x16x32_bf16 v[104:107], v[136:139], v[24:27], v[40:43]
	s_nop 2
	v_mul_f32_e64 v42, v114, v88
	v_mul_f32_e64 v43, v115, v88
	v_pk_mul_f32 v[40:41], v[112:113], v[88:89] op_sel_hi:[1,0]
	s_waitcnt lgkmcnt(6)
	s_nop 0
	v_mfma_f32_16x16x32_bf16 v[108:111], v[132:135], v[16:19], v[40:43]
	s_nop 2
	v_mul_f32_e64 v42, v118, v48
	v_mul_f32_e64 v43, v119, v48
	v_pk_mul_f32 v[40:41], v[116:117], v[48:49] op_sel_hi:[1,0]
	s_nop 1
	v_mfma_f32_16x16x32_bf16 v[112:115], v[132:135], v[24:27], v[40:43]
	s_nop 2
	v_mul_f32_e64 v42, v122, v88
	v_mul_f32_e64 v43, v123, v88
	v_pk_mul_f32 v[40:41], v[120:121], v[88:89] op_sel_hi:[1,0]
	s_waitcnt lgkmcnt(4)
	s_nop 0
	v_mfma_f32_16x16x32_bf16 v[116:119], v[128:131], v[16:19], v[40:43]
	v_mul_f32_e64 v18, v126, v48
	v_mul_f32_e64 v19, v127, v48
	v_pk_mul_f32 v[16:17], v[124:125], v[48:49] op_sel_hi:[1,0]
	s_nop 1
	v_mfma_f32_16x16x32_bf16 v[128:131], v[128:131], v[24:27], v[16:19]
	s_nop 2
	v_min_i32_e32 v16, s75, v184
	v_cndmask_b32_e32 v16, 0, v16, vcc
	v_lshl_add_u32 v16, v16, 9, v152
	global_load_dwordx4 v[88:91], v16, s[98:99]
	v_med3_i32 v16, v185, 0, s75
	v_lshl_add_u32 v16, v16, 9, v152
	global_load_dwordx4 v[92:95], v16, s[98:99]
	v_med3_i32 v16, v186, 0, s75
	v_lshl_add_u32 v16, v16, 9, v152
	global_load_dwordx4 v[120:123], v16, s[98:99]
	v_med3_i32 v16, v188, 0, s75
	v_lshl_add_u32 v16, v16, 9, v152
	global_load_dwordx4 v[124:127], v16, s[98:99]
	v_add_u32_e32 v16, s76, v209
	v_med3_i32 v16, v16, 0, s75
	v_lshl_add_u32 v16, v16, 9, v158
	global_load_dwordx4 v[48:51], v16, s[100:101]
	global_load_dwordx4 v[40:43], v16, s[100:101] offset:64
	v_or_b32_e32 v16, 64, v209
	v_add_u32_e32 v16, s76, v16
	v_med3_i32 v16, v16, 0, s75
	v_lshl_add_u32 v16, v16, 9, v158
	global_load_dwordx4 v[24:27], v16, s[100:101]
	s_nop 0
	global_load_dwordx4 v[16:19], v16, s[100:101] offset:64
	ds_read_b64_tr_b16 v[98:99], v169 offset:2304
	ds_read_b64_tr_b16 v[96:97], v169
	ds_read_b64_tr_b16 v[140:141], v169 offset:32
	ds_read_b64_tr_b16 v[142:143], v169 offset:2336
	ds_read_b64_tr_b16 v[136:137], v169 offset:64
	ds_read_b64_tr_b16 v[138:139], v169 offset:2368
	ds_read_b64_tr_b16 v[132:133], v169 offset:96
	ds_read_b64_tr_b16 v[134:135], v169 offset:2400
	s_waitcnt vmcnt(15)
	ds_write_b128 v241, v[32:35] offset:4608
	s_waitcnt vmcnt(14)
	ds_write_b128 v242, v[64:67] offset:4608
	s_waitcnt vmcnt(13)
	ds_write_b128 v243, v[76:79] offset:4608
	s_waitcnt vmcnt(12)
	ds_write_b128 v244, v[100:103] offset:4608
	v_mfma_f32_16x16x32_bf16 v[64:67], v[60:63], v[4:7], 0
	v_mfma_f32_16x16x32_bf16 v[60:63], v[60:63], v[12:15], 0
	v_mfma_f32_16x16x32_bf16 v[32:35], v[84:87], v[4:7], 0
	v_mfma_f32_16x16x32_bf16 v[64:67], v[56:59], v[8:11], v[64:67]
	v_mfma_f32_16x16x32_bf16 v[56:59], v[56:59], v[0:3], v[60:63]
	s_nop 4
	v_ashrrev_i32_e32 v60, 2, v250
	v_max_i32_e32 v176, s1, v60
	v_add_u32_e32 v60, s22, v251
	v_ashrrev_i32_e32 v60, 2, v60
	v_min3_i32 v60, v60, s0, v247
	v_mfma_f32_16x16x32_bf16 v[32:35], v[80:83], v[8:11], v[32:35]
	v_sub_u32_e32 v175, v60, v176
	v_ashrrev_i32_e32 v60, 2, v249
	v_max_i32_e32 v181, s1, v60
	v_add_u32_e32 v60, s22, v144
	v_sub_u32_e32 v61, v154, v176
	v_ashrrev_i32_e32 v60, 2, v60
	v_mfma_f32_16x16x32_bf16 v[76:79], v[84:87], v[12:15], 0
	v_min3_i32 v60, v60, s0, v247
	v_add_u32_e32 v63, 1, v61
	v_sub_u32_e32 v252, v60, v181
	v_cmp_gt_u32_e64 s[0:1], v63, v175
	v_cmp_gt_u32_e32 vcc, v61, v175
	s_nop 0
	v_cndmask_b32_e64 v33, v33, v246, s[0:1]
	s_nop 0
	v_cndmask_b32_e32 v32, v32, v246, vcc
	v_mfma_f32_16x16x32_bf16 v[76:79], v[80:83], v[0:3], v[76:79]
	v_max_f32_e32 v60, v32, v33
	v_add_u32_e32 v63, 2, v61
	v_add_u32_e32 v80, 3, v61
	v_cmp_gt_u32_e64 s[22:23], v63, v175
	v_cmp_gt_u32_e64 s[24:25], v80, v175
	v_sub_u32_e32 v62, v154, v181
	v_cndmask_b32_e64 v34, v34, v246, s[22:23]
	v_cndmask_b32_e64 v35, v35, v246, s[24:25]
	v_max3_f32 v60, v60, v34, v35
	v_add_u32_e32 v63, 16, v61
	v_add_u32_e32 v80, 17, v61
	v_cmp_gt_u32_e64 s[26:27], v63, v175
	v_cmp_gt_u32_e64 s[28:29], v80, v175
	v_cmp_gt_u32_e64 s[38:39], v62, v252
	v_cndmask_b32_e64 v64, v64, v246, s[26:27]
	v_cndmask_b32_e64 v65, v65, v246, s[28:29]
	v_max3_f32 v60, v60, v64, v65
	v_add_u32_e32 v63, 18, v61
	v_add_u32_e32 v61, 19, v61
	v_cmp_gt_u32_e64 s[30:31], v63, v175
	v_cmp_gt_u32_e64 s[34:35], v61, v175
	v_add_u32_e32 v80, 3, v62
	v_cndmask_b32_e64 v66, v66, v246, s[30:31]
	v_cndmask_b32_e64 v67, v67, v246, s[34:35]
	v_max3_f32 v60, v60, v66, v67
	v_add_u32_e32 v63, 1, v62
	v_cmp_gt_u32_e64 s[40:41], v63, v252
	v_cndmask_b32_e64 v76, v76, v246, s[38:39]
	s_nop 0
	v_cndmask_b32_e64 v77, v77, v246, s[40:41]
	v_max_f32_e32 v61, v76, v77
	v_add_u32_e32 v63, 2, v62
	v_cmp_gt_u32_e64 s[42:43], v63, v252
	v_cmp_gt_u32_e64 s[44:45], v80, v252
	s_nop 0
	v_cndmask_b32_e64 v78, v78, v246, s[42:43]
	v_cndmask_b32_e64 v79, v79, v246, s[44:45]
	v_max3_f32 v61, v61, v78, v79
	v_add_u32_e32 v63, 16, v62
	v_add_u32_e32 v80, 17, v62
	v_cmp_gt_u32_e64 s[46:47], v63, v252
	v_cmp_gt_u32_e64 s[48:49], v80, v252
	s_nop 0
	v_cndmask_b32_e64 v56, v56, v246, s[46:47]
	v_cndmask_b32_e64 v57, v57, v246, s[48:49]
	v_max3_f32 v61, v61, v56, v57
	v_add_u32_e32 v63, 18, v62
	v_add_u32_e32 v62, 19, v62
	v_cmp_gt_u32_e64 s[50:51], v63, v252
	v_cmp_gt_u32_e64 s[52:53], v62, v252
	s_nop 0
	v_cndmask_b32_e64 v58, v58, v246, s[50:51]
	v_cndmask_b32_e64 v59, v59, v246, s[52:53]
	v_max3_f32 v61, v61, v58, v59
	v_mov_b32_e32 v62, v60
	s_nop 1
	v_permlane32_swap_b32_e32 v62, v60
	v_max_f32_e32 v60, v60, v62
	v_mov_b32_e32 v62, v61
	s_nop 1
	v_permlane32_swap_b32_e32 v62, v61
	v_max_f32_e32 v61, v61, v62
	v_mov_b32_e32 v62, v60
	s_nop 1
	v_permlane16_swap_b32_e32 v62, v60
	v_max3_f32 v148, v145, v60, v62
	v_sub_f32_e32 v32, v32, v148
	v_exp_f32_e32 v32, v32
	v_sub_f32_e32 v33, v33, v148
	v_exp_f32_e32 v33, v33
	v_sub_f32_e32 v34, v34, v148
	v_mov_b32_e32 v62, v61
	v_exp_f32_e32 v34, v34
	v_sub_f32_e32 v35, v35, v148
	v_permlane16_swap_b32_e32 v62, v61
	v_exp_f32_e32 v35, v35
	v_sub_f32_e32 v63, v64, v148
	v_exp_f32_e32 v63, v63
	v_sub_f32_e32 v64, v65, v148
	v_max_f32_e32 v61, v61, v62
	v_exp_f32_e32 v64, v64
	v_sub_f32_e32 v65, v66, v148
	v_add_f32_e32 v62, v33, v32
	v_exp_f32_e32 v65, v65
	v_sub_f32_e32 v66, v67, v148
	v_add_f32_e32 v62, v34, v62
	v_exp_f32_e32 v66, v66
	v_add_f32_e32 v62, v35, v62
	v_add_f32_e32 v62, v63, v62
	v_add_f32_e32 v62, v64, v62
	v_max_f32_e32 v150, v147, v61
	v_add_f32_e32 v62, v65, v62
	v_sub_f32_e32 v61, v147, v150
	v_add_f32_e32 v149, v66, v62
	v_exp_f32_e32 v62, v61
	v_sub_f32_e32 v61, v76, v150
	v_cvt_pk_bf16_f32 v32, v32, v33
	v_cvt_pk_bf16_f32 v33, v34, v35
	v_cvt_pk_bf16_f32 v34, v63, v64
	v_exp_f32_e32 v61, v61
	v_sub_f32_e32 v64, v77, v150
	v_cvt_pk_bf16_f32 v35, v65, v66
	v_exp_f32_e32 v64, v64
	v_sub_f32_e32 v65, v78, v150
	v_exp_f32_e32 v65, v65
	v_sub_f32_e32 v66, v79, v150
	v_exp_f32_e32 v66, v66
	v_sub_f32_e32 v56, v56, v150
	v_exp_f32_e32 v56, v56
	v_sub_f32_e32 v57, v57, v150
	v_exp_f32_e32 v57, v57
	v_add_f32_e32 v63, v64, v61
	v_add_f32_e32 v63, v65, v63
	v_add_f32_e32 v63, v66, v63
	v_cndmask_b32_e64 v67, v56, 0, s[46:47]
	v_add_f32_e32 v56, v67, v63
	v_cndmask_b32_e64 v63, v57, 0, s[48:49]
	v_sub_f32_e32 v57, v58, v150
	v_exp_f32_e32 v57, v57
	v_sub_f32_e32 v60, v145, v148
	v_exp_f32_e32 v60, v60
	v_add_f32_e32 v56, v63, v56
	v_cndmask_b32_e64 v76, v57, 0, s[50:51]
	v_sub_f32_e32 v57, v59, v150
	v_exp_f32_e32 v57, v57
	v_add_f32_e32 v56, v76, v56
	v_pk_mul_f32 v[38:39], v[38:39], v[60:61] op_sel_hi:[1,0]
	v_pk_mul_f32 v[36:37], v[36:37], v[60:61] op_sel_hi:[1,0]
	v_cndmask_b32_e64 v59, v57, 0, s[52:53]
	v_add_f32_e32 v151, v59, v56
	v_cvt_pk_bf16_f32 v56, v61, v64
	v_cvt_pk_bf16_f32 v57, v65, v66
	v_cvt_pk_bf16_f32 v58, v67, v63
	v_cvt_pk_bf16_f32 v59, v76, v59
	s_waitcnt lgkmcnt(10)
	v_mfma_f32_16x16x32_bf16 v[80:83], v[96:99], v[32:35], v[36:39]
	v_fmac_f32_e32 v149, v146, v60
	v_fmac_f32_e32 v151, v183, v62
	s_nop 0
	v_pk_mul_f32 v[38:39], v[70:71], v[62:63] op_sel_hi:[1,0]
	v_pk_mul_f32 v[36:37], v[68:69], v[62:63] op_sel_hi:[1,0]
	s_nop 1
	v_mfma_f32_16x16x32_bf16 v[84:87], v[96:99], v[56:59], v[36:39]
	s_nop 2
	v_mul_f32_e64 v38, v74, v60
	v_mul_f32_e64 v39, v75, v60
	v_pk_mul_f32 v[36:37], v[72:73], v[60:61] op_sel_hi:[1,0]
	s_waitcnt lgkmcnt(8)
	s_nop 0
	v_mfma_f32_16x16x32_bf16 v[96:99], v[140:143], v[32:35], v[36:39]
	s_nop 2
	v_mul_f32_e64 v38, v106, v62
	v_mul_f32_e64 v39, v107, v62
	v_pk_mul_f32 v[36:37], v[104:105], v[62:63] op_sel_hi:[1,0]
	s_nop 1
	v_mfma_f32_16x16x32_bf16 v[100:103], v[140:143], v[56:59], v[36:39]
	s_nop 2
	v_mul_f32_e64 v38, v110, v60
	v_mul_f32_e64 v39, v111, v60
	v_pk_mul_f32 v[36:37], v[108:109], v[60:61] op_sel_hi:[1,0]
	s_waitcnt lgkmcnt(6)
	s_nop 0
	v_mfma_f32_16x16x32_bf16 v[104:107], v[136:139], v[32:35], v[36:39]
	s_nop 2
	v_mul_f32_e64 v38, v114, v62
	v_mul_f32_e64 v39, v115, v62
	v_pk_mul_f32 v[36:37], v[112:113], v[62:63] op_sel_hi:[1,0]
	s_nop 1
	v_mfma_f32_16x16x32_bf16 v[108:111], v[136:139], v[56:59], v[36:39]
	s_nop 2
	v_mul_f32_e64 v38, v118, v60
	v_mul_f32_e64 v39, v119, v60
	v_pk_mul_f32 v[36:37], v[116:117], v[60:61] op_sel_hi:[1,0]
	s_waitcnt lgkmcnt(4)
	s_nop 0
	v_mfma_f32_16x16x32_bf16 v[112:115], v[132:135], v[32:35], v[36:39]
	v_mul_f32_e64 v34, v130, v62
	v_mul_f32_e64 v35, v131, v62
	v_pk_mul_f32 v[32:33], v[128:129], v[62:63] op_sel_hi:[1,0]
	s_nop 1
	v_mfma_f32_16x16x32_bf16 v[116:119], v[132:135], v[56:59], v[32:35]
	s_nop 2
	v_add_u32_e32 v32, 0x80, v184
	v_med3_i32 v32, v32, 0, s75
	v_lshl_add_u32 v32, v32, 9, v152
	global_load_dwordx4 v[64:67], v32, s[98:99]
	v_add_u32_e32 v32, 0x80, v185
	v_med3_i32 v32, v32, 0, s75
	v_lshl_add_u32 v32, v32, 9, v152
	global_load_dwordx4 v[68:71], v32, s[98:99]
	v_add_u32_e32 v32, 0x80, v186
	v_med3_i32 v32, v32, 0, s75
	v_lshl_add_u32 v32, v32, 9, v152
	global_load_dwordx4 v[72:75], v32, s[98:99]
	v_add_u32_e32 v32, 0x80, v188
	v_med3_i32 v32, v32, 0, s75
	v_lshl_add_u32 v32, v32, 9, v152
	global_load_dwordx4 v[76:79], v32, s[98:99]
	v_or_b32_e32 v32, 0x80, v209
	v_add_u32_e32 v32, s76, v32
	v_med3_i32 v32, v32, 0, s75
	v_lshl_add_u32 v32, v32, 9, v158
	global_load_dwordx4 v[60:63], v32, s[100:101]
	global_load_dwordx4 v[56:59], v32, s[100:101] offset:64
	v_or_b32_e32 v32, 0xc0, v209
	v_add_u32_e32 v32, s76, v32
	v_med3_i32 v32, v32, 0, s75
	v_lshl_add_u32 v32, v32, 9, v158
	global_load_dwordx4 v[36:39], v32, s[100:101]
	s_nop 0
	global_load_dwordx4 v[32:35], v32, s[100:101] offset:64
	ds_read_b64_tr_b16 v[134:135], v169 offset:6912
	ds_read_b64_tr_b16 v[132:133], v169 offset:4608
	ds_read_b64_tr_b16 v[128:129], v169 offset:4640
	ds_read_b64_tr_b16 v[130:131], v169 offset:6944
	ds_read_b64_tr_b16 v[136:137], v169 offset:4672
	ds_read_b64_tr_b16 v[138:139], v169 offset:6976
	ds_read_b64_tr_b16 v[144:145], v169 offset:4704
	ds_read_b64_tr_b16 v[146:147], v169 offset:7008
	s_waitcnt vmcnt(15)
	ds_write_b128 v241, v[88:91]
	s_waitcnt vmcnt(14)
	ds_write_b128 v242, v[92:95]
	s_waitcnt vmcnt(13)
	ds_write_b128 v243, v[120:123]
	s_waitcnt vmcnt(12)
	ds_write_b128 v244, v[124:127]
	v_mfma_f32_16x16x32_bf16 v[88:91], v[52:55], v[4:7], 0
	v_mfma_f32_16x16x32_bf16 v[92:95], v[28:31], v[4:7], 0
	v_mfma_f32_16x16x32_bf16 v[28:31], v[28:31], v[12:15], 0
	v_mfma_f32_16x16x32_bf16 v[88:91], v[44:47], v[8:11], v[88:91]
	v_mfma_f32_16x16x32_bf16 v[92:95], v[20:23], v[8:11], v[92:95]
	v_mfma_f32_16x16x32_bf16 v[20:23], v[20:23], v[0:3], v[28:31]
	s_nop 4
	v_sub_u32_e32 v28, v187, v176
	v_mfma_f32_16x16x32_bf16 v[52:55], v[52:55], v[12:15], 0
	v_add_u32_e32 v31, 1, v28
	v_cmp_gt_u32_e64 s[0:1], v31, v175
	v_cmp_gt_u32_e32 vcc, v28, v175
	s_nop 0
	v_cndmask_b32_e64 v89, v89, v246, s[0:1]
	s_nop 0
	v_cndmask_b32_e32 v88, v88, v246, vcc
	v_mfma_f32_16x16x32_bf16 v[44:47], v[44:47], v[0:3], v[52:55]
	v_max_f32_e32 v30, v88, v89
	v_add_u32_e32 v31, 2, v28
	v_cmp_gt_u32_e64 s[22:23], v31, v175
	v_add_u32_e32 v52, 3, v28
	v_cmp_gt_u32_e64 s[24:25], v52, v175
	v_cndmask_b32_e64 v90, v90, v246, s[22:23]
	v_sub_u32_e32 v29, v187, v181
	v_cndmask_b32_e64 v91, v91, v246, s[24:25]
	v_max3_f32 v30, v30, v90, v91
	v_add_u32_e32 v31, 16, v28
	v_add_u32_e32 v52, 17, v28
	v_cmp_gt_u32_e64 s[26:27], v31, v175
	v_cmp_gt_u32_e64 s[28:29], v52, v175
	v_cmp_gt_u32_e64 s[38:39], v29, v252
	v_cndmask_b32_e64 v92, v92, v246, s[26:27]
	v_cndmask_b32_e64 v93, v93, v246, s[28:29]
	v_max3_f32 v30, v30, v92, v93
	v_add_u32_e32 v31, 18, v28
	v_add_u32_e32 v28, 19, v28
	v_cmp_gt_u32_e64 s[30:31], v31, v175
	v_cmp_gt_u32_e64 s[34:35], v28, v175
	v_add_u32_e32 v52, 3, v29
	v_cndmask_b32_e64 v94, v94, v246, s[30:31]
	v_cndmask_b32_e64 v95, v95, v246, s[34:35]
	v_max3_f32 v28, v30, v94, v95
	v_add_u32_e32 v31, 1, v29
	v_cmp_gt_u32_e64 s[40:41], v31, v252
	v_cndmask_b32_e64 v44, v44, v246, s[38:39]
	s_nop 0
	v_cndmask_b32_e64 v45, v45, v246, s[40:41]
	v_max_f32_e32 v30, v44, v45
	v_add_u32_e32 v31, 2, v29
	v_cmp_gt_u32_e64 s[42:43], v31, v252
	v_cmp_gt_u32_e64 s[44:45], v52, v252
	s_nop 0
	v_cndmask_b32_e64 v46, v46, v246, s[42:43]
	v_cndmask_b32_e64 v47, v47, v246, s[44:45]
	v_max3_f32 v30, v30, v46, v47
	v_add_u32_e32 v31, 16, v29
	v_add_u32_e32 v52, 17, v29
	v_cmp_gt_u32_e64 s[46:47], v31, v252
	v_cmp_gt_u32_e64 s[48:49], v52, v252
	s_nop 0
	v_cndmask_b32_e64 v20, v20, v246, s[46:47]
	v_cndmask_b32_e64 v21, v21, v246, s[48:49]
	v_max3_f32 v30, v30, v20, v21
	v_add_u32_e32 v31, 18, v29
	v_add_u32_e32 v29, 19, v29
	v_cmp_gt_u32_e64 s[50:51], v31, v252
	v_cmp_gt_u32_e64 s[52:53], v29, v252
	s_nop 0
	v_cndmask_b32_e64 v22, v22, v246, s[50:51]
	v_cndmask_b32_e64 v23, v23, v246, s[52:53]
	v_max3_f32 v29, v30, v22, v23
	v_mov_b32_e32 v30, v28
	s_nop 1
	v_permlane32_swap_b32_e32 v30, v28
	v_max_f32_e32 v28, v28, v30
	v_mov_b32_e32 v30, v29
	s_nop 1
	v_permlane32_swap_b32_e32 v30, v29
	v_max_f32_e32 v29, v29, v30
	v_mov_b32_e32 v30, v28
	s_nop 1
	v_permlane16_swap_b32_e32 v30, v28
	v_max_f32_e32 v28, v28, v30
	v_mov_b32_e32 v30, v29
	v_max_f32_e32 v183, v148, v28
	s_nop 0
	v_permlane16_swap_b32_e32 v30, v29
	v_sub_f32_e32 v28, v148, v183
	v_exp_f32_e32 v52, v28
	v_sub_f32_e32 v28, v88, v183
	v_max_f32_e32 v54, v29, v30
	v_exp_f32_e32 v28, v28
	v_sub_f32_e32 v30, v89, v183
	v_exp_f32_e32 v30, v30
	v_sub_f32_e32 v31, v90, v183
	v_exp_f32_e32 v31, v31
	v_sub_f32_e32 v55, v91, v183
	v_max_f32_e32 v185, v150, v54
	v_exp_f32_e32 v55, v55
	v_sub_f32_e32 v88, v92, v183
	v_sub_f32_e32 v44, v44, v185
	v_exp_f32_e32 v88, v88
	v_sub_f32_e32 v89, v93, v183
	v_exp_f32_e32 v44, v44
	v_sub_f32_e32 v45, v45, v185
	v_exp_f32_e32 v89, v89
	v_sub_f32_e32 v90, v94, v183
	v_exp_f32_e32 v45, v45
	v_sub_f32_e32 v46, v46, v185
	v_add_f32_e32 v29, v30, v28
	v_exp_f32_e32 v90, v90
	v_sub_f32_e32 v91, v95, v183
	v_exp_f32_e32 v46, v46
	v_sub_f32_e32 v47, v47, v185
	v_add_f32_e32 v29, v31, v29
	v_exp_f32_e32 v91, v91
	v_exp_f32_e32 v47, v47
	v_sub_f32_e32 v20, v20, v185
	v_add_f32_e32 v29, v55, v29
	v_sub_f32_e32 v53, v150, v185
	v_exp_f32_e32 v20, v20
	v_sub_f32_e32 v21, v21, v185
	v_add_f32_e32 v29, v88, v29
	v_exp_f32_e32 v54, v53
	v_exp_f32_e32 v21, v21
	v_add_f32_e32 v29, v89, v29
	v_add_f32_e32 v53, v45, v44
	v_add_f32_e32 v29, v90, v29
	v_add_f32_e32 v53, v46, v53
	v_add_f32_e32 v184, v91, v29
	v_cvt_pk_bf16_f32 v29, v31, v55
	v_add_f32_e32 v53, v47, v53
	v_cndmask_b32_e64 v55, v20, 0, s[46:47]
	v_add_f32_e32 v20, v55, v53
	v_cndmask_b32_e64 v53, v21, 0, s[48:49]
	v_sub_f32_e32 v21, v22, v185
	v_exp_f32_e32 v21, v21
	v_cvt_pk_bf16_f32 v28, v28, v30
	v_cvt_pk_bf16_f32 v30, v88, v89
	v_add_f32_e32 v20, v53, v20
	v_cndmask_b32_e64 v88, v21, 0, s[50:51]
	v_sub_f32_e32 v21, v23, v185
	v_exp_f32_e32 v21, v21
	v_add_f32_e32 v20, v88, v20
	v_cvt_pk_bf16_f32 v31, v90, v91
	v_cvt_pk_bf16_f32 v22, v55, v53
	v_cndmask_b32_e64 v23, v21, 0, s[52:53]
	v_add_f32_e32 v186, v23, v20
	v_cvt_pk_bf16_f32 v20, v44, v45
	v_cvt_pk_bf16_f32 v21, v46, v47
	v_pk_mul_f32 v[46:47], v[82:83], v[52:53] op_sel_hi:[1,0]
	v_pk_mul_f32 v[44:45], v[80:81], v[52:53] op_sel_hi:[1,0]
	v_cvt_pk_bf16_f32 v23, v88, v23
	v_fmac_f32_e32 v184, v149, v52
	s_waitcnt lgkmcnt(10)
	v_mfma_f32_16x16x32_bf16 v[120:123], v[132:135], v[28:31], v[44:47]
	v_fmac_f32_e32 v186, v151, v54
	s_nop 1
	v_pk_mul_f32 v[46:47], v[86:87], v[54:55] op_sel_hi:[1,0]
	v_pk_mul_f32 v[44:45], v[84:85], v[54:55] op_sel_hi:[1,0]
	s_nop 1
	v_mfma_f32_16x16x32_bf16 v[124:127], v[132:135], v[20:23], v[44:47]
	s_nop 2
	v_mul_f32_e64 v46, v98, v52
	v_mul_f32_e64 v47, v99, v52
	v_pk_mul_f32 v[44:45], v[96:97], v[52:53] op_sel_hi:[1,0]
	s_waitcnt lgkmcnt(8)
	s_nop 0
	v_mfma_f32_16x16x32_bf16 v[96:99], v[128:131], v[28:31], v[44:47]
	s_nop 2
	v_mul_f32_e64 v46, v102, v54
	v_mul_f32_e64 v47, v103, v54
	v_pk_mul_f32 v[44:45], v[100:101], v[54:55] op_sel_hi:[1,0]
	s_nop 1
	v_mfma_f32_16x16x32_bf16 v[128:131], v[128:131], v[20:23], v[44:47]
	s_nop 2
	v_mul_f32_e64 v46, v106, v52
	v_mul_f32_e64 v47, v107, v52
	v_pk_mul_f32 v[44:45], v[104:105], v[52:53] op_sel_hi:[1,0]
	s_waitcnt lgkmcnt(6)
	s_nop 0
	v_mfma_f32_16x16x32_bf16 v[132:135], v[136:139], v[28:31], v[44:47]
	s_nop 2
	v_mul_f32_e64 v46, v110, v54
	v_mul_f32_e64 v47, v111, v54
	v_pk_mul_f32 v[44:45], v[108:109], v[54:55] op_sel_hi:[1,0]
	s_nop 1
	v_mfma_f32_16x16x32_bf16 v[136:139], v[136:139], v[20:23], v[44:47]
	s_nop 2
	v_mul_f32_e64 v46, v114, v52
	v_mul_f32_e64 v47, v115, v52
	v_pk_mul_f32 v[44:45], v[112:113], v[52:53] op_sel_hi:[1,0]
	s_waitcnt lgkmcnt(4)
	s_nop 0
	v_mfma_f32_16x16x32_bf16 v[140:143], v[144:147], v[28:31], v[44:47]
	v_mul_f32_e64 v30, v118, v54
	v_mul_f32_e64 v31, v119, v54
	v_pk_mul_f32 v[28:29], v[116:117], v[54:55] op_sel_hi:[1,0]
	s_nop 1
	v_mfma_f32_16x16x32_bf16 v[144:147], v[144:147], v[20:23], v[28:31]
	v_lshl_add_u32 v20, v155, 1, v155
	v_add_u32_e32 v20, v180, v20
	v_med3_i32 v20, v20, 0, s75
	v_lshl_add_u32 v20, v20, 9, v152
	global_load_dwordx4 v[80:83], v20, s[98:99]
	v_lshl_add_u32 v20, v172, 1, v172
	v_add_u32_e32 v20, v179, v20
	v_med3_i32 v20, v20, 0, s75
	v_lshl_add_u32 v20, v20, 9, v152
	global_load_dwordx4 v[84:87], v20, s[98:99]
	v_lshl_add_u32 v20, v173, 1, v173
	v_add_u32_e32 v20, v178, v20
	v_med3_i32 v20, v20, 0, s75
	v_lshl_add_u32 v20, v20, 9, v152
	global_load_dwordx4 v[88:91], v20, s[98:99]
	v_lshl_add_u32 v20, v182, 1, v182
	v_add_u32_e32 v20, v177, v20
	v_med3_i32 v20, v20, 0, s75
	v_lshl_add_u32 v20, v20, 9, v152
	global_load_dwordx4 v[92:95], v20, s[98:99]
	v_or_b32_e32 v20, 0x100, v209
	v_add_u32_e32 v20, s76, v20
	v_med3_i32 v20, v20, 0, s75
	v_lshl_add_u32 v20, v20, 9, v158
	global_load_dwordx4 v[52:55], v20, s[100:101]
	global_load_dwordx4 v[44:47], v20, s[100:101] offset:64
	v_or_b32_e32 v20, 0x140, v209
	v_add_u32_e32 v20, s76, v20
	v_med3_i32 v20, v20, 0, s75
	v_lshl_add_u32 v20, v20, 9, v158
	global_load_dwordx4 v[28:31], v20, s[100:101]
	s_nop 0
	global_load_dwordx4 v[20:23], v20, s[100:101] offset:64
	ds_read_b64_tr_b16 v[102:103], v169 offset:2304
	ds_read_b64_tr_b16 v[100:101], v169
	ds_read_b64_tr_b16 v[108:109], v169 offset:32
	ds_read_b64_tr_b16 v[110:111], v169 offset:2336
	ds_read_b64_tr_b16 v[116:117], v169 offset:64
	ds_read_b64_tr_b16 v[118:119], v169 offset:2368
	ds_read_b64_tr_b16 v[148:149], v169 offset:96
	ds_read_b64_tr_b16 v[150:151], v169 offset:2400
	s_waitcnt vmcnt(15)
	ds_write_b128 v241, v[64:67] offset:4608
	s_waitcnt vmcnt(14)
	ds_write_b128 v242, v[68:71] offset:4608
	s_waitcnt vmcnt(13)
	ds_write_b128 v243, v[72:75] offset:4608
	s_waitcnt vmcnt(12)
	ds_write_b128 v244, v[76:79] offset:4608
	v_mfma_f32_16x16x32_bf16 v[64:67], v[48:51], v[4:7], 0
	v_mfma_f32_16x16x32_bf16 v[68:71], v[24:27], v[4:7], 0
	v_mfma_f32_16x16x32_bf16 v[24:27], v[24:27], v[12:15], 0
	v_mfma_f32_16x16x32_bf16 v[64:67], v[40:43], v[8:11], v[64:67]
	v_mfma_f32_16x16x32_bf16 v[68:71], v[16:19], v[8:11], v[68:71]
	v_mfma_f32_16x16x32_bf16 v[16:19], v[16:19], v[0:3], v[24:27]
	s_nop 4
	v_sub_u32_e32 v24, v192, v176
	v_mfma_f32_16x16x32_bf16 v[48:51], v[48:51], v[12:15], 0
	v_add_u32_e32 v27, 1, v24
	v_cmp_gt_u32_e64 s[0:1], v27, v175
	v_cmp_gt_u32_e32 vcc, v24, v175
	s_nop 0
	v_cndmask_b32_e64 v65, v65, v246, s[0:1]
	s_nop 0
	v_cndmask_b32_e32 v64, v64, v246, vcc
	v_mfma_f32_16x16x32_bf16 v[40:43], v[40:43], v[0:3], v[48:51]
	v_max_f32_e32 v26, v64, v65
	v_add_u32_e32 v27, 2, v24
	v_cmp_gt_u32_e64 s[22:23], v27, v175
	v_add_u32_e32 v48, 3, v24
	v_cmp_gt_u32_e64 s[24:25], v48, v175
	v_cndmask_b32_e64 v66, v66, v246, s[22:23]
	v_sub_u32_e32 v25, v192, v181
	v_cndmask_b32_e64 v67, v67, v246, s[24:25]
	v_max3_f32 v26, v26, v66, v67
	v_add_u32_e32 v27, 16, v24
	v_add_u32_e32 v48, 17, v24
	v_cmp_gt_u32_e64 s[26:27], v27, v175
	v_cmp_gt_u32_e64 s[28:29], v48, v175
	v_cmp_gt_u32_e64 s[38:39], v25, v252
	v_cndmask_b32_e64 v68, v68, v246, s[26:27]
	v_cndmask_b32_e64 v69, v69, v246, s[28:29]
	v_max3_f32 v26, v26, v68, v69
	v_add_u32_e32 v27, 18, v24
	v_add_u32_e32 v24, 19, v24
	v_cmp_gt_u32_e64 s[30:31], v27, v175
	v_cmp_gt_u32_e64 s[34:35], v24, v175
	v_add_u32_e32 v48, 3, v25
	v_cndmask_b32_e64 v70, v70, v246, s[30:31]
	v_cndmask_b32_e64 v71, v71, v246, s[34:35]
	v_max3_f32 v24, v26, v70, v71
	v_add_u32_e32 v27, 1, v25
	v_cmp_gt_u32_e64 s[40:41], v27, v252
	v_cndmask_b32_e64 v40, v40, v246, s[38:39]
	s_nop 0
	v_cndmask_b32_e64 v41, v41, v246, s[40:41]
	v_max_f32_e32 v26, v40, v41
	v_add_u32_e32 v27, 2, v25
	v_cmp_gt_u32_e64 s[42:43], v27, v252
	v_cmp_gt_u32_e64 s[44:45], v48, v252
	s_nop 0
	v_cndmask_b32_e64 v42, v42, v246, s[42:43]
	v_cndmask_b32_e64 v43, v43, v246, s[44:45]
	v_max3_f32 v26, v26, v42, v43
	v_add_u32_e32 v27, 16, v25
	v_add_u32_e32 v48, 17, v25
	v_cmp_gt_u32_e64 s[46:47], v27, v252
	v_cmp_gt_u32_e64 s[48:49], v48, v252
	s_nop 0
	v_cndmask_b32_e64 v16, v16, v246, s[46:47]
	v_cndmask_b32_e64 v17, v17, v246, s[48:49]
	v_max3_f32 v26, v26, v16, v17
	v_add_u32_e32 v27, 18, v25
	v_add_u32_e32 v25, 19, v25
	v_cmp_gt_u32_e64 s[50:51], v27, v252
	v_cmp_gt_u32_e64 s[52:53], v25, v252
	s_nop 0
	v_cndmask_b32_e64 v18, v18, v246, s[50:51]
	v_cndmask_b32_e64 v19, v19, v246, s[52:53]
	v_max3_f32 v25, v26, v18, v19
	v_mov_b32_e32 v26, v24
	s_nop 1
	v_permlane32_swap_b32_e32 v26, v24
	v_max_f32_e32 v24, v24, v26
	v_mov_b32_e32 v26, v25
	s_nop 1
	v_permlane32_swap_b32_e32 v26, v25
	v_max_f32_e32 v25, v25, v26
	v_mov_b32_e32 v26, v24
	s_nop 1
	v_permlane16_swap_b32_e32 v26, v24
	v_max3_f32 v177, v183, v24, v26
	v_sub_f32_e32 v48, v66, v177
	v_exp_f32_e32 v48, v48
	v_sub_f32_e32 v24, v183, v177
	v_exp_f32_e32 v72, v24
	v_sub_f32_e32 v24, v64, v177
	v_cndmask_b32_e64 v49, v48, 0, s[22:23]
	v_sub_f32_e32 v48, v67, v177
	v_exp_f32_e32 v48, v48
	v_exp_f32_e32 v24, v24
	v_sub_f32_e32 v27, v65, v177
	v_exp_f32_e32 v27, v27
	v_cndmask_b32_e64 v50, v48, 0, s[24:25]
	v_sub_f32_e32 v48, v68, v177
	v_exp_f32_e32 v48, v48
	v_mov_b32_e32 v26, v25
	s_nop 1
	v_permlane16_swap_b32_e32 v26, v25
	v_cndmask_b32_e64 v51, v48, 0, s[26:27]
	v_sub_f32_e32 v48, v69, v177
	v_exp_f32_e32 v48, v48
	v_max_f32_e32 v25, v25, v26
	v_cndmask_b32_e64 v64, v48, 0, s[28:29]
	v_sub_f32_e32 v48, v70, v177
	v_exp_f32_e32 v48, v48
	v_add_f32_e32 v26, v27, v24
	v_cndmask_b32_e64 v65, v48, 0, s[30:31]
	v_sub_f32_e32 v48, v71, v177
	v_exp_f32_e32 v48, v48
	v_add_f32_e32 v26, v49, v26
	v_add_f32_e32 v26, v50, v26
	v_add_f32_e32 v26, v51, v26
	v_max_f32_e32 v179, v185, v25
	v_add_f32_e32 v26, v64, v26
	v_cndmask_b32_e64 v66, v48, 0, s[34:35]
	v_cvt_pk_bf16_f32 v48, v24, v27
	v_sub_f32_e32 v24, v185, v179
	v_add_f32_e32 v26, v65, v26
	v_cvt_pk_bf16_f32 v49, v49, v50
	v_cvt_pk_bf16_f32 v50, v51, v64
	v_exp_f32_e32 v64, v24
	v_sub_f32_e32 v24, v40, v179
	v_add_f32_e32 v178, v66, v26
	v_exp_f32_e32 v24, v24
	v_sub_f32_e32 v26, v41, v179
	v_exp_f32_e32 v26, v26
	v_sub_f32_e32 v27, v42, v179
	v_exp_f32_e32 v27, v27
	v_sub_f32_e32 v40, v43, v179
	v_exp_f32_e32 v40, v40
	v_sub_f32_e32 v16, v16, v179
	v_exp_f32_e32 v16, v16
	v_sub_f32_e32 v17, v17, v179
	v_exp_f32_e32 v17, v17
	v_add_f32_e32 v25, v26, v24
	v_add_f32_e32 v25, v27, v25
	v_add_f32_e32 v25, v40, v25
	v_cndmask_b32_e64 v41, v16, 0, s[46:47]
	v_add_f32_e32 v16, v41, v25
	v_cndmask_b32_e64 v25, v17, 0, s[48:49]
	v_sub_f32_e32 v17, v18, v179
	v_exp_f32_e32 v17, v17
	v_add_f32_e32 v16, v25, v16
	v_cvt_pk_bf16_f32 v51, v65, v66
	v_cvt_pk_bf16_f32 v18, v41, v25
	v_cndmask_b32_e64 v42, v17, 0, s[50:51]
	v_sub_f32_e32 v17, v19, v179
	v_exp_f32_e32 v17, v17
	v_add_f32_e32 v16, v42, v16
	v_fmac_f32_e32 v178, v184, v72
	v_cndmask_b32_e64 v19, v17, 0, s[52:53]
	v_add_f32_e32 v180, v19, v16
	v_cvt_pk_bf16_f32 v16, v24, v26
	v_cvt_pk_bf16_f32 v17, v27, v40
	v_cvt_pk_bf16_f32 v19, v42, v19
	v_pk_mul_f32 v[26:27], v[122:123], v[72:73] op_sel_hi:[1,0]
	v_pk_mul_f32 v[24:25], v[120:121], v[72:73] op_sel_hi:[1,0]
	v_pk_mul_f32 v[42:43], v[126:127], v[64:65] op_sel_hi:[1,0]
	v_pk_mul_f32 v[40:41], v[124:125], v[64:65] op_sel_hi:[1,0]
	s_waitcnt lgkmcnt(10)
	v_mfma_f32_16x16x32_bf16 v[24:27], v[100:103], v[48:51], v[24:27]
	v_fmac_f32_e32 v180, v186, v64
	v_mfma_f32_16x16x32_bf16 v[100:103], v[100:103], v[16:19], v[40:43]
	s_nop 2
	v_mul_f32_e64 v42, v98, v72
	v_mul_f32_e64 v43, v99, v72
	v_pk_mul_f32 v[40:41], v[96:97], v[72:73] op_sel_hi:[1,0]
	s_waitcnt lgkmcnt(8)
	s_nop 0
	v_mfma_f32_16x16x32_bf16 v[104:107], v[108:111], v[48:51], v[40:43]
	s_nop 2
	v_mul_f32_e64 v42, v130, v64
	v_mul_f32_e64 v43, v131, v64
	v_pk_mul_f32 v[40:41], v[128:129], v[64:65] op_sel_hi:[1,0]
	s_nop 1
	v_mfma_f32_16x16x32_bf16 v[108:111], v[108:111], v[16:19], v[40:43]
	s_nop 2
	v_mul_f32_e64 v42, v134, v72
	v_mul_f32_e64 v43, v135, v72
	v_pk_mul_f32 v[40:41], v[132:133], v[72:73] op_sel_hi:[1,0]
	s_waitcnt lgkmcnt(6)
	s_nop 0
	v_mfma_f32_16x16x32_bf16 v[112:115], v[116:119], v[48:51], v[40:43]
	s_nop 2
	v_mul_f32_e64 v42, v138, v64
	v_mul_f32_e64 v43, v139, v64
	v_pk_mul_f32 v[40:41], v[136:137], v[64:65] op_sel_hi:[1,0]
	s_nop 1
	v_mfma_f32_16x16x32_bf16 v[116:119], v[116:119], v[16:19], v[40:43]
	s_nop 2
	v_mul_f32_e64 v42, v142, v72
	v_mul_f32_e64 v43, v143, v72
	v_pk_mul_f32 v[40:41], v[140:141], v[72:73] op_sel_hi:[1,0]
	s_waitcnt lgkmcnt(4)
	s_nop 0
	v_mfma_f32_16x16x32_bf16 v[120:123], v[148:151], v[48:51], v[40:43]
	s_nop 2
	v_mul_f32_e64 v42, v146, v64
	v_mul_f32_e64 v43, v147, v64
	v_pk_mul_f32 v[40:41], v[144:145], v[64:65] op_sel_hi:[1,0]
	s_nop 1
	v_mfma_f32_16x16x32_bf16 v[124:127], v[148:151], v[16:19], v[40:43]
	v_lshlrev_b32_e32 v16, 2, v196
	v_add_u32_e32 v16, s76, v16
	v_med3_i32 v16, v16, 0, s75
	v_lshl_add_u32 v16, v16, 9, v152
	global_load_dwordx4 v[68:71], v16, s[98:99]
	v_lshlrev_b32_e32 v16, 2, v168
	v_add_u32_e32 v16, s76, v16
	v_med3_i32 v16, v16, 0, s75
	v_lshl_add_u32 v16, v16, 9, v152
	global_load_dwordx4 v[72:75], v16, s[98:99]
	v_lshlrev_b32_e32 v16, 2, v193
	v_add_u32_e32 v16, s76, v16
	v_med3_i32 v16, v16, 0, s75
	v_lshl_add_u32 v16, v16, 9, v152
	global_load_dwordx4 v[76:79], v16, s[98:99]
	v_lshlrev_b32_e32 v16, 2, v194
	v_add_u32_e32 v16, s76, v16
	v_med3_i32 v16, v16, 0, s75
	v_lshl_add_u32 v16, v16, 9, v152
	global_load_dwordx4 v[96:99], v16, s[98:99]
	v_or_b32_e32 v16, 0x180, v209
	v_add_u32_e32 v16, s76, v16
	v_med3_i32 v16, v16, 0, s75
	v_lshl_add_u32 v16, v16, 9, v158
	global_load_dwordx4 v[64:67], v16, s[100:101]
	global_load_dwordx4 v[48:51], v16, s[100:101] offset:64
	v_or_b32_e32 v16, 0x1c0, v209
	v_add_u32_e32 v16, s76, v16
	v_med3_i32 v16, v16, 0, s75
	v_lshl_add_u32 v16, v16, 9, v158
	global_load_dwordx4 v[40:43], v16, s[100:101]
	s_nop 0
	global_load_dwordx4 v[16:19], v16, s[100:101] offset:64
	ds_read_b64_tr_b16 v[142:143], v169 offset:6912
	ds_read_b64_tr_b16 v[140:141], v169 offset:4608
	ds_read_b64_tr_b16 v[136:137], v169 offset:4640
	ds_read_b64_tr_b16 v[138:139], v169 offset:6944
	ds_read_b64_tr_b16 v[132:133], v169 offset:4672
	ds_read_b64_tr_b16 v[134:135], v169 offset:6976
	ds_read_b64_tr_b16 v[128:129], v169 offset:4704
	ds_read_b64_tr_b16 v[130:131], v169 offset:7008
	s_waitcnt vmcnt(15)
	ds_write_b128 v241, v[80:83]
	s_waitcnt vmcnt(14)
	ds_write_b128 v242, v[84:87]
	s_waitcnt vmcnt(13)
	ds_write_b128 v243, v[88:91]
	s_waitcnt vmcnt(12)
	ds_write_b128 v244, v[92:95]
	v_mfma_f32_16x16x32_bf16 v[80:83], v[60:63], v[4:7], 0
	v_mfma_f32_16x16x32_bf16 v[84:87], v[36:39], v[4:7], 0
	v_mfma_f32_16x16x32_bf16 v[36:39], v[36:39], v[12:15], 0
	v_mfma_f32_16x16x32_bf16 v[80:83], v[56:59], v[8:11], v[80:83]
	v_mfma_f32_16x16x32_bf16 v[84:87], v[32:35], v[8:11], v[84:87]
	v_mfma_f32_16x16x32_bf16 v[32:35], v[32:35], v[0:3], v[36:39]
	s_nop 4
	v_sub_u32_e32 v36, v197, v176
	v_mfma_f32_16x16x32_bf16 v[60:63], v[60:63], v[12:15], 0
	v_add_u32_e32 v39, 1, v36
	v_cmp_gt_u32_e64 s[0:1], v39, v175
	v_cmp_gt_u32_e32 vcc, v36, v175
	s_nop 0
	v_cndmask_b32_e64 v81, v81, v246, s[0:1]
	s_nop 0
	v_cndmask_b32_e32 v80, v80, v246, vcc
	v_mfma_f32_16x16x32_bf16 v[56:59], v[56:59], v[0:3], v[60:63]
	v_max_f32_e32 v38, v80, v81
	v_add_u32_e32 v39, 2, v36
	v_cmp_gt_u32_e64 s[22:23], v39, v175
	v_add_u32_e32 v60, 3, v36
	v_cmp_gt_u32_e64 s[24:25], v60, v175
	v_cndmask_b32_e64 v82, v82, v246, s[22:23]
	v_sub_u32_e32 v37, v197, v181
	v_cndmask_b32_e64 v83, v83, v246, s[24:25]
	v_max3_f32 v38, v38, v82, v83
	v_add_u32_e32 v39, 16, v36
	v_add_u32_e32 v60, 17, v36
	v_cmp_gt_u32_e64 s[26:27], v39, v175
	v_cmp_gt_u32_e64 s[28:29], v60, v175
	v_cmp_gt_u32_e64 s[38:39], v37, v252
	v_cndmask_b32_e64 v84, v84, v246, s[26:27]
	v_cndmask_b32_e64 v85, v85, v246, s[28:29]
	v_max3_f32 v38, v38, v84, v85
	v_add_u32_e32 v39, 18, v36
	v_add_u32_e32 v36, 19, v36
	v_cmp_gt_u32_e64 s[30:31], v39, v175
	v_cmp_gt_u32_e64 s[34:35], v36, v175
	v_add_u32_e32 v60, 3, v37
	v_cndmask_b32_e64 v86, v86, v246, s[30:31]
	v_cndmask_b32_e64 v87, v87, v246, s[34:35]
	v_max3_f32 v36, v38, v86, v87
	v_add_u32_e32 v39, 1, v37
	v_cmp_gt_u32_e64 s[40:41], v39, v252
	v_cndmask_b32_e64 v56, v56, v246, s[38:39]
	s_nop 0
	v_cndmask_b32_e64 v57, v57, v246, s[40:41]
	v_max_f32_e32 v38, v56, v57
	v_add_u32_e32 v39, 2, v37
	v_cmp_gt_u32_e64 s[42:43], v39, v252
	v_cmp_gt_u32_e64 s[44:45], v60, v252
	s_nop 0
	v_cndmask_b32_e64 v58, v58, v246, s[42:43]
	v_cndmask_b32_e64 v59, v59, v246, s[44:45]
	v_max3_f32 v38, v38, v58, v59
	v_add_u32_e32 v39, 16, v37
	v_add_u32_e32 v60, 17, v37
	v_cmp_gt_u32_e64 s[46:47], v39, v252
	v_cmp_gt_u32_e64 s[48:49], v60, v252
	s_nop 0
	v_cndmask_b32_e64 v32, v32, v246, s[46:47]
	v_cndmask_b32_e64 v33, v33, v246, s[48:49]
	v_max3_f32 v38, v38, v32, v33
	v_add_u32_e32 v39, 18, v37
	v_add_u32_e32 v37, 19, v37
	v_cmp_gt_u32_e64 s[50:51], v39, v252
	v_cmp_gt_u32_e64 s[52:53], v37, v252
	s_nop 0
	v_cndmask_b32_e64 v34, v34, v246, s[50:51]
	v_cndmask_b32_e64 v35, v35, v246, s[52:53]
	v_max3_f32 v37, v38, v34, v35
	v_mov_b32_e32 v38, v36
	s_nop 1
	v_permlane32_swap_b32_e32 v38, v36
	v_max_f32_e32 v36, v36, v38
	v_mov_b32_e32 v38, v37
	s_nop 1
	v_permlane32_swap_b32_e32 v38, v37
	v_max_f32_e32 v37, v37, v38
	v_mov_b32_e32 v38, v36
	s_nop 1
	v_permlane16_swap_b32_e32 v38, v36
	v_max_f32_e32 v36, v36, v38
	v_mov_b32_e32 v38, v37
	v_max_f32_e32 v144, v177, v36
	s_nop 0
	v_permlane16_swap_b32_e32 v38, v37
	v_sub_f32_e32 v36, v177, v144
	v_exp_f32_e32 v60, v36
	v_sub_f32_e32 v36, v80, v144
	v_max_f32_e32 v62, v37, v38
	v_exp_f32_e32 v36, v36
	v_sub_f32_e32 v38, v81, v144
	v_exp_f32_e32 v38, v38
	v_sub_f32_e32 v39, v82, v144
	v_exp_f32_e32 v39, v39
	v_sub_f32_e32 v63, v83, v144
	v_max_f32_e32 v146, v179, v62
	v_exp_f32_e32 v63, v63
	v_sub_f32_e32 v80, v84, v144
	v_sub_f32_e32 v56, v56, v146
	v_exp_f32_e32 v80, v80
	v_sub_f32_e32 v81, v85, v144
	v_exp_f32_e32 v56, v56
	v_sub_f32_e32 v57, v57, v146
	v_exp_f32_e32 v81, v81
	v_sub_f32_e32 v82, v86, v144
	v_exp_f32_e32 v57, v57
	v_sub_f32_e32 v58, v58, v146
	v_add_f32_e32 v37, v38, v36
	v_exp_f32_e32 v82, v82
	v_sub_f32_e32 v83, v87, v144
	v_exp_f32_e32 v58, v58
	v_sub_f32_e32 v59, v59, v146
	v_add_f32_e32 v37, v39, v37
	v_exp_f32_e32 v83, v83
	v_exp_f32_e32 v59, v59
	v_sub_f32_e32 v32, v32, v146
	v_add_f32_e32 v37, v63, v37
	v_sub_f32_e32 v61, v179, v146
	v_exp_f32_e32 v32, v32
	v_sub_f32_e32 v33, v33, v146
	v_add_f32_e32 v37, v80, v37
	v_exp_f32_e32 v62, v61
	v_exp_f32_e32 v33, v33
	v_add_f32_e32 v37, v81, v37
	v_add_f32_e32 v61, v57, v56
	v_add_f32_e32 v37, v82, v37
	v_add_f32_e32 v61, v58, v61
	v_add_f32_e32 v145, v83, v37
	v_cvt_pk_bf16_f32 v37, v39, v63
	v_add_f32_e32 v61, v59, v61
	v_cndmask_b32_e64 v63, v32, 0, s[46:47]
	v_add_f32_e32 v32, v63, v61
	v_cndmask_b32_e64 v61, v33, 0, s[48:49]
	v_sub_f32_e32 v33, v34, v146
	v_exp_f32_e32 v33, v33
	v_cvt_pk_bf16_f32 v36, v36, v38
	v_cvt_pk_bf16_f32 v38, v80, v81
	v_add_f32_e32 v32, v61, v32
	v_cndmask_b32_e64 v80, v33, 0, s[50:51]
	v_sub_f32_e32 v33, v35, v146
	v_exp_f32_e32 v33, v33
	v_cvt_pk_bf16_f32 v39, v82, v83
	v_add_f32_e32 v32, v80, v32
	v_pk_mul_f32 v[26:27], v[26:27], v[60:61] op_sel_hi:[1,0]
	v_cndmask_b32_e64 v35, v33, 0, s[52:53]
	v_pk_mul_f32 v[24:25], v[24:25], v[60:61] op_sel_hi:[1,0]
	v_add_f32_e32 v147, v35, v32
	v_cvt_pk_bf16_f32 v32, v56, v57
	v_cvt_pk_bf16_f32 v33, v58, v59
	v_cvt_pk_bf16_f32 v34, v63, v61
	v_cvt_pk_bf16_f32 v35, v80, v35
	s_waitcnt lgkmcnt(10)
	v_mfma_f32_16x16x32_bf16 v[92:95], v[140:143], v[36:39], v[24:27]
	v_fmac_f32_e32 v145, v178, v60
	v_fmac_f32_e32 v147, v180, v62
	s_nop 0
	v_pk_mul_f32 v[26:27], v[102:103], v[62:63] op_sel_hi:[1,0]
	v_pk_mul_f32 v[24:25], v[100:101], v[62:63] op_sel_hi:[1,0]
	s_nop 1
	v_mfma_f32_16x16x32_bf16 v[100:103], v[140:143], v[32:35], v[24:27]
	s_nop 2
	v_mul_f32_e64 v26, v106, v60
	v_mul_f32_e64 v27, v107, v60
	v_pk_mul_f32 v[24:25], v[104:105], v[60:61] op_sel_hi:[1,0]
	s_waitcnt lgkmcnt(8)
	s_nop 0
	v_mfma_f32_16x16x32_bf16 v[104:107], v[136:139], v[36:39], v[24:27]
	s_nop 2
	v_mul_f32_e64 v26, v110, v62
	v_mul_f32_e64 v27, v111, v62
	v_pk_mul_f32 v[24:25], v[108:109], v[62:63] op_sel_hi:[1,0]
	s_nop 1
	v_mfma_f32_16x16x32_bf16 v[108:111], v[136:139], v[32:35], v[24:27]
	s_nop 2
	v_mul_f32_e64 v26, v114, v60
	v_mul_f32_e64 v27, v115, v60
	v_pk_mul_f32 v[24:25], v[112:113], v[60:61] op_sel_hi:[1,0]
	s_waitcnt lgkmcnt(6)
	s_nop 0
	v_mfma_f32_16x16x32_bf16 v[112:115], v[132:135], v[36:39], v[24:27]
	s_nop 2
	v_mul_f32_e64 v26, v118, v62
	v_mul_f32_e64 v27, v119, v62
	v_pk_mul_f32 v[24:25], v[116:117], v[62:63] op_sel_hi:[1,0]
	s_nop 1
	v_mfma_f32_16x16x32_bf16 v[116:119], v[132:135], v[32:35], v[24:27]
	s_nop 2
	v_mul_f32_e64 v26, v122, v60
	v_mul_f32_e64 v27, v123, v60
	v_pk_mul_f32 v[24:25], v[120:121], v[60:61] op_sel_hi:[1,0]
	s_waitcnt lgkmcnt(4)
	s_nop 0
	v_mfma_f32_16x16x32_bf16 v[120:123], v[128:131], v[36:39], v[24:27]
	s_nop 2
	v_mul_f32_e64 v26, v126, v62
	v_mul_f32_e64 v27, v127, v62
	v_pk_mul_f32 v[24:25], v[124:125], v[62:63] op_sel_hi:[1,0]
	s_nop 1
	v_mfma_f32_16x16x32_bf16 v[124:127], v[128:131], v[32:35], v[24:27]
	s_nop 2
	v_add_u32_e32 v24, s76, v214
	v_med3_i32 v24, v24, 0, s75
	v_lshl_add_u32 v24, v24, 9, v152
	global_load_dwordx4 v[60:63], v24, s[98:99]
	v_add_u32_e32 v24, s76, v216
	v_med3_i32 v24, v24, 0, s75
	v_lshl_add_u32 v24, v24, 9, v152
	global_load_dwordx4 v[80:83], v24, s[98:99]
	v_add_u32_e32 v24, s76, v218
	v_med3_i32 v24, v24, 0, s75
	v_lshl_add_u32 v24, v24, 9, v152
	global_load_dwordx4 v[84:87], v24, s[98:99]
	v_add_u32_e32 v24, s76, v220
	v_med3_i32 v24, v24, 0, s75
	v_lshl_add_u32 v24, v24, 9, v152
	global_load_dwordx4 v[88:91], v24, s[98:99]
	v_add_u32_e32 v24, s76, v221
	v_med3_i32 v24, v24, 0, s75
	v_lshl_add_u32 v24, v24, 9, v158
	global_load_dwordx4 v[56:59], v24, s[100:101]
	global_load_dwordx4 v[36:39], v24, s[100:101] offset:64
	v_or_b32_e32 v24, 0x100, v221
	v_add_u32_e32 v24, s76, v24
	v_med3_i32 v24, v24, 0, s75
	v_lshl_add_u32 v24, v24, 9, v158
	global_load_dwordx4 v[32:35], v24, s[100:101]
	s_nop 0
	global_load_dwordx4 v[24:27], v24, s[100:101] offset:64
	ds_read_b64_tr_b16 v[142:143], v169 offset:2304
	ds_read_b64_tr_b16 v[140:141], v169
	ds_read_b64_tr_b16 v[136:137], v169 offset:32
	ds_read_b64_tr_b16 v[138:139], v169 offset:2336
	ds_read_b64_tr_b16 v[132:133], v169 offset:64
	ds_read_b64_tr_b16 v[134:135], v169 offset:2368
	ds_read_b64_tr_b16 v[128:129], v169 offset:96
	ds_read_b64_tr_b16 v[130:131], v169 offset:2400
	s_waitcnt vmcnt(15)
	ds_write_b128 v241, v[68:71] offset:4608
	s_waitcnt vmcnt(14)
	ds_write_b128 v242, v[72:75] offset:4608
	s_waitcnt vmcnt(13)
	ds_write_b128 v243, v[76:79] offset:4608
	s_waitcnt vmcnt(12)
	ds_write_b128 v244, v[96:99] offset:4608
	v_mfma_f32_16x16x32_bf16 v[68:71], v[52:55], v[4:7], 0
	v_mfma_f32_16x16x32_bf16 v[72:75], v[28:31], v[4:7], 0
	v_mfma_f32_16x16x32_bf16 v[28:31], v[28:31], v[12:15], 0
	v_mfma_f32_16x16x32_bf16 v[68:71], v[44:47], v[8:11], v[68:71]
	v_mfma_f32_16x16x32_bf16 v[72:75], v[20:23], v[8:11], v[72:75]
	v_mfma_f32_16x16x32_bf16 v[20:23], v[20:23], v[0:3], v[28:31]
	s_nop 4
	v_sub_u32_e32 v28, v198, v176
	v_mfma_f32_16x16x32_bf16 v[52:55], v[52:55], v[12:15], 0
	v_add_u32_e32 v31, 1, v28
	v_cmp_gt_u32_e64 s[0:1], v31, v175
	v_cmp_gt_u32_e32 vcc, v28, v175
	s_nop 0
	v_cndmask_b32_e64 v69, v69, v246, s[0:1]
	s_nop 0
	v_cndmask_b32_e32 v68, v68, v246, vcc
	v_mfma_f32_16x16x32_bf16 v[44:47], v[44:47], v[0:3], v[52:55]
	v_max_f32_e32 v30, v68, v69
	v_add_u32_e32 v31, 2, v28
	v_cmp_gt_u32_e64 s[22:23], v31, v175
	v_add_u32_e32 v52, 3, v28
	v_cmp_gt_u32_e64 s[24:25], v52, v175
	v_cndmask_b32_e64 v70, v70, v246, s[22:23]
	v_sub_u32_e32 v29, v198, v181
	v_cndmask_b32_e64 v71, v71, v246, s[24:25]
	v_max3_f32 v30, v30, v70, v71
	v_add_u32_e32 v31, 16, v28
	v_add_u32_e32 v52, 17, v28
	v_cmp_gt_u32_e64 s[26:27], v31, v175
	v_cmp_gt_u32_e64 s[28:29], v52, v175
	v_cmp_gt_u32_e64 s[38:39], v29, v252
	v_cndmask_b32_e64 v72, v72, v246, s[26:27]
	v_cndmask_b32_e64 v73, v73, v246, s[28:29]
	v_max3_f32 v30, v30, v72, v73
	v_add_u32_e32 v31, 18, v28
	v_add_u32_e32 v28, 19, v28
	v_cmp_gt_u32_e64 s[30:31], v31, v175
	v_cmp_gt_u32_e64 s[34:35], v28, v175
	v_add_u32_e32 v52, 3, v29
	v_cndmask_b32_e64 v74, v74, v246, s[30:31]
	v_cndmask_b32_e64 v75, v75, v246, s[34:35]
	v_max3_f32 v28, v30, v74, v75
	v_add_u32_e32 v31, 1, v29
	v_cmp_gt_u32_e64 s[40:41], v31, v252
	v_cndmask_b32_e64 v44, v44, v246, s[38:39]
	s_nop 0
	v_cndmask_b32_e64 v45, v45, v246, s[40:41]
	v_max_f32_e32 v30, v44, v45
	v_add_u32_e32 v31, 2, v29
	v_cmp_gt_u32_e64 s[42:43], v31, v252
	v_cmp_gt_u32_e64 s[44:45], v52, v252
	s_nop 0
	v_cndmask_b32_e64 v46, v46, v246, s[42:43]
	v_cndmask_b32_e64 v47, v47, v246, s[44:45]
	v_max3_f32 v30, v30, v46, v47
	v_add_u32_e32 v31, 16, v29
	v_add_u32_e32 v52, 17, v29
	v_cmp_gt_u32_e64 s[46:47], v31, v252
	v_cmp_gt_u32_e64 s[48:49], v52, v252
	s_nop 0
	v_cndmask_b32_e64 v20, v20, v246, s[46:47]
	v_cndmask_b32_e64 v21, v21, v246, s[48:49]
	v_max3_f32 v30, v30, v20, v21
	v_add_u32_e32 v31, 18, v29
	v_add_u32_e32 v29, 19, v29
	v_cmp_gt_u32_e64 s[50:51], v31, v252
	v_cmp_gt_u32_e64 s[52:53], v29, v252
	s_nop 0
	v_cndmask_b32_e64 v22, v22, v246, s[50:51]
	v_cndmask_b32_e64 v23, v23, v246, s[52:53]
	v_max3_f32 v29, v30, v22, v23
	v_mov_b32_e32 v30, v28
	s_nop 1
	v_permlane32_swap_b32_e32 v30, v28
	v_max_f32_e32 v28, v28, v30
	v_mov_b32_e32 v30, v29
	s_nop 1
	v_permlane32_swap_b32_e32 v30, v29
	v_max_f32_e32 v29, v29, v30
	v_mov_b32_e32 v30, v28
	s_nop 1
	v_permlane16_swap_b32_e32 v30, v28
	v_max_f32_e32 v28, v28, v30
	v_mov_b32_e32 v30, v29
	v_max_f32_e32 v148, v144, v28
	s_nop 0
	v_permlane16_swap_b32_e32 v30, v29
	v_sub_f32_e32 v28, v144, v148
	v_exp_f32_e32 v52, v28
	v_sub_f32_e32 v28, v68, v148
	v_max_f32_e32 v54, v29, v30
	v_exp_f32_e32 v28, v28
	v_sub_f32_e32 v30, v69, v148
	v_exp_f32_e32 v30, v30
	v_sub_f32_e32 v31, v70, v148
	v_exp_f32_e32 v31, v31
	v_sub_f32_e32 v55, v71, v148
	v_max_f32_e32 v149, v146, v54
	v_exp_f32_e32 v55, v55
	v_sub_f32_e32 v68, v72, v148
	v_sub_f32_e32 v44, v44, v149
	v_exp_f32_e32 v68, v68
	v_sub_f32_e32 v69, v73, v148
	v_exp_f32_e32 v44, v44
	v_sub_f32_e32 v45, v45, v149
	v_exp_f32_e32 v69, v69
	v_sub_f32_e32 v70, v74, v148
	v_exp_f32_e32 v45, v45
	v_sub_f32_e32 v46, v46, v149
	v_add_f32_e32 v29, v30, v28
	v_exp_f32_e32 v70, v70
	v_sub_f32_e32 v71, v75, v148
	v_exp_f32_e32 v46, v46
	v_sub_f32_e32 v47, v47, v149
	v_add_f32_e32 v29, v31, v29
	v_exp_f32_e32 v71, v71
	v_exp_f32_e32 v47, v47
	v_sub_f32_e32 v20, v20, v149
	v_add_f32_e32 v29, v55, v29
	v_sub_f32_e32 v53, v146, v149
	v_exp_f32_e32 v20, v20
	v_sub_f32_e32 v21, v21, v149
	v_add_f32_e32 v29, v68, v29
	v_exp_f32_e32 v54, v53
	v_exp_f32_e32 v21, v21
	v_add_f32_e32 v29, v69, v29
	v_add_f32_e32 v53, v45, v44
	v_add_f32_e32 v29, v70, v29
	v_add_f32_e32 v53, v46, v53
	v_add_f32_e32 v144, v71, v29
	v_cvt_pk_bf16_f32 v29, v31, v55
	v_add_f32_e32 v53, v47, v53
	v_cndmask_b32_e64 v55, v20, 0, s[46:47]
	v_add_f32_e32 v20, v55, v53
	v_cndmask_b32_e64 v53, v21, 0, s[48:49]
	v_sub_f32_e32 v21, v22, v149
	v_exp_f32_e32 v21, v21
	v_cvt_pk_bf16_f32 v28, v28, v30
	v_cvt_pk_bf16_f32 v30, v68, v69
	v_add_f32_e32 v20, v53, v20
	v_cndmask_b32_e64 v68, v21, 0, s[50:51]
	v_sub_f32_e32 v21, v23, v149
	v_exp_f32_e32 v21, v21
	v_add_f32_e32 v20, v68, v20
	v_fmac_f32_e32 v144, v145, v52
	v_cvt_pk_bf16_f32 v31, v70, v71
	v_cndmask_b32_e64 v23, v21, 0, s[52:53]
	v_add_f32_e32 v145, v23, v20
	v_cvt_pk_bf16_f32 v20, v44, v45
	v_cvt_pk_bf16_f32 v21, v46, v47
	v_pk_mul_f32 v[46:47], v[94:95], v[52:53] op_sel_hi:[1,0]
	v_pk_mul_f32 v[44:45], v[92:93], v[52:53] op_sel_hi:[1,0]
	v_cvt_pk_bf16_f32 v22, v55, v53
	v_cvt_pk_bf16_f32 v23, v68, v23
	s_waitcnt lgkmcnt(10)
	v_mfma_f32_16x16x32_bf16 v[96:99], v[140:143], v[28:31], v[44:47]
	v_fmac_f32_e32 v145, v147, v54
	s_nop 1
	v_pk_mul_f32 v[46:47], v[102:103], v[54:55] op_sel_hi:[1,0]
	v_pk_mul_f32 v[44:45], v[100:101], v[54:55] op_sel_hi:[1,0]
	s_nop 1
	v_mfma_f32_16x16x32_bf16 v[100:103], v[140:143], v[20:23], v[44:47]
	s_nop 2
	v_mul_f32_e64 v46, v106, v52
	v_mul_f32_e64 v47, v107, v52
	v_pk_mul_f32 v[44:45], v[104:105], v[52:53] op_sel_hi:[1,0]
	s_waitcnt lgkmcnt(8)
	s_nop 0
	v_mfma_f32_16x16x32_bf16 v[104:107], v[136:139], v[28:31], v[44:47]
	s_nop 2
	v_mul_f32_e64 v46, v110, v54
	v_mul_f32_e64 v47, v111, v54
	v_pk_mul_f32 v[44:45], v[108:109], v[54:55] op_sel_hi:[1,0]
	s_nop 1
	v_mfma_f32_16x16x32_bf16 v[108:111], v[136:139], v[20:23], v[44:47]
	s_nop 2
	v_mul_f32_e64 v46, v114, v52
	v_mul_f32_e64 v47, v115, v52
	v_pk_mul_f32 v[44:45], v[112:113], v[52:53] op_sel_hi:[1,0]
	s_waitcnt lgkmcnt(6)
	s_nop 0
	v_mfma_f32_16x16x32_bf16 v[112:115], v[132:135], v[28:31], v[44:47]
	s_nop 2
	v_mul_f32_e64 v46, v118, v54
	v_mul_f32_e64 v47, v119, v54
	v_pk_mul_f32 v[44:45], v[116:117], v[54:55] op_sel_hi:[1,0]
	s_nop 1
	v_mfma_f32_16x16x32_bf16 v[116:119], v[132:135], v[20:23], v[44:47]
	s_nop 2
	v_mul_f32_e64 v46, v122, v52
	v_mul_f32_e64 v47, v123, v52
	v_pk_mul_f32 v[44:45], v[120:121], v[52:53] op_sel_hi:[1,0]
	s_waitcnt lgkmcnt(4)
	s_nop 0
	v_mfma_f32_16x16x32_bf16 v[120:123], v[128:131], v[28:31], v[44:47]
	v_mul_f32_e64 v30, v126, v54
	v_mul_f32_e64 v31, v127, v54
	v_pk_mul_f32 v[28:29], v[124:125], v[54:55] op_sel_hi:[1,0]
	s_nop 1
	v_mfma_f32_16x16x32_bf16 v[124:127], v[128:131], v[20:23], v[28:31]
	v_add_u32_e32 v20, s76, v222
	v_med3_i32 v20, v20, 0, s75
	v_lshl_add_u32 v20, v20, 9, v152
	global_load_dwordx4 v[68:71], v20, s[98:99]
	v_add_u32_e32 v20, s76, v223
	v_med3_i32 v20, v20, 0, s75
	v_lshl_add_u32 v20, v20, 9, v152
	global_load_dwordx4 v[72:75], v20, s[98:99]
	v_add_u32_e32 v20, s76, v224
	v_med3_i32 v20, v20, 0, s75
	v_lshl_add_u32 v20, v20, 9, v152
	global_load_dwordx4 v[76:79], v20, s[98:99]
	v_add_u32_e32 v20, s76, v225
	v_med3_i32 v20, v20, 0, s75
	v_lshl_add_u32 v20, v20, 9, v152
	global_load_dwordx4 v[92:95], v20, s[98:99]
	v_add_u32_e32 v20, s76, v226
	v_med3_i32 v20, v20, 0, s75
	v_lshl_add_u32 v20, v20, 9, v158
	global_load_dwordx4 v[52:55], v20, s[100:101]
	global_load_dwordx4 v[44:47], v20, s[100:101] offset:64
	v_add_u32_e32 v20, s76, v227
	v_med3_i32 v20, v20, 0, s75
	v_lshl_add_u32 v20, v20, 9, v158
	global_load_dwordx4 v[28:31], v20, s[100:101]
	s_nop 0
	global_load_dwordx4 v[20:23], v20, s[100:101] offset:64
	ds_read_b64_tr_b16 v[142:143], v169 offset:6912
	ds_read_b64_tr_b16 v[140:141], v169 offset:4608
	ds_read_b64_tr_b16 v[136:137], v169 offset:4640
	ds_read_b64_tr_b16 v[138:139], v169 offset:6944
	ds_read_b64_tr_b16 v[132:133], v169 offset:4672
	ds_read_b64_tr_b16 v[134:135], v169 offset:6976
	ds_read_b64_tr_b16 v[128:129], v169 offset:4704
	ds_read_b64_tr_b16 v[130:131], v169 offset:7008
	s_waitcnt vmcnt(15)
	ds_write_b128 v241, v[60:63]
	s_waitcnt vmcnt(14)
	ds_write_b128 v242, v[80:83]
	s_waitcnt vmcnt(13)
	ds_write_b128 v243, v[84:87]
	s_waitcnt vmcnt(12)
	ds_write_b128 v244, v[88:91]
	v_mfma_f32_16x16x32_bf16 v[60:63], v[64:67], v[4:7], 0
	v_mfma_f32_16x16x32_bf16 v[80:83], v[40:43], v[4:7], 0
	v_mfma_f32_16x16x32_bf16 v[40:43], v[40:43], v[12:15], 0
	v_mfma_f32_16x16x32_bf16 v[60:63], v[48:51], v[8:11], v[60:63]
	v_mfma_f32_16x16x32_bf16 v[80:83], v[16:19], v[8:11], v[80:83]
	v_mfma_f32_16x16x32_bf16 v[16:19], v[16:19], v[0:3], v[40:43]
	s_nop 4
	v_sub_u32_e32 v40, v199, v176
	v_mfma_f32_16x16x32_bf16 v[64:67], v[64:67], v[12:15], 0
	v_add_u32_e32 v43, 1, v40
	v_cmp_gt_u32_e64 s[0:1], v43, v175
	v_cmp_gt_u32_e32 vcc, v40, v175
	s_nop 0
	v_cndmask_b32_e64 v61, v61, v246, s[0:1]
	s_nop 0
	v_cndmask_b32_e32 v60, v60, v246, vcc
	v_mfma_f32_16x16x32_bf16 v[48:51], v[48:51], v[0:3], v[64:67]
	v_max_f32_e32 v42, v60, v61
	v_add_u32_e32 v43, 2, v40
	v_cmp_gt_u32_e64 s[22:23], v43, v175
	v_add_u32_e32 v64, 3, v40
	v_cmp_gt_u32_e64 s[24:25], v64, v175
	v_cndmask_b32_e64 v62, v62, v246, s[22:23]
	v_sub_u32_e32 v41, v199, v181
	v_cndmask_b32_e64 v63, v63, v246, s[24:25]
	v_max3_f32 v42, v42, v62, v63
	v_add_u32_e32 v43, 16, v40
	v_add_u32_e32 v64, 17, v40
	v_cmp_gt_u32_e64 s[26:27], v43, v175
	v_cmp_gt_u32_e64 s[28:29], v64, v175
	v_cmp_gt_u32_e64 s[38:39], v41, v252
	v_cndmask_b32_e64 v80, v80, v246, s[26:27]
	v_cndmask_b32_e64 v81, v81, v246, s[28:29]
	v_max3_f32 v42, v42, v80, v81
	v_add_u32_e32 v43, 18, v40
	v_add_u32_e32 v40, 19, v40
	v_cmp_gt_u32_e64 s[30:31], v43, v175
	v_cmp_gt_u32_e64 s[34:35], v40, v175
	v_add_u32_e32 v64, 3, v41
	v_cndmask_b32_e64 v82, v82, v246, s[30:31]
	v_cndmask_b32_e64 v83, v83, v246, s[34:35]
	v_max3_f32 v40, v42, v82, v83
	v_add_u32_e32 v43, 1, v41
	v_cmp_gt_u32_e64 s[40:41], v43, v252
	v_cndmask_b32_e64 v48, v48, v246, s[38:39]
	s_nop 0
	v_cndmask_b32_e64 v49, v49, v246, s[40:41]
	v_max_f32_e32 v42, v48, v49
	v_add_u32_e32 v43, 2, v41
	v_cmp_gt_u32_e64 s[42:43], v43, v252
	v_cmp_gt_u32_e64 s[44:45], v64, v252
	s_nop 0
	v_cndmask_b32_e64 v50, v50, v246, s[42:43]
	v_cndmask_b32_e64 v51, v51, v246, s[44:45]
	v_max3_f32 v42, v42, v50, v51
	v_add_u32_e32 v43, 16, v41
	v_add_u32_e32 v64, 17, v41
	v_cmp_gt_u32_e64 s[46:47], v43, v252
	v_cmp_gt_u32_e64 s[48:49], v64, v252
	s_nop 0
	v_cndmask_b32_e64 v16, v16, v246, s[46:47]
	v_cndmask_b32_e64 v17, v17, v246, s[48:49]
	v_max3_f32 v42, v42, v16, v17
	v_add_u32_e32 v43, 18, v41
	v_add_u32_e32 v41, 19, v41
	v_cmp_gt_u32_e64 s[50:51], v43, v252
	v_cmp_gt_u32_e64 s[52:53], v41, v252
	s_nop 0
	v_cndmask_b32_e64 v18, v18, v246, s[50:51]
	v_cndmask_b32_e64 v19, v19, v246, s[52:53]
	v_max3_f32 v41, v42, v18, v19
	v_mov_b32_e32 v42, v40
	s_nop 1
	v_permlane32_swap_b32_e32 v42, v40
	v_max_f32_e32 v40, v40, v42
	v_mov_b32_e32 v42, v41
	s_nop 1
	v_permlane32_swap_b32_e32 v42, v41
	v_max_f32_e32 v41, v41, v42
	v_mov_b32_e32 v42, v40
	s_nop 1
	v_permlane16_swap_b32_e32 v42, v40
	v_max3_f32 v147, v148, v40, v42
	v_sub_f32_e32 v40, v148, v147
	v_exp_f32_e32 v84, v40
	v_sub_f32_e32 v40, v60, v147
	v_exp_f32_e32 v40, v40
	v_mov_b32_e32 v42, v41
	s_nop 1
	v_permlane16_swap_b32_e32 v42, v41
	v_cndmask_b32_e64 v85, v40, 0, vcc
	v_sub_f32_e32 v40, v61, v147
	v_exp_f32_e32 v40, v40
	v_max3_f32 v146, v149, v41, v42
	v_cndmask_b32_e64 v61, v40, 0, s[0:1]
	v_sub_f32_e32 v40, v62, v147
	v_exp_f32_e32 v40, v40
	v_sub_f32_e32 v48, v48, v146
	v_sub_f32_e32 v16, v16, v146
	v_exp_f32_e32 v48, v48
	v_cndmask_b32_e64 v62, v40, 0, s[22:23]
	v_sub_f32_e32 v40, v63, v147
	v_exp_f32_e32 v40, v40
	v_exp_f32_e32 v16, v16
	v_cndmask_b32_e64 v86, v48, 0, s[38:39]
	v_sub_f32_e32 v48, v49, v146
	v_cndmask_b32_e64 v63, v40, 0, s[24:25]
	v_sub_f32_e32 v40, v80, v147
	v_exp_f32_e32 v40, v40
	v_cndmask_b32_e64 v90, v16, 0, s[46:47]
	v_sub_f32_e32 v16, v17, v146
	v_exp_f32_e32 v48, v48
	v_cndmask_b32_e64 v80, v40, 0, s[26:27]
	v_sub_f32_e32 v40, v81, v147
	v_exp_f32_e32 v40, v40
	v_exp_f32_e32 v16, v16
	v_cndmask_b32_e64 v87, v48, 0, s[40:41]
	v_sub_f32_e32 v48, v50, v146
	v_cndmask_b32_e64 v81, v40, 0, s[28:29]
	v_sub_f32_e32 v40, v82, v147
	v_exp_f32_e32 v40, v40
	v_cndmask_b32_e64 v91, v16, 0, s[48:49]
	v_sub_f32_e32 v16, v18, v146
	v_exp_f32_e32 v48, v48
	v_exp_f32_e32 v16, v16
	v_cndmask_b32_e64 v82, v40, 0, s[30:31]
	v_sub_f32_e32 v40, v83, v147
	v_exp_f32_e32 v40, v40
	v_cndmask_b32_e64 v88, v48, 0, s[42:43]
	v_sub_f32_e32 v48, v51, v146
	v_cndmask_b32_e64 v148, v16, 0, s[50:51]
	v_sub_f32_e32 v16, v19, v146
	v_sub_f32_e32 v60, v149, v146
	v_exp_f32_e32 v48, v48
	v_exp_f32_e32 v16, v16
	v_exp_f32_e32 v60, v60
	v_cndmask_b32_e64 v83, v40, 0, s[34:35]
	v_cvt_pk_bf16_f32 v40, v85, v61
	v_cvt_pk_bf16_f32 v41, v62, v63
	v_cvt_pk_bf16_f32 v42, v80, v81
	v_cvt_pk_bf16_f32 v43, v82, v83
	v_cndmask_b32_e64 v89, v48, 0, s[44:45]
	v_cndmask_b32_e64 v149, v16, 0, s[52:53]
	v_pk_mul_f32 v[50:51], v[98:99], v[84:85] op_sel_hi:[1,0]
	v_pk_mul_f32 v[48:49], v[96:97], v[84:85] op_sel_hi:[1,0]
	v_cvt_pk_bf16_f32 v16, v86, v87
	v_cvt_pk_bf16_f32 v17, v88, v89
	v_cvt_pk_bf16_f32 v18, v90, v91
	v_cvt_pk_bf16_f32 v19, v148, v149
	s_waitcnt lgkmcnt(10)
	v_mfma_f32_16x16x32_bf16 v[64:67], v[140:143], v[40:43], v[48:51]
	s_cselect_b64 s[38:39], -1, 0
	s_add_i32 s0, s76, 0xfffffc00
	s_min_i32 s1, s0, 0
	v_pk_mul_f32 v[50:51], v[102:103], v[60:61] op_sel_hi:[1,0]
	v_pk_mul_f32 v[48:49], v[100:101], v[60:61] op_sel_hi:[1,0]
	s_sub_i32 s1, 15, s1
	s_ashr_i32 s1, s1, 4
	v_mfma_f32_16x16x32_bf16 v[100:103], v[140:143], v[16:19], v[48:51]
	s_sub_i32 s0, s75, s0
	s_ashr_i32 s0, s0, 4
	s_or_b32 s40, s76, 8
	v_pk_mul_f32 v[50:51], v[106:107], v[84:85] op_sel_hi:[1,0]
	v_pk_mul_f32 v[48:49], v[104:105], v[84:85] op_sel_hi:[1,0]
	s_lshl_b32 s56, s56, 7
	s_add_i32 s71, s71, s78
	s_waitcnt lgkmcnt(8)
	v_mfma_f32_16x16x32_bf16 v[104:107], v[136:139], v[40:43], v[48:51]
	s_nop 2
	v_mul_f32_e64 v50, v110, v60
	v_mul_f32_e64 v51, v111, v60
	v_pk_mul_f32 v[48:49], v[108:109], v[60:61] op_sel_hi:[1,0]
	s_nop 1
	v_mfma_f32_16x16x32_bf16 v[108:111], v[136:139], v[16:19], v[48:51]
	s_nop 2
	v_mul_f32_e64 v50, v114, v84
	v_mul_f32_e64 v51, v115, v84
	v_pk_mul_f32 v[48:49], v[112:113], v[84:85] op_sel_hi:[1,0]
	s_waitcnt lgkmcnt(6)
	s_nop 0
	v_mfma_f32_16x16x32_bf16 v[112:115], v[132:135], v[40:43], v[48:51]
	s_nop 2
	v_mul_f32_e64 v50, v118, v60
	v_mul_f32_e64 v51, v119, v60
	v_pk_mul_f32 v[48:49], v[116:117], v[60:61] op_sel_hi:[1,0]
	s_nop 1
	v_mfma_f32_16x16x32_bf16 v[116:119], v[132:135], v[16:19], v[48:51]
	s_nop 2
	v_mul_f32_e64 v50, v122, v84
	v_mul_f32_e64 v51, v123, v84
	v_pk_mul_f32 v[48:49], v[120:121], v[84:85] op_sel_hi:[1,0]
	s_waitcnt lgkmcnt(4)
	s_nop 0
	v_mfma_f32_16x16x32_bf16 v[120:123], v[128:131], v[40:43], v[48:51]
	v_mul_f32_e64 v42, v126, v60
	v_mul_f32_e64 v43, v127, v60
	v_pk_mul_f32 v[40:41], v[124:125], v[60:61] op_sel_hi:[1,0]
	s_nop 1
	v_mfma_f32_16x16x32_bf16 v[124:127], v[128:131], v[16:19], v[40:43]
	v_add_f32_e32 v16, v87, v86
	v_add_f32_e32 v16, v88, v16
	v_add_f32_e32 v16, v89, v16
	v_add_f32_e32 v16, v90, v16
	v_add_f32_e32 v16, v91, v16
	v_add_f32_e32 v16, v148, v16
	v_add_f32_e32 v151, v149, v16
	v_add_f32_e32 v16, v61, v85
	v_add_f32_e32 v16, v62, v16
	v_add_f32_e32 v16, v63, v16
	v_add_f32_e32 v16, v80, v16
	v_add_f32_e32 v16, v81, v16
	v_add_f32_e32 v16, v82, v16
	v_fmac_f32_e32 v151, v145, v60
	v_add_f32_e32 v145, v83, v16
	v_add_u32_e32 v16, s76, v213
	v_fmac_f32_e32 v145, v144, v84
	v_ashrrev_i32_e32 v148, 4, v250
	v_med3_i32 v16, v16, 0, s75
	v_lshl_add_u32 v16, v16, 9, v152
	global_load_dwordx4 v[80:83], v16, s[98:99]
	v_add_u32_e32 v16, s76, v215
	v_max_i32_e32 v150, s1, v148
	s_nop 0
	v_med3_i32 v16, v16, 0, s75
	v_lshl_add_u32 v16, v16, 9, v152
	global_load_dwordx4 v[84:87], v16, s[98:99]
	v_add_u32_e32 v16, s76, v217
	v_med3_i32 v16, v16, 0, s75
	v_lshl_add_u32 v16, v16, 9, v152
	global_load_dwordx4 v[88:91], v16, s[98:99]
	v_add_u32_e32 v16, s76, v219
	v_med3_i32 v16, v16, 0, s75
	v_lshl_add_u32 v16, v16, 9, v152
	global_load_dwordx4 v[96:99], v16, s[98:99]
	v_min_i32_e32 v16, s75, v251
	v_cndmask_b32_e64 v16, v16, 0, s[38:39]
	v_lshl_add_u32 v16, v16, 9, v158
	global_load_dwordx4 v[48:51], v16, s[100:101]
	global_load_dwordx4 v[60:63], v16, s[100:101] offset:64
	v_add_u32_e32 v16, s76, v228
	v_med3_i32 v16, v16, 0, s75
	v_lshl_add_u32 v16, v16, 9, v158
	global_load_dwordx4 v[40:43], v16, s[100:101]
	s_nop 0
	global_load_dwordx4 v[16:19], v16, s[100:101] offset:64
	ds_read_b64_tr_b16 v[142:143], v169 offset:2304
	ds_read_b64_tr_b16 v[140:141], v169
	ds_read_b64_tr_b16 v[136:137], v169 offset:32
	ds_read_b64_tr_b16 v[138:139], v169 offset:2336
	ds_read_b64_tr_b16 v[132:133], v169 offset:64
	ds_read_b64_tr_b16 v[134:135], v169 offset:2368
	ds_read_b64_tr_b16 v[128:129], v169 offset:96
	ds_read_b64_tr_b16 v[130:131], v169 offset:2400
	s_waitcnt vmcnt(15)
	ds_write_b128 v241, v[68:71] offset:4608
	s_waitcnt vmcnt(14)
	ds_write_b128 v242, v[72:75] offset:4608
	s_waitcnt vmcnt(13)
	ds_write_b128 v243, v[76:79] offset:4608
	s_waitcnt vmcnt(12)
	ds_write_b128 v244, v[92:95] offset:4608
	v_mfma_f32_16x16x32_bf16 v[72:75], v[32:35], v[4:7], 0
	v_mfma_f32_16x16x32_bf16 v[68:71], v[56:59], v[4:7], 0
	v_mfma_f32_16x16x32_bf16 v[72:75], v[24:27], v[8:11], v[72:75]
	v_mfma_f32_16x16x32_bf16 v[68:71], v[36:39], v[8:11], v[68:71]
	s_nop 5
	v_add_u32_e32 v25, 0x800, v250
	v_ashrrev_i32_e32 v25, 4, v25
	v_min3_i32 v25, v25, s0, v248
	v_sub_u32_e32 v26, v154, v150
	v_sub_u32_e32 v149, v25, v150
	v_add_u32_e32 v27, 1, v26
	v_cmp_gt_u32_e64 s[0:1], v27, v149
	v_cmp_gt_u32_e32 vcc, v26, v149
	s_nop 0
	v_cndmask_b32_e64 v69, v69, v246, s[0:1]
	s_nop 0
	v_cndmask_b32_e32 v68, v68, v246, vcc
	v_max_f32_e32 v25, v68, v69
	v_add_u32_e32 v27, 2, v26
	v_add_u32_e32 v32, 3, v26
	v_cmp_gt_u32_e64 s[22:23], v27, v149
	v_cmp_gt_u32_e64 s[24:25], v32, v149
	s_nop 0
	v_cndmask_b32_e64 v70, v70, v246, s[22:23]
	s_nop 0
	v_cndmask_b32_e64 v71, v71, v246, s[24:25]
	v_max3_f32 v25, v25, v70, v71
	v_add_u32_e32 v27, 16, v26
	v_add_u32_e32 v32, 17, v26
	v_cmp_gt_u32_e64 s[26:27], v27, v149
	v_cmp_gt_u32_e64 s[28:29], v32, v149
	s_nop 0
	v_cndmask_b32_e64 v72, v72, v246, s[26:27]
	v_cndmask_b32_e64 v73, v73, v246, s[28:29]
	v_max3_f32 v25, v25, v72, v73
	v_add_u32_e32 v27, 18, v26
	v_add_u32_e32 v26, 19, v26
	v_cmp_gt_u32_e64 s[30:31], v27, v149
	v_cmp_gt_u32_e64 s[34:35], v26, v149
	s_nop 0
	v_cndmask_b32_e64 v74, v74, v246, s[30:31]
	v_cndmask_b32_e64 v75, v75, v246, s[34:35]
	v_max3_f32 v25, v25, v74, v75
	v_mov_b32_e32 v27, v25
	s_nop 1
	v_permlane32_swap_b32_e32 v27, v25
	v_max_f32_e32 v25, v25, v27
	s_nop 1
	v_mov_b32_e32 v27, v25
	s_nop 1
	v_permlane16_swap_b32_e32 v27, v25
	v_max3_f32 v144, v147, v25, v27
	v_sub_f32_e32 v25, v147, v144
	v_exp_f32_e32 v56, v25
	v_sub_f32_e32 v25, v68, v144
	v_exp_f32_e32 v25, v25
	v_sub_f32_e32 v32, v69, v144
	v_exp_f32_e32 v32, v32
	v_sub_f32_e32 v33, v70, v144
	v_exp_f32_e32 v33, v33
	v_sub_f32_e32 v34, v71, v144
	v_exp_f32_e32 v34, v34
	v_sub_f32_e32 v35, v72, v144
	v_exp_f32_e32 v35, v35
	v_sub_f32_e32 v38, v73, v144
	v_exp_f32_e32 v38, v38
	v_sub_f32_e32 v39, v74, v144
	v_add_f32_e32 v27, v32, v25
	v_exp_f32_e32 v39, v39
	v_sub_f32_e32 v57, v75, v144
	v_add_f32_e32 v27, v33, v27
	v_exp_f32_e32 v57, v57
	v_add_f32_e32 v27, v34, v27
	v_add_f32_e32 v27, v35, v27
	v_add_f32_e32 v27, v38, v27
	v_add_f32_e32 v27, v39, v27
	v_add_f32_e32 v147, v57, v27
	v_fmac_f32_e32 v147, v145, v56
	v_mov_b32_e32 v145, v146
	v_cvt_pk_bf16_f32 v32, v25, v32
	v_mov_b32_e32 v58, 1.0
	v_cvt_pk_bf16_f32 v33, v33, v34
	v_mov_b32_e32 v25, 0
	v_cvt_pk_bf16_f32 v34, v35, v38
	v_cvt_pk_bf16_f32 v35, v39, v57
	v_mov_b32_e32 v27, 0
	v_pk_mul_f32 v[38:39], v[66:67], v[56:57] op_sel_hi:[1,0]
	v_pk_mul_f32 v[36:37], v[64:65], v[56:57] op_sel_hi:[1,0]
	v_add_f32_e32 v146, v27, v25
	v_cvt_pk_bf16_f32 v24, v25, 0
	v_cvt_pk_bf16_f32 v26, v27, 0
	v_mov_b32_e32 v25, v153
	v_mov_b32_e32 v27, v153
	s_waitcnt lgkmcnt(10)
	v_mfma_f32_16x16x32_bf16 v[76:79], v[140:143], v[32:35], v[36:39]
	v_fmac_f32_e32 v146, v151, v58
	s_nop 1
	v_pk_mul_f32 v[38:39], v[102:103], v[58:59] op_sel_hi:[1,0]
	v_pk_mul_f32 v[36:37], v[100:101], v[58:59] op_sel_hi:[1,0]
	s_nop 1
	v_mfma_f32_16x16x32_bf16 v[100:103], v[140:143], v[24:27], v[36:39]
	s_nop 2
	v_mul_f32_e64 v38, v106, v56
	v_mul_f32_e64 v39, v107, v56
	v_pk_mul_f32 v[36:37], v[104:105], v[56:57] op_sel_hi:[1,0]
	s_waitcnt lgkmcnt(8)
	s_nop 0
	v_mfma_f32_16x16x32_bf16 v[104:107], v[136:139], v[32:35], v[36:39]
	s_nop 2
	v_mul_f32_e64 v38, v110, v58
	v_mul_f32_e64 v39, v111, v58
	v_pk_mul_f32 v[36:37], v[108:109], v[58:59] op_sel_hi:[1,0]
	s_nop 1
	v_mfma_f32_16x16x32_bf16 v[108:111], v[136:139], v[24:27], v[36:39]
	s_nop 2
	v_mul_f32_e64 v38, v114, v56
	v_mul_f32_e64 v39, v115, v56
	v_pk_mul_f32 v[36:37], v[112:113], v[56:57] op_sel_hi:[1,0]
	s_waitcnt lgkmcnt(6)
	s_nop 0
	v_mfma_f32_16x16x32_bf16 v[112:115], v[132:135], v[32:35], v[36:39]
	s_nop 2
	v_mul_f32_e64 v38, v118, v58
	v_mul_f32_e64 v39, v119, v58
	v_pk_mul_f32 v[36:37], v[116:117], v[58:59] op_sel_hi:[1,0]
	s_nop 1
	v_mfma_f32_16x16x32_bf16 v[116:119], v[132:135], v[24:27], v[36:39]
	s_nop 2
	v_mul_f32_e64 v38, v122, v56
	v_mul_f32_e64 v39, v123, v56
	v_pk_mul_f32 v[36:37], v[120:121], v[56:57] op_sel_hi:[1,0]
	v_add_u32_e32 v56, s76, v232
	s_waitcnt lgkmcnt(4)
	v_mfma_f32_16x16x32_bf16 v[120:123], v[128:131], v[32:35], v[36:39]
	v_mul_f32_e64 v34, v126, v58
	v_mul_f32_e64 v35, v127, v58
	v_pk_mul_f32 v[32:33], v[124:125], v[58:59] op_sel_hi:[1,0]
	v_add_u32_e32 v36, s76, v231
	s_nop 0
	v_mfma_f32_16x16x32_bf16 v[124:127], v[128:131], v[24:27], v[32:35]
	v_add_u32_e32 v24, s76, v229
	s_nop 1
	v_add_u32_e32 v32, s76, v230
	v_med3_i32 v24, v24, 0, s75
	v_med3_i32 v32, v32, 0, s75
	v_med3_i32 v36, v36, 0, s75
	v_med3_i32 v56, v56, 0, s75
	v_lshl_add_u32 v36, v36, 9, v152
	v_lshl_add_u32 v56, v56, 9, v152
	global_load_dwordx4 v[36:39], v36, s[98:99]
	global_load_dwordx4 v[92:95], v56, s[98:99]
	v_add_u32_e32 v56, s76, v233
	v_med3_i32 v56, v56, 0, s75
	v_lshl_add_u32 v24, v24, 9, v152
	v_lshl_add_u32 v32, v32, 9, v152
	v_lshl_add_u32 v56, v56, 9, v158
	global_load_dwordx4 v[24:27], v24, s[98:99]
	s_nop 0
	global_load_dwordx4 v[32:35], v32, s[98:99]
	s_nop 0
	global_load_dwordx4 v[72:75], v56, s[100:101]
	global_load_dwordx4 v[68:71], v56, s[100:101] offset:64
	v_add_u32_e32 v56, s76, v234
	v_med3_i32 v56, v56, 0, s75
	v_lshl_add_u32 v56, v56, 9, v158
	global_load_dwordx4 v[64:67], v56, s[100:101]
	s_nop 0
	global_load_dwordx4 v[56:59], v56, s[100:101] offset:64
	ds_read_b64_tr_b16 v[142:143], v169 offset:6912
	ds_read_b64_tr_b16 v[140:141], v169 offset:4608
	ds_read_b64_tr_b16 v[136:137], v169 offset:4640
	ds_read_b64_tr_b16 v[138:139], v169 offset:6944
	ds_read_b64_tr_b16 v[132:133], v169 offset:4672
	ds_read_b64_tr_b16 v[134:135], v169 offset:6976
	ds_read_b64_tr_b16 v[128:129], v169 offset:4704
	ds_read_b64_tr_b16 v[130:131], v169 offset:7008
	s_waitcnt vmcnt(15)
	ds_write_b128 v241, v[80:83]
	s_waitcnt vmcnt(14)
	ds_write_b128 v242, v[84:87]
	s_waitcnt vmcnt(13)
	ds_write_b128 v243, v[88:91]
	s_waitcnt vmcnt(12)
	ds_write_b128 v244, v[96:99]
	v_mfma_f32_16x16x32_bf16 v[80:83], v[52:55], v[4:7], 0
	v_mfma_f32_16x16x32_bf16 v[84:87], v[28:31], v[4:7], 0
	v_mfma_f32_16x16x32_bf16 v[80:83], v[44:47], v[8:11], v[80:83]
	v_mfma_f32_16x16x32_bf16 v[84:87], v[20:23], v[8:11], v[84:87]
	s_nop 5
	v_sub_u32_e32 v21, v187, v150
	v_add_u32_e32 v23, 1, v21
	v_cmp_gt_u32_e64 s[0:1], v23, v149
	v_cmp_gt_u32_e32 vcc, v21, v149
	s_nop 0
	v_cndmask_b32_e64 v81, v81, v246, s[0:1]
	s_nop 0
	v_cndmask_b32_e32 v80, v80, v246, vcc
	v_max_f32_e32 v22, v80, v81
	v_add_u32_e32 v23, 2, v21
	v_add_u32_e32 v28, 3, v21
	v_cmp_gt_u32_e64 s[22:23], v23, v149
	v_cmp_gt_u32_e64 s[24:25], v28, v149
	s_nop 0
	v_cndmask_b32_e64 v82, v82, v246, s[22:23]
	v_cndmask_b32_e64 v83, v83, v246, s[24:25]
	v_max3_f32 v22, v22, v82, v83
	v_add_u32_e32 v23, 16, v21
	v_add_u32_e32 v28, 17, v21
	v_cmp_gt_u32_e64 s[26:27], v23, v149
	v_cmp_gt_u32_e64 s[28:29], v28, v149
	s_nop 0
	v_cndmask_b32_e64 v84, v84, v246, s[26:27]
	v_cndmask_b32_e64 v85, v85, v246, s[28:29]
	v_max3_f32 v22, v22, v84, v85
	v_add_u32_e32 v23, 18, v21
	v_add_u32_e32 v21, 19, v21
	v_cmp_gt_u32_e64 s[30:31], v23, v149
	v_cmp_gt_u32_e64 s[34:35], v21, v149
	s_nop 0
	v_cndmask_b32_e64 v86, v86, v246, s[30:31]
	v_cndmask_b32_e64 v87, v87, v246, s[34:35]
	v_max3_f32 v21, v22, v86, v87
	v_mov_b32_e32 v23, v21
	s_nop 1
	v_permlane32_swap_b32_e32 v23, v21
	v_max_f32_e32 v21, v21, v23
	s_nop 1
	v_mov_b32_e32 v23, v21
	s_nop 1
	v_permlane16_swap_b32_e32 v23, v21
	v_max3_f32 v175, v144, v21, v23
	v_sub_f32_e32 v21, v144, v175
	v_exp_f32_e32 v144, v21
	v_sub_f32_e32 v21, v80, v175
	v_sub_f32_e32 v28, v81, v175
	v_exp_f32_e32 v21, v21
	v_exp_f32_e32 v28, v28
	v_sub_f32_e32 v30, v82, v175
	v_exp_f32_e32 v30, v30
	v_sub_f32_e32 v31, v83, v175
	v_exp_f32_e32 v31, v31
	v_sub_f32_e32 v45, v84, v175
	v_exp_f32_e32 v45, v45
	v_sub_f32_e32 v46, v85, v175
	v_mov_b32_e32 v176, v145
	v_exp_f32_e32 v46, v46
	v_sub_f32_e32 v47, v86, v175
	v_cvt_pk_bf16_f32 v80, v21, v28
	v_add_f32_e32 v23, v28, v21
	v_exp_f32_e32 v47, v47
	v_sub_f32_e32 v52, v87, v175
	v_mov_b32_e32 v84, 1.0
	v_add_f32_e32 v23, v30, v23
	v_exp_f32_e32 v52, v52
	v_add_f32_e32 v23, v31, v23
	v_add_f32_e32 v23, v45, v23
	v_add_f32_e32 v23, v46, v23
	v_add_f32_e32 v23, v47, v23
	v_mov_b32_e32 v21, 0
	v_add_f32_e32 v151, v52, v23
	v_mov_b32_e32 v23, 0
	v_fmac_f32_e32 v151, v147, v144
	v_cvt_pk_bf16_f32 v81, v30, v31
	v_add_f32_e32 v147, v23, v21
	v_cvt_pk_bf16_f32 v20, v21, 0
	v_cvt_pk_bf16_f32 v22, v23, 0
	v_mov_b32_e32 v21, v153
	v_mov_b32_e32 v23, v153
	v_pk_mul_f32 v[30:31], v[78:79], v[144:145] op_sel_hi:[1,0]
	v_pk_mul_f32 v[28:29], v[76:77], v[144:145] op_sel_hi:[1,0]
	v_pk_mul_f32 v[78:79], v[110:111], v[84:85] op_sel_hi:[1,0]
	v_pk_mul_f32 v[76:77], v[108:109], v[84:85] op_sel_hi:[1,0]
	v_cvt_pk_bf16_f32 v82, v45, v46
	v_cvt_pk_bf16_f32 v83, v47, v52
	s_waitcnt lgkmcnt(8)
	v_mfma_f32_16x16x32_bf16 v[88:91], v[136:139], v[20:23], v[76:79]
	v_mul_f32_e64 v46, v102, v84
	v_mul_f32_e64 v47, v103, v84
	v_pk_mul_f32 v[44:45], v[100:101], v[84:85] op_sel_hi:[1,0]
	v_pk_mul_f32 v[54:55], v[106:107], v[144:145] op_sel_hi:[1,0]
	v_pk_mul_f32 v[78:79], v[114:115], v[144:145] op_sel_hi:[1,0]
	v_pk_mul_f32 v[76:77], v[112:113], v[144:145] op_sel_hi:[1,0]
	v_pk_mul_f32 v[52:53], v[104:105], v[144:145] op_sel_hi:[1,0]
	v_mfma_f32_16x16x32_bf16 v[44:47], v[140:143], v[20:23], v[44:47]
	v_fmac_f32_e32 v147, v146, v84
	s_waitcnt lgkmcnt(6)
	v_mfma_f32_16x16x32_bf16 v[96:99], v[132:135], v[80:83], v[76:79]
	s_nop 2
	v_mul_f32_e64 v78, v118, v84
	v_mul_f32_e64 v79, v119, v84
	v_pk_mul_f32 v[76:77], v[116:117], v[84:85] op_sel_hi:[1,0]
	v_mfma_f32_16x16x32_bf16 v[28:31], v[140:143], v[80:83], v[28:31]
	s_nop 0
	v_mfma_f32_16x16x32_bf16 v[100:103], v[132:135], v[20:23], v[76:79]
	s_nop 2
	v_mul_f32_e64 v78, v122, v144
	v_mul_f32_e64 v79, v123, v144
	v_pk_mul_f32 v[76:77], v[120:121], v[144:145] op_sel_hi:[1,0]
	v_mfma_f32_16x16x32_bf16 v[52:55], v[136:139], v[80:83], v[52:55]
	s_waitcnt lgkmcnt(4)
	v_mfma_f32_16x16x32_bf16 v[104:107], v[128:131], v[80:83], v[76:79]
	s_nop 2
	v_mul_f32_e64 v78, v126, v84
	v_mul_f32_e64 v79, v127, v84
	v_pk_mul_f32 v[76:77], v[124:125], v[84:85] op_sel_hi:[1,0]
	s_nop 1
	v_mfma_f32_16x16x32_bf16 v[108:111], v[128:131], v[20:23], v[76:79]
	v_add_u32_e32 v20, s76, v235
	v_med3_i32 v20, v20, 0, s75
	v_lshl_add_u32 v20, v20, 9, v152
	global_load_dwordx4 v[112:115], v20, s[98:99]
	v_add_u32_e32 v20, s76, v236
	v_med3_i32 v20, v20, 0, s75
	v_lshl_add_u32 v20, v20, 9, v152
	global_load_dwordx4 v[116:119], v20, s[98:99]
	v_add_u32_e32 v20, s76, v237
	v_med3_i32 v20, v20, 0, s75
	v_lshl_add_u32 v20, v20, 9, v152
	global_load_dwordx4 v[120:123], v20, s[98:99]
	v_add_u32_e32 v20, s76, v238
	v_med3_i32 v20, v20, 0, s75
	v_lshl_add_u32 v20, v20, 9, v152
	global_load_dwordx4 v[124:127], v20, s[98:99]
	v_add_u32_e32 v20, s76, v239
	v_med3_i32 v20, v20, 0, s75
	v_lshl_add_u32 v20, v20, 9, v158
	global_load_dwordx4 v[84:87], v20, s[100:101]
	global_load_dwordx4 v[80:83], v20, s[100:101] offset:64
	v_add_u32_e32 v20, s76, v240
	s_addk_i32 s76, 0xfc08
	s_nop 0
	v_med3_i32 v20, v20, 0, s75
	v_lshl_add_u32 v20, v20, 9, v158
	global_load_dwordx4 v[76:79], v20, s[100:101]
	s_nop 0
	global_load_dwordx4 v[20:23], v20, s[100:101] offset:64
	ds_read_b64_tr_b16 v[142:143], v169 offset:2304
	ds_read_b64_tr_b16 v[140:141], v169
	ds_read_b64_tr_b16 v[136:137], v169 offset:32
	ds_read_b64_tr_b16 v[138:139], v169 offset:2336
	ds_read_b64_tr_b16 v[132:133], v169 offset:64
	ds_read_b64_tr_b16 v[134:135], v169 offset:2368
	ds_read_b64_tr_b16 v[128:129], v169 offset:96
	ds_read_b64_tr_b16 v[130:131], v169 offset:2400
	s_waitcnt vmcnt(13)
	ds_write_b128 v241, v[24:27] offset:4608
	s_waitcnt vmcnt(12)
	ds_write_b128 v242, v[32:35] offset:4608
	ds_write_b128 v243, v[36:39] offset:4608
	ds_write_b128 v244, v[92:95] offset:4608
	v_mfma_f32_16x16x32_bf16 v[24:27], v[48:51], v[4:7], 0
	v_mfma_f32_16x16x32_bf16 v[32:35], v[40:43], v[4:7], 0
	v_mfma_f32_16x16x32_bf16 v[24:27], v[60:63], v[8:11], v[24:27]
	v_mfma_f32_16x16x32_bf16 v[32:35], v[16:19], v[8:11], v[32:35]
	s_nop 7
	v_sub_u32_e32 v17, v192, v150
	v_add_u32_e32 v19, 1, v17
	v_cmp_gt_u32_e64 s[0:1], v19, v149
	v_cmp_gt_u32_e32 vcc, v17, v149
	s_nop 0
	v_cndmask_b32_e64 v25, v25, v246, s[0:1]
	s_nop 0
	v_cndmask_b32_e32 v24, v24, v246, vcc
	v_max_f32_e32 v18, v24, v25
	v_add_u32_e32 v19, 2, v17
	v_add_u32_e32 v37, 3, v17
	v_cmp_gt_u32_e64 s[22:23], v19, v149
	v_cmp_gt_u32_e64 s[24:25], v37, v149
	s_nop 0
	v_cndmask_b32_e64 v26, v26, v246, s[22:23]
	v_cndmask_b32_e64 v27, v27, v246, s[24:25]
	v_max3_f32 v18, v18, v26, v27
	v_add_u32_e32 v19, 16, v17
	v_add_u32_e32 v37, 17, v17
	v_cmp_gt_u32_e64 s[26:27], v19, v149
	v_cmp_gt_u32_e64 s[28:29], v37, v149
	s_nop 0
	v_cndmask_b32_e64 v32, v32, v246, s[26:27]
	v_cndmask_b32_e64 v33, v33, v246, s[28:29]
	v_max3_f32 v18, v18, v32, v33
	v_add_u32_e32 v19, 18, v17
	v_add_u32_e32 v17, 19, v17
	v_cmp_gt_u32_e64 s[30:31], v19, v149
	v_cmp_gt_u32_e64 s[34:35], v17, v149
	s_nop 0
	v_cndmask_b32_e64 v34, v34, v246, s[30:31]
	v_cndmask_b32_e64 v35, v35, v246, s[34:35]
	v_max3_f32 v17, v18, v34, v35
	v_mov_b32_e32 v19, v17
	s_nop 1
	v_permlane32_swap_b32_e32 v19, v17
	v_max_f32_e32 v17, v17, v19
	s_nop 1
	v_mov_b32_e32 v19, v17
	s_nop 1
	v_permlane16_swap_b32_e32 v19, v17
	v_max3_f32 v145, v175, v17, v19
	v_sub_f32_e32 v17, v175, v145
	v_exp_f32_e32 v38, v17
	v_sub_f32_e32 v17, v24, v145
	v_exp_f32_e32 v17, v17
	s_nop 1
	v_cndmask_b32_e64 v37, v17, 0, vcc
	v_sub_f32_e32 v17, v25, v145
	v_exp_f32_e32 v17, v17
	v_mov_b32_e32 v144, v176
	v_cndmask_b32_e64 v60, v17, 0, s[0:1]
	v_sub_f32_e32 v17, v26, v145
	v_exp_f32_e32 v17, v17
	v_cvt_pk_bf16_f32 v24, v37, v60
	v_cndmask_b32_e64 v61, v17, 0, s[22:23]
	v_sub_f32_e32 v17, v27, v145
	v_exp_f32_e32 v17, v17
	v_mov_b32_e32 v39, 0
	v_pk_mul_f32 v[30:31], v[30:31], v[38:39] op_sel_hi:[1,0]
	v_pk_mul_f32 v[28:29], v[28:29], v[38:39] op_sel_hi:[1,0]
	v_cndmask_b32_e64 v62, v17, 0, s[24:25]
	v_sub_f32_e32 v17, v32, v145
	v_exp_f32_e32 v17, v17
	v_cvt_pk_bf16_f32 v25, v61, v62
	v_cvt_pk_bf16_f32 v18, v39, 0
	v_mov_b32_e32 v19, v153
	v_cndmask_b32_e64 v63, v17, 0, s[26:27]
	v_sub_f32_e32 v17, v33, v145
	v_exp_f32_e32 v17, v17
	s_nop 0
	v_cndmask_b32_e64 v33, v17, 0, s[28:29]
	v_sub_f32_e32 v17, v34, v145
	v_exp_f32_e32 v17, v17
	v_cvt_pk_bf16_f32 v26, v63, v33
	v_cndmask_b32_e64 v34, v17, 0, s[30:31]
	v_sub_f32_e32 v17, v35, v145
	v_exp_f32_e32 v17, v17
	s_nop 0
	v_cndmask_b32_e64 v35, v17, 0, s[34:35]
	v_mov_b32_e32 v32, 1.0
	v_cvt_pk_bf16_f32 v27, v34, v35
	v_mov_b32_e32 v36, 0
	v_cvt_pk_bf16_f32 v16, v36, 0
	v_mov_b32_e32 v17, v153
	s_waitcnt lgkmcnt(10)
	v_mfma_f32_16x16x32_bf16 v[40:43], v[140:143], v[24:27], v[28:31]
	s_nop 2
	v_mul_f32_e64 v30, v46, v32
	v_mul_f32_e64 v31, v47, v32
	v_pk_mul_f32 v[28:29], v[44:45], v[32:33] op_sel_hi:[1,0]
	s_nop 1
	v_mfma_f32_16x16x32_bf16 v[44:47], v[140:143], v[16:19], v[28:31]
	s_nop 2
	v_mul_f32_e64 v30, v54, v38
	v_mul_f32_e64 v31, v55, v38
	v_pk_mul_f32 v[28:29], v[52:53], v[38:39] op_sel_hi:[1,0]
	s_waitcnt lgkmcnt(8)
	s_nop 0
	v_mfma_f32_16x16x32_bf16 v[48:51], v[136:139], v[24:27], v[28:31]
	s_nop 2
	v_mul_f32_e64 v30, v90, v32
	v_mul_f32_e64 v31, v91, v32
	v_pk_mul_f32 v[28:29], v[88:89], v[32:33] op_sel_hi:[1,0]
	s_nop 1
	v_mfma_f32_16x16x32_bf16 v[52:55], v[136:139], v[16:19], v[28:31]
	s_nop 2
	v_mul_f32_e64 v30, v98, v38
	v_mul_f32_e64 v31, v99, v38
	v_pk_mul_f32 v[28:29], v[96:97], v[38:39] op_sel_hi:[1,0]
	s_waitcnt lgkmcnt(6)
	s_nop 0
	v_mfma_f32_16x16x32_bf16 v[88:91], v[132:135], v[24:27], v[28:31]
	s_nop 2
	v_mul_f32_e64 v30, v102, v32
	v_mul_f32_e64 v31, v103, v32
	v_pk_mul_f32 v[28:29], v[100:101], v[32:33] op_sel_hi:[1,0]
	s_nop 1
	v_mfma_f32_16x16x32_bf16 v[100:103], v[132:135], v[16:19], v[28:31]
	s_nop 2
	v_mul_f32_e64 v30, v106, v38
	v_mul_f32_e64 v31, v107, v38
	v_pk_mul_f32 v[28:29], v[104:105], v[38:39] op_sel_hi:[1,0]
	s_waitcnt lgkmcnt(4)
	s_nop 0
	v_mfma_f32_16x16x32_bf16 v[104:107], v[128:131], v[24:27], v[28:31]
	v_mul_f32_e64 v26, v110, v32
	v_mul_f32_e64 v27, v111, v32
	v_pk_mul_f32 v[24:25], v[108:109], v[32:33] op_sel_hi:[1,0]
	s_nop 1
	v_mfma_f32_16x16x32_bf16 v[108:111], v[128:131], v[16:19], v[24:27]
	v_add_f32_e32 v146, v39, v36
	v_add_f32_e32 v16, v60, v37
	v_add_f32_e32 v16, v61, v16
	v_add_f32_e32 v16, v62, v16
	v_add_f32_e32 v16, v63, v16
	v_add_f32_e32 v16, v33, v16
	v_add_f32_e32 v16, v34, v16
	v_fmac_f32_e32 v146, v147, v32
	v_add_f32_e32 v147, v35, v16
	v_add_u32_e32 v16, s40, v214
	v_add_u32_e32 v24, s40, v216
	v_med3_i32 v16, v16, 0, s75
	v_med3_i32 v24, v24, 0, s75
	v_lshl_add_u32 v16, v16, 9, v152
	v_lshl_add_u32 v24, v24, 9, v152
	global_load_dwordx4 v[16:19], v16, s[98:99]
	v_or_b32_e32 v32, 0xfffffd00, v167
	global_load_dwordx4 v[60:63], v24, s[98:99]
	v_add_u32_e32 v24, s40, v218
	v_add_u32_e32 v32, s40, v32
	v_med3_i32 v24, v24, 0, s75
	v_lshl_add_u32 v24, v24, 9, v152
	global_load_dwordx4 v[92:95], v24, s[98:99]
	v_add_u32_e32 v24, s40, v220
	v_fmac_f32_e32 v147, v151, v38
	s_nop 0
	v_med3_i32 v24, v24, 0, s75
	v_lshl_add_u32 v24, v24, 9, v152
	global_load_dwordx4 v[96:99], v24, s[98:99]
	v_add_u32_e32 v24, s40, v221
	v_med3_i32 v24, v24, 0, s75
	v_med3_i32 v32, v32, 0, s75
	v_lshl_add_u32 v28, v24, 9, v158
	v_lshl_add_u32 v36, v32, 9, v158
	global_load_dwordx4 v[24:27], v28, s[100:101]
	s_nop 0
	global_load_dwordx4 v[28:31], v28, s[100:101] offset:64
	s_nop 0
	global_load_dwordx4 v[32:35], v36, s[100:101]
	s_nop 0
	global_load_dwordx4 v[36:39], v36, s[100:101] offset:64
	ds_read_b64_tr_b16 v[142:143], v169 offset:6912
	ds_read_b64_tr_b16 v[140:141], v169 offset:4608
	ds_read_b64_tr_b16 v[132:133], v169 offset:4640
	ds_read_b64_tr_b16 v[134:135], v169 offset:6944
	ds_read_b64_tr_b16 v[128:129], v169 offset:4672
	ds_read_b64_tr_b16 v[130:131], v169 offset:6976
	ds_read_b64_tr_b16 v[136:137], v169 offset:4704
	ds_read_b64_tr_b16 v[138:139], v169 offset:7008
	s_waitcnt vmcnt(15)
	ds_write_b128 v241, v[112:115]
	s_waitcnt vmcnt(14)
	ds_write_b128 v242, v[116:119]
	s_waitcnt vmcnt(13)
	ds_write_b128 v243, v[120:123]
	s_waitcnt vmcnt(12)
	ds_write_b128 v244, v[124:127]
	v_mfma_f32_16x16x32_bf16 v[112:115], v[72:75], v[4:7], 0
	v_mfma_f32_16x16x32_bf16 v[116:119], v[64:67], v[4:7], 0
	v_mfma_f32_16x16x32_bf16 v[112:115], v[68:71], v[8:11], v[112:115]
	v_mfma_f32_16x16x32_bf16 v[116:119], v[56:59], v[8:11], v[116:119]
	s_nop 5
	v_sub_u32_e32 v57, v197, v150
	v_add_u32_e32 v59, 1, v57
	v_cmp_gt_u32_e64 s[0:1], v59, v149
	v_cmp_gt_u32_e32 vcc, v57, v149
	s_nop 0
	v_cndmask_b32_e64 v113, v113, v246, s[0:1]
	s_nop 0
	v_cndmask_b32_e32 v112, v112, v246, vcc
	v_max_f32_e32 v58, v112, v113
	v_add_u32_e32 v59, 2, v57
	v_add_u32_e32 v64, 3, v57
	v_cmp_gt_u32_e64 s[22:23], v59, v149
	v_cmp_gt_u32_e64 s[24:25], v64, v149
	s_nop 0
	v_cndmask_b32_e64 v114, v114, v246, s[22:23]
	v_cndmask_b32_e64 v115, v115, v246, s[24:25]
	v_max3_f32 v58, v58, v114, v115
	v_add_u32_e32 v59, 16, v57
	v_add_u32_e32 v64, 17, v57
	v_cmp_gt_u32_e64 s[26:27], v59, v149
	v_cmp_gt_u32_e64 s[28:29], v64, v149
	s_nop 0
	v_cndmask_b32_e64 v116, v116, v246, s[26:27]
	v_cndmask_b32_e64 v117, v117, v246, s[28:29]
	v_max3_f32 v58, v58, v116, v117
	v_add_u32_e32 v59, 18, v57
	v_add_u32_e32 v57, 19, v57
	v_cmp_gt_u32_e64 s[30:31], v59, v149
	v_cmp_gt_u32_e64 s[34:35], v57, v149
	s_nop 0
	v_cndmask_b32_e64 v118, v118, v246, s[30:31]
	v_cndmask_b32_e64 v119, v119, v246, s[34:35]
	v_max3_f32 v57, v58, v118, v119
	v_mov_b32_e32 v59, v57
	s_nop 1
	v_permlane32_swap_b32_e32 v59, v57
	v_max_f32_e32 v57, v57, v59
	s_nop 1
	v_mov_b32_e32 v59, v57
	s_nop 1
	v_permlane16_swap_b32_e32 v59, v57
	v_max3_f32 v175, v145, v57, v59
	v_sub_f32_e32 v57, v145, v175
	v_exp_f32_e32 v72, v57
	v_sub_f32_e32 v57, v112, v175
	v_exp_f32_e32 v57, v57
	v_sub_f32_e32 v64, v113, v175
	v_exp_f32_e32 v64, v64
	s_nop 0
	v_sub_f32_e32 v65, v114, v175
	v_exp_f32_e32 v65, v65
	v_sub_f32_e32 v66, v115, v175
	v_exp_f32_e32 v66, v66
	v_sub_f32_e32 v67, v116, v175
	v_mov_b32_e32 v177, v144
	v_add_f32_e32 v59, v64, v57
	v_exp_f32_e32 v67, v67
	v_sub_f32_e32 v70, v117, v175
	v_cvt_pk_bf16_f32 v64, v57, v64
	v_exp_f32_e32 v70, v70
	v_sub_f32_e32 v71, v118, v175
	v_sub_f32_e32 v73, v119, v175
	v_mov_b32_e32 v74, 1.0
	v_exp_f32_e32 v71, v71
	v_exp_f32_e32 v73, v73
	v_add_f32_e32 v59, v65, v59
	v_add_f32_e32 v59, v66, v59
	v_add_f32_e32 v59, v67, v59
	v_add_f32_e32 v59, v70, v59
	v_mov_b32_e32 v57, 0
	v_add_f32_e32 v59, v71, v59
	v_cvt_pk_bf16_f32 v65, v65, v66
	v_cvt_pk_bf16_f32 v66, v67, v70
	v_cvt_pk_bf16_f32 v67, v71, v73
	v_mov_b32_e32 v56, 0
	v_pk_mul_f32 v[42:43], v[42:43], v[72:73] op_sel_hi:[1,0]
	v_pk_mul_f32 v[40:41], v[40:41], v[72:73] op_sel_hi:[1,0]
	v_add_f32_e32 v176, v73, v59
	v_add_f32_e32 v178, v56, v57
	v_cvt_pk_bf16_f32 v68, v57, 0
	v_cvt_pk_bf16_f32 v70, v56, 0
	v_mov_b32_e32 v69, v153
	v_mov_b32_e32 v71, v153
	s_waitcnt lgkmcnt(10)
	v_mfma_f32_16x16x32_bf16 v[56:59], v[140:143], v[64:67], v[40:43]
	v_fmac_f32_e32 v176, v147, v72
	v_fmac_f32_e32 v178, v146, v74
	s_nop 0
	v_pk_mul_f32 v[42:43], v[46:47], v[74:75] op_sel_hi:[1,0]
	v_pk_mul_f32 v[40:41], v[44:45], v[74:75] op_sel_hi:[1,0]
	s_nop 1
	v_mfma_f32_16x16x32_bf16 v[112:115], v[140:143], v[68:71], v[40:43]
	s_nop 2
	v_mul_f32_e64 v42, v50, v72
	v_mul_f32_e64 v43, v51, v72
	v_pk_mul_f32 v[40:41], v[48:49], v[72:73] op_sel_hi:[1,0]
	v_add_u32_e32 v48, s40, v227
	v_min_i32_e32 v49, s75, v48
	s_waitcnt lgkmcnt(8)
	v_mfma_f32_16x16x32_bf16 v[116:119], v[132:135], v[64:67], v[40:43]
	s_nop 2
	v_mul_f32_e64 v42, v54, v74
	v_mul_f32_e64 v43, v55, v74
	v_pk_mul_f32 v[40:41], v[52:53], v[74:75] op_sel_hi:[1,0]
	s_nop 1
	v_mfma_f32_16x16x32_bf16 v[120:123], v[132:135], v[68:71], v[40:43]
	s_nop 2
	v_mul_f32_e64 v42, v90, v72
	v_mul_f32_e64 v43, v91, v72
	v_pk_mul_f32 v[40:41], v[88:89], v[72:73] op_sel_hi:[1,0]
	s_waitcnt lgkmcnt(6)
	s_nop 0
	v_mfma_f32_16x16x32_bf16 v[124:127], v[128:131], v[64:67], v[40:43]
	s_nop 2
	v_mul_f32_e64 v42, v102, v74
	v_mul_f32_e64 v43, v103, v74
	v_pk_mul_f32 v[40:41], v[100:101], v[74:75] op_sel_hi:[1,0]
	s_nop 1
	v_mfma_f32_16x16x32_bf16 v[128:131], v[128:131], v[68:71], v[40:43]
	s_nop 2
	v_mul_f32_e64 v42, v106, v72
	v_mul_f32_e64 v43, v107, v72
	v_pk_mul_f32 v[40:41], v[104:105], v[72:73] op_sel_hi:[1,0]
	s_waitcnt lgkmcnt(4)
	s_nop 0
	v_mfma_f32_16x16x32_bf16 v[132:135], v[136:139], v[64:67], v[40:43]
	s_nop 2
	v_mul_f32_e64 v42, v110, v74
	v_mul_f32_e64 v43, v111, v74
	v_pk_mul_f32 v[40:41], v[108:109], v[74:75] op_sel_hi:[1,0]
	s_nop 1
	v_mfma_f32_16x16x32_bf16 v[136:139], v[136:139], v[68:71], v[40:43]
	s_nop 2
	v_add_u32_e32 v40, s40, v222
	v_med3_i32 v40, v40, 0, s75
	v_lshl_add_u32 v40, v40, 9, v152
	global_load_dwordx4 v[64:67], v40, s[98:99]
	v_add_u32_e32 v40, s40, v223
	v_med3_i32 v40, v40, 0, s75
	v_lshl_add_u32 v40, v40, 9, v152
	global_load_dwordx4 v[68:71], v40, s[98:99]
	v_add_u32_e32 v40, s40, v224
	v_med3_i32 v40, v40, 0, s75
	v_lshl_add_u32 v40, v40, 9, v152
	global_load_dwordx4 v[72:75], v40, s[98:99]
	v_add_u32_e32 v40, s40, v225
	v_med3_i32 v40, v40, 0, s75
	v_lshl_add_u32 v40, v40, 9, v152
	global_load_dwordx4 v[88:91], v40, s[98:99]
	v_add_u32_e32 v40, s40, v226
	v_med3_i32 v40, v40, 0, s75
	v_cmp_lt_i32_e32 vcc, -1, v48
	s_nop 1
	v_cndmask_b32_e32 v48, 0, v49, vcc
	v_lshl_add_u32 v44, v40, 9, v158
	v_lshl_add_u32 v52, v48, 9, v158
	global_load_dwordx4 v[40:43], v44, s[100:101]
	s_nop 0
	global_load_dwordx4 v[44:47], v44, s[100:101] offset:64
	s_nop 0
	global_load_dwordx4 v[48:51], v52, s[100:101]
	s_nop 0
	global_load_dwordx4 v[52:55], v52, s[100:101] offset:64
	ds_read_b64_tr_b16 v[102:103], v169 offset:2304
	ds_read_b64_tr_b16 v[100:101], v169
	ds_read_b64_tr_b16 v[108:109], v169 offset:32
	ds_read_b64_tr_b16 v[110:111], v169 offset:2336
	ds_read_b64_tr_b16 v[144:145], v169 offset:64
	ds_read_b64_tr_b16 v[146:147], v169 offset:2368
	ds_read_b64_tr_b16 v[140:141], v169 offset:96
	ds_read_b64_tr_b16 v[142:143], v169 offset:2400
	s_waitcnt vmcnt(15)
	ds_write_b128 v241, v[16:19] offset:4608
	s_waitcnt vmcnt(14)
	ds_write_b128 v242, v[60:63] offset:4608
	s_waitcnt vmcnt(13)
	ds_write_b128 v243, v[92:95] offset:4608
	s_waitcnt vmcnt(12)
	ds_write_b128 v244, v[96:99] offset:4608
	v_mfma_f32_16x16x32_bf16 v[16:19], v[84:87], v[4:7], 0
	v_mfma_f32_16x16x32_bf16 v[60:63], v[76:79], v[4:7], 0
	v_mfma_f32_16x16x32_bf16 v[16:19], v[80:83], v[8:11], v[16:19]
	v_mfma_f32_16x16x32_bf16 v[60:63], v[20:23], v[8:11], v[60:63]
	s_nop 5
	v_sub_u32_e32 v21, v198, v150
	v_add_u32_e32 v23, 1, v21
	v_cmp_gt_u32_e64 s[0:1], v23, v149
	v_cmp_gt_u32_e32 vcc, v21, v149
	s_nop 0
	v_cndmask_b32_e64 v17, v17, v246, s[0:1]
	s_nop 0
	v_cndmask_b32_e32 v16, v16, v246, vcc
	v_max_f32_e32 v22, v16, v17
	v_add_u32_e32 v23, 2, v21
	v_add_u32_e32 v76, 3, v21
	v_cmp_gt_u32_e64 s[22:23], v23, v149
	v_cmp_gt_u32_e64 s[24:25], v76, v149
	s_nop 0
	v_cndmask_b32_e64 v18, v18, v246, s[22:23]
	v_cndmask_b32_e64 v19, v19, v246, s[24:25]
	v_max3_f32 v22, v22, v18, v19
	v_add_u32_e32 v23, 16, v21
	v_add_u32_e32 v76, 17, v21
	v_cmp_gt_u32_e64 s[26:27], v23, v149
	v_cmp_gt_u32_e64 s[28:29], v76, v149
	s_nop 0
	v_cndmask_b32_e64 v60, v60, v246, s[26:27]
	v_cndmask_b32_e64 v61, v61, v246, s[28:29]
	v_max3_f32 v22, v22, v60, v61
	v_add_u32_e32 v23, 18, v21
	v_add_u32_e32 v21, 19, v21
	v_cmp_gt_u32_e64 s[30:31], v23, v149
	v_cmp_gt_u32_e64 s[34:35], v21, v149
	s_nop 0
	v_cndmask_b32_e64 v62, v62, v246, s[30:31]
	v_cndmask_b32_e64 v63, v63, v246, s[34:35]
	v_max3_f32 v21, v22, v62, v63
	v_mov_b32_e32 v23, v21
	s_nop 1
	v_permlane32_swap_b32_e32 v23, v21
	v_max_f32_e32 v21, v21, v23
	s_nop 1
	v_mov_b32_e32 v23, v21
	s_nop 1
	v_permlane16_swap_b32_e32 v23, v21
	v_max3_f32 v151, v175, v21, v23
	v_sub_f32_e32 v16, v16, v151
	v_exp_f32_e32 v16, v16
	v_sub_f32_e32 v17, v17, v151
	v_exp_f32_e32 v17, v17
	v_sub_f32_e32 v18, v18, v151
	v_exp_f32_e32 v18, v18
	v_sub_f32_e32 v19, v19, v151
	v_exp_f32_e32 v19, v19
	v_sub_f32_e32 v23, v60, v151
	v_sub_f32_e32 v21, v175, v151
	v_exp_f32_e32 v23, v23
	v_sub_f32_e32 v60, v61, v151
	v_exp_f32_e32 v76, v21
	v_exp_f32_e32 v60, v60
	v_sub_f32_e32 v61, v62, v151
	v_add_f32_e32 v21, v17, v16
	v_exp_f32_e32 v61, v61
	v_sub_f32_e32 v62, v63, v151
	v_add_f32_e32 v21, v18, v21
	v_exp_f32_e32 v62, v62
	v_add_f32_e32 v21, v19, v21
	v_add_f32_e32 v21, v23, v21
	v_add_f32_e32 v21, v60, v21
	v_add_f32_e32 v21, v61, v21
	v_mov_b32_e32 v175, v177
	v_add_f32_e32 v149, v62, v21
	v_cvt_pk_bf16_f32 v16, v16, v17
	v_cvt_pk_bf16_f32 v17, v18, v19
	v_cvt_pk_bf16_f32 v18, v23, v60
	v_mov_b32_e32 v60, 1.0
	v_cvt_pk_bf16_f32 v19, v61, v62
	v_mov_b32_e32 v21, 0
	v_mov_b32_e32 v23, 0
	v_pk_mul_f32 v[58:59], v[58:59], v[76:77] op_sel_hi:[1,0]
	v_pk_mul_f32 v[56:57], v[56:57], v[76:77] op_sel_hi:[1,0]
	v_add_f32_e32 v150, v23, v21
	v_cvt_pk_bf16_f32 v20, v21, 0
	v_cvt_pk_bf16_f32 v22, v23, 0
	v_mov_b32_e32 v21, v153
	v_mov_b32_e32 v23, v153
	s_waitcnt lgkmcnt(10)
	v_mfma_f32_16x16x32_bf16 v[96:99], v[100:103], v[16:19], v[56:59]
	v_fmac_f32_e32 v149, v176, v76
	v_fmac_f32_e32 v150, v178, v60
	s_min_i32 s0, s76, 0
	v_pk_mul_f32 v[58:59], v[114:115], v[60:61] op_sel_hi:[1,0]
	v_pk_mul_f32 v[56:57], v[112:113], v[60:61] op_sel_hi:[1,0]
	s_sub_i32 s0, 15, s0
	s_sub_i32 s1, s75, s76
	v_mfma_f32_16x16x32_bf16 v[100:103], v[100:103], v[20:23], v[56:59]
	s_ashr_i32 s0, s0, 4
	s_ashr_i32 s1, s1, 4
	s_cmpk_lt_i32 s71, 0x3000
	v_pk_mul_f32 v[58:59], v[118:119], v[76:77] op_sel_hi:[1,0]
	v_pk_mul_f32 v[56:57], v[116:117], v[76:77] op_sel_hi:[1,0]
	s_waitcnt lgkmcnt(8)
	s_nop 0
	v_mfma_f32_16x16x32_bf16 v[104:107], v[108:111], v[16:19], v[56:59]
	s_nop 2
	v_mul_f32_e64 v58, v122, v60
	v_mul_f32_e64 v59, v123, v60
	v_pk_mul_f32 v[56:57], v[120:121], v[60:61] op_sel_hi:[1,0]
	s_nop 1
	v_mfma_f32_16x16x32_bf16 v[108:111], v[108:111], v[20:23], v[56:59]
	s_nop 2
	v_mul_f32_e64 v58, v126, v76
	v_mul_f32_e64 v59, v127, v76
	v_pk_mul_f32 v[56:57], v[124:125], v[76:77] op_sel_hi:[1,0]
	s_waitcnt lgkmcnt(6)
	s_nop 0
	v_mfma_f32_16x16x32_bf16 v[112:115], v[144:147], v[16:19], v[56:59]
	s_nop 2
	v_mul_f32_e64 v58, v130, v60
	v_mul_f32_e64 v59, v131, v60
	v_pk_mul_f32 v[56:57], v[128:129], v[60:61] op_sel_hi:[1,0]
	s_nop 1
	v_mfma_f32_16x16x32_bf16 v[116:119], v[144:147], v[20:23], v[56:59]
	v_max_i32_e32 v145, s0, v148
	s_nop 1
	v_pk_mul_f32 v[58:59], v[134:135], v[76:77] op_sel_hi:[1,0]
	v_pk_mul_f32 v[56:57], v[132:133], v[76:77] op_sel_hi:[1,0]
	s_waitcnt lgkmcnt(4)
	s_nop 0
	v_mfma_f32_16x16x32_bf16 v[120:123], v[140:143], v[16:19], v[56:59]
	v_mul_f32_e64 v18, v138, v60
	v_mul_f32_e64 v19, v139, v60
	v_pk_mul_f32 v[16:17], v[136:137], v[60:61] op_sel_hi:[1,0]
	v_add_u32_e32 v56, s40, v228
	s_nop 0
	v_mfma_f32_16x16x32_bf16 v[124:127], v[140:143], v[20:23], v[16:19]
	s_nop 1
	s_nop 0
	v_add_u32_e32 v16, s40, v213
	v_med3_i32 v16, v16, 0, s75
	v_lshl_add_u32 v16, v16, 9, v152
	global_load_dwordx4 v[76:79], v16, s[98:99]
	v_add_u32_e32 v16, s40, v215
	v_med3_i32 v16, v16, 0, s75
	v_lshl_add_u32 v16, v16, 9, v152
	global_load_dwordx4 v[80:83], v16, s[98:99]
	v_add_u32_e32 v16, s40, v217
	v_med3_i32 v16, v16, 0, s75
	v_lshl_add_u32 v16, v16, 9, v152
	global_load_dwordx4 v[84:87], v16, s[98:99]
	v_add_u32_e32 v16, s40, v219
	v_med3_i32 v16, v16, 0, s75
	v_lshl_add_u32 v16, v16, 9, v152
	global_load_dwordx4 v[92:95], v16, s[98:99]
	v_or_b32_e32 v16, s40, v167
	v_min_i32_e32 v16, s75, v16
	v_cndmask_b32_e64 v16, v16, 0, s[38:39]
	v_med3_i32 v56, v56, 0, s75
	v_lshl_add_u32 v20, v16, 9, v158
	v_lshl_add_u32 v60, v56, 9, v158
	global_load_dwordx4 v[16:19], v20, s[100:101]
	s_nop 0
	global_load_dwordx4 v[20:23], v20, s[100:101] offset:64
	s_nop 0
	global_load_dwordx4 v[56:59], v60, s[100:101]
	s_nop 0
	global_load_dwordx4 v[60:63], v60, s[100:101] offset:64
	ds_read_b64_tr_b16 v[132:133], v169 offset:6912
	ds_read_b64_tr_b16 v[130:131], v169 offset:4608
	ds_read_b64_tr_b16 v[134:135], v169 offset:4640
	ds_read_b64_tr_b16 v[136:137], v169 offset:6944
	ds_read_b64_tr_b16 v[138:139], v169 offset:4672
	ds_read_b64_tr_b16 v[140:141], v169 offset:6976
	ds_read_b64_tr_b16 v[176:177], v169 offset:4704
	ds_read_b64_tr_b16 v[178:179], v169 offset:7008
	s_waitcnt vmcnt(15)
	ds_write_b128 v241, v[64:67]
	s_waitcnt vmcnt(14)
	ds_write_b128 v242, v[68:71]
	s_waitcnt vmcnt(13)
	ds_write_b128 v243, v[72:75]
	s_waitcnt vmcnt(12)
	ds_write_b128 v244, v[88:91]
	v_mfma_f32_16x16x32_bf16 v[24:27], v[24:27], v[12:15], 0
	v_mfma_f32_16x16x32_bf16 v[24:27], v[28:31], v[0:3], v[24:27]
	v_mfma_f32_16x16x32_bf16 v[28:31], v[32:35], v[12:15], 0
	v_add_u32_e32 v32, 0x7f8, v249
	v_ashrrev_i32_e32 v32, 4, v32
	v_min3_i32 v32, v32, s1, v248
	v_sub_u32_e32 v144, v32, v145
	v_sub_u32_e32 v33, v154, v145
	s_nop 2
	v_add_u32_e32 v35, 1, v33
	v_cmp_gt_u32_e64 s[0:1], v35, v144
	v_cmp_gt_u32_e32 vcc, v33, v144
	s_nop 0
	v_cndmask_b32_e64 v25, v25, v246, s[0:1]
	s_nop 0
	v_cndmask_b32_e32 v24, v24, v246, vcc
	v_mfma_f32_16x16x32_bf16 v[28:31], v[36:39], v[0:3], v[28:31]
	v_max_f32_e32 v34, v24, v25
	v_add_u32_e32 v35, 2, v33
	v_add_u32_e32 v36, 3, v33
	v_cmp_gt_u32_e64 s[22:23], v35, v144
	v_cmp_gt_u32_e64 s[24:25], v36, v144
	s_nop 0
	v_cndmask_b32_e64 v26, v26, v246, s[22:23]
	v_cndmask_b32_e64 v27, v27, v246, s[24:25]
	v_max3_f32 v34, v34, v26, v27
	v_add_u32_e32 v35, 16, v33
	v_add_u32_e32 v36, 17, v33
	v_cmp_gt_u32_e64 s[26:27], v35, v144
	v_cmp_gt_u32_e64 s[28:29], v36, v144
	s_nop 0
	v_cndmask_b32_e64 v28, v28, v246, s[26:27]
	v_cndmask_b32_e64 v29, v29, v246, s[28:29]
	v_max3_f32 v34, v34, v28, v29
	v_add_u32_e32 v35, 18, v33
	v_add_u32_e32 v33, 19, v33
	v_cmp_gt_u32_e64 s[30:31], v35, v144
	v_cmp_gt_u32_e64 s[34:35], v33, v144
	s_nop 0
	v_cndmask_b32_e64 v30, v30, v246, s[30:31]
	v_cndmask_b32_e64 v31, v31, v246, s[34:35]
	v_max3_f32 v33, v34, v30, v31
	s_nop 1
	v_mov_b32_e32 v34, v33
	s_nop 1
	v_permlane32_swap_b32_e32 v34, v33
	v_max_f32_e32 v33, v33, v34
	s_nop 1
	v_mov_b32_e32 v34, v33
	s_nop 1
	v_permlane16_swap_b32_e32 v34, v33
	v_max3_f32 v128, v175, v33, v34
	v_sub_f32_e32 v24, v24, v128
	v_exp_f32_e32 v24, v24
	v_sub_f32_e32 v37, v175, v128
	v_exp_f32_e32 v38, v37
	v_mov_b32_e32 v129, v151
	v_cndmask_b32_e64 v37, v24, 0, vcc
	v_sub_f32_e32 v24, v25, v128
	v_exp_f32_e32 v24, v24
	v_mov_b32_e32 v36, 1.0
	v_cndmask_b32_e64 v65, v24, 0, s[0:1]
	v_sub_f32_e32 v24, v26, v128
	v_exp_f32_e32 v24, v24
	v_mov_b32_e32 v33, v153
	v_mov_b32_e32 v35, v153
	v_mov_b32_e32 v39, 0
	v_cndmask_b32_e64 v66, v24, 0, s[22:23]
	v_sub_f32_e32 v24, v27, v128
	v_exp_f32_e32 v24, v24
	s_nop 0
	v_cndmask_b32_e64 v67, v24, 0, s[24:25]
	v_sub_f32_e32 v24, v28, v128
	v_exp_f32_e32 v24, v24
	v_mov_b32_e32 v64, 0
	v_cvt_pk_bf16_f32 v32, v39, 0
	v_cvt_pk_bf16_f32 v34, v64, 0
	v_cndmask_b32_e64 v68, v24, 0, s[26:27]
	v_sub_f32_e32 v24, v29, v128
	v_exp_f32_e32 v24, v24
	v_pk_mul_f32 v[28:29], v[96:97], v[36:37] op_sel_hi:[1,0]
	v_cvt_pk_bf16_f32 v25, v66, v67
	v_cndmask_b32_e64 v69, v24, 0, s[28:29]
	v_sub_f32_e32 v24, v30, v128
	v_exp_f32_e32 v24, v24
	v_cvt_pk_bf16_f32 v26, v68, v69
	v_cndmask_b32_e64 v70, v24, 0, s[30:31]
	v_sub_f32_e32 v24, v31, v128
	v_exp_f32_e32 v24, v24
	v_pk_mul_f32 v[30:31], v[98:99], v[36:37] op_sel_hi:[1,0]
	v_cndmask_b32_e64 v71, v24, 0, s[34:35]
	v_cvt_pk_bf16_f32 v24, v37, v65
	v_cvt_pk_bf16_f32 v27, v70, v71
	s_waitcnt lgkmcnt(10)
	v_mfma_f32_16x16x32_bf16 v[96:99], v[130:133], v[32:35], v[28:31]
	s_nop 2
	v_mul_f32_e64 v30, v102, v38
	v_mul_f32_e64 v31, v103, v38
	v_pk_mul_f32 v[28:29], v[100:101], v[38:39] op_sel_hi:[1,0]
	s_nop 1
	v_mfma_f32_16x16x32_bf16 v[100:103], v[130:133], v[24:27], v[28:31]
	s_nop 2
	v_mul_f32_e64 v30, v106, v36
	v_mul_f32_e64 v31, v107, v36
	v_pk_mul_f32 v[28:29], v[104:105], v[36:37] op_sel_hi:[1,0]
	s_waitcnt lgkmcnt(8)
	s_nop 0
	v_mfma_f32_16x16x32_bf16 v[104:107], v[134:137], v[32:35], v[28:31]
	s_nop 2
	v_mul_f32_e64 v30, v110, v38
	v_mul_f32_e64 v31, v111, v38
	v_pk_mul_f32 v[28:29], v[108:109], v[38:39] op_sel_hi:[1,0]
	s_nop 1
	v_mfma_f32_16x16x32_bf16 v[108:111], v[134:137], v[24:27], v[28:31]
	s_nop 2
	v_mul_f32_e64 v30, v114, v36
	v_mul_f32_e64 v31, v115, v36
	v_pk_mul_f32 v[28:29], v[112:113], v[36:37] op_sel_hi:[1,0]
	s_waitcnt lgkmcnt(6)
	s_nop 0
	v_mfma_f32_16x16x32_bf16 v[112:115], v[138:141], v[32:35], v[28:31]
	s_nop 2
	v_mul_f32_e64 v30, v118, v38
	v_mul_f32_e64 v31, v119, v38
	v_pk_mul_f32 v[28:29], v[116:117], v[38:39] op_sel_hi:[1,0]
	s_nop 1
	v_mfma_f32_16x16x32_bf16 v[116:119], v[138:141], v[24:27], v[28:31]
	s_nop 2
	v_mul_f32_e64 v30, v122, v36
	v_mul_f32_e64 v31, v123, v36
	v_pk_mul_f32 v[28:29], v[120:121], v[36:37] op_sel_hi:[1,0]
	s_waitcnt lgkmcnt(4)
	s_nop 0
	v_mfma_f32_16x16x32_bf16 v[120:123], v[176:179], v[32:35], v[28:31]
	v_add_u32_e32 v32, s40, v234
	s_nop 0
	s_nop 0
	v_pk_mul_f32 v[30:31], v[126:127], v[38:39] op_sel_hi:[1,0]
	v_pk_mul_f32 v[28:29], v[124:125], v[38:39] op_sel_hi:[1,0]
	s_nop 1
	v_mfma_f32_16x16x32_bf16 v[124:127], v[176:179], v[24:27], v[28:31]
	v_add_f32_e32 v24, v65, v37
	v_add_f32_e32 v24, v66, v24
	v_add_f32_e32 v24, v67, v24
	v_add_f32_e32 v24, v68, v24
	v_add_f32_e32 v24, v69, v24
	v_add_f32_e32 v24, v70, v24
	v_add_f32_e32 v130, v71, v24
	v_add_f32_e32 v131, v64, v39
	v_add_u32_e32 v24, s40, v229
	v_fmac_f32_e32 v131, v149, v36
	v_fmac_f32_e32 v130, v150, v38
	v_med3_i32 v24, v24, 0, s75
	v_lshl_add_u32 v24, v24, 9, v152
	global_load_dwordx4 v[64:67], v24, s[98:99]
	v_add_u32_e32 v24, s40, v230
	v_med3_i32 v24, v24, 0, s75
	v_lshl_add_u32 v24, v24, 9, v152
	global_load_dwordx4 v[68:71], v24, s[98:99]
	v_add_u32_e32 v24, s40, v231
	v_med3_i32 v24, v24, 0, s75
	v_lshl_add_u32 v24, v24, 9, v152
	global_load_dwordx4 v[72:75], v24, s[98:99]
	v_add_u32_e32 v24, s40, v232
	v_med3_i32 v24, v24, 0, s75
	v_lshl_add_u32 v24, v24, 9, v152
	global_load_dwordx4 v[88:91], v24, s[98:99]
	v_add_u32_e32 v24, s40, v233
	v_med3_i32 v24, v24, 0, s75
	v_med3_i32 v32, v32, 0, s75
	v_lshl_add_u32 v28, v24, 9, v158
	v_lshl_add_u32 v36, v32, 9, v158
	global_load_dwordx4 v[24:27], v28, s[100:101]
	s_nop 0
	global_load_dwordx4 v[28:31], v28, s[100:101] offset:64
	s_nop 0
	global_load_dwordx4 v[32:35], v36, s[100:101]
	s_nop 0
	global_load_dwordx4 v[36:39], v36, s[100:101] offset:64
	ds_read_b64_tr_b16 v[134:135], v169 offset:2304
	ds_read_b64_tr_b16 v[132:133], v169
	ds_read_b64_tr_b16 v[136:137], v169 offset:32
	ds_read_b64_tr_b16 v[138:139], v169 offset:2336
	ds_read_b64_tr_b16 v[140:141], v169 offset:64
	ds_read_b64_tr_b16 v[142:143], v169 offset:2368
	ds_read_b64_tr_b16 v[176:177], v169 offset:96
	ds_read_b64_tr_b16 v[178:179], v169 offset:2400
	s_waitcnt vmcnt(15)
	ds_write_b128 v241, v[76:79] offset:4608
	s_waitcnt vmcnt(14)
	ds_write_b128 v242, v[80:83] offset:4608
	s_waitcnt vmcnt(13)
	ds_write_b128 v243, v[84:87] offset:4608
	s_waitcnt vmcnt(12)
	ds_write_b128 v244, v[92:95] offset:4608
	v_mfma_f32_16x16x32_bf16 v[40:43], v[40:43], v[12:15], 0
	s_nop 5
	v_mov_b32_e32 v77, v153
	v_mfma_f32_16x16x32_bf16 v[40:43], v[44:47], v[0:3], v[40:43]
	v_mfma_f32_16x16x32_bf16 v[44:47], v[48:51], v[12:15], 0
	v_sub_u32_e32 v48, v187, v145
	s_nop 1
	v_add_u32_e32 v51, 1, v48
	v_cmp_gt_u32_e64 s[0:1], v51, v144
	v_cmp_gt_u32_e32 vcc, v48, v144
	s_nop 0
	v_cndmask_b32_e64 v41, v41, v246, s[0:1]
	s_nop 0
	v_cndmask_b32_e32 v40, v40, v246, vcc
	v_mfma_f32_16x16x32_bf16 v[44:47], v[52:55], v[0:3], v[44:47]
	v_max_f32_e32 v50, v40, v41
	v_add_u32_e32 v51, 2, v48
	v_add_u32_e32 v52, 3, v48
	v_cmp_gt_u32_e64 s[22:23], v51, v144
	v_cmp_gt_u32_e64 s[24:25], v52, v144
	v_mov_b32_e32 v79, v153
	v_cndmask_b32_e64 v42, v42, v246, s[22:23]
	v_cndmask_b32_e64 v43, v43, v246, s[24:25]
	v_max3_f32 v50, v50, v42, v43
	v_add_u32_e32 v51, 16, v48
	v_add_u32_e32 v52, 17, v48
	v_cmp_gt_u32_e64 s[26:27], v51, v144
	v_cmp_gt_u32_e64 s[28:29], v52, v144
	s_nop 0
	v_cndmask_b32_e64 v44, v44, v246, s[26:27]
	v_cndmask_b32_e64 v45, v45, v246, s[28:29]
	v_max3_f32 v50, v50, v44, v45
	v_add_u32_e32 v51, 18, v48
	v_add_u32_e32 v48, 19, v48
	v_cmp_gt_u32_e64 s[30:31], v51, v144
	v_cmp_gt_u32_e64 s[34:35], v48, v144
	s_nop 0
	v_cndmask_b32_e64 v46, v46, v246, s[30:31]
	v_cndmask_b32_e64 v47, v47, v246, s[34:35]
	v_max3_f32 v48, v50, v46, v47
	s_nop 1
	v_mov_b32_e32 v50, v48
	s_nop 1
	v_permlane32_swap_b32_e32 v50, v48
	v_max_f32_e32 v48, v48, v50
	s_nop 1
	v_mov_b32_e32 v50, v48
	s_nop 1
	v_permlane16_swap_b32_e32 v50, v48
	v_max3_f32 v148, v128, v48, v50
	v_sub_f32_e32 v40, v40, v148
	v_exp_f32_e32 v40, v40
	v_sub_f32_e32 v41, v41, v148
	v_exp_f32_e32 v41, v41
	v_sub_f32_e32 v42, v42, v148
	v_exp_f32_e32 v42, v42
	v_sub_f32_e32 v43, v43, v148
	v_exp_f32_e32 v43, v43
	v_sub_f32_e32 v44, v44, v148
	v_mov_b32_e32 v146, v129
	v_sub_f32_e32 v48, v128, v148
	v_exp_f32_e32 v44, v44
	v_sub_f32_e32 v45, v45, v148
	v_exp_f32_e32 v86, v48
	v_exp_f32_e32 v45, v45
	v_sub_f32_e32 v46, v46, v148
	v_sub_f32_e32 v47, v47, v148
	v_mov_b32_e32 v84, 1.0
	v_add_f32_e32 v48, v41, v40
	v_exp_f32_e32 v46, v46
	v_exp_f32_e32 v47, v47
	v_add_f32_e32 v48, v42, v48
	v_add_f32_e32 v48, v43, v48
	v_add_f32_e32 v48, v44, v48
	v_add_f32_e32 v48, v45, v48
	v_mov_b32_e32 v49, 0
	v_mov_b32_e32 v51, 0
	v_add_f32_e32 v48, v46, v48
	v_cvt_pk_bf16_f32 v40, v40, v41
	v_cvt_pk_bf16_f32 v41, v42, v43
	v_cvt_pk_bf16_f32 v42, v44, v45
	v_cvt_pk_bf16_f32 v43, v46, v47
	v_pk_mul_f32 v[82:83], v[110:111], v[86:87] op_sel_hi:[1,0]
	v_pk_mul_f32 v[80:81], v[108:109], v[86:87] op_sel_hi:[1,0]
	v_cvt_pk_bf16_f32 v76, v49, 0
	v_cvt_pk_bf16_f32 v78, v51, 0
	v_add_f32_e32 v149, v47, v48
	v_pk_mul_f32 v[46:47], v[98:99], v[84:85] op_sel_hi:[1,0]
	v_pk_mul_f32 v[44:45], v[96:97], v[84:85] op_sel_hi:[1,0]
	s_waitcnt lgkmcnt(8)
	v_mfma_f32_16x16x32_bf16 v[96:99], v[136:139], v[40:43], v[80:83]
	v_add_f32_e32 v147, v51, v49
	v_pk_mul_f32 v[50:51], v[102:103], v[86:87] op_sel_hi:[1,0]
	v_pk_mul_f32 v[48:49], v[100:101], v[86:87] op_sel_hi:[1,0]
	v_pk_mul_f32 v[82:83], v[114:115], v[84:85] op_sel_hi:[1,0]
	v_pk_mul_f32 v[80:81], v[112:113], v[84:85] op_sel_hi:[1,0]
	v_pk_mul_f32 v[54:55], v[106:107], v[84:85] op_sel_hi:[1,0]
	v_pk_mul_f32 v[52:53], v[104:105], v[84:85] op_sel_hi:[1,0]
	s_waitcnt lgkmcnt(6)
	v_mfma_f32_16x16x32_bf16 v[100:103], v[140:143], v[76:79], v[80:83]
	v_fmac_f32_e32 v147, v131, v84
	v_fmac_f32_e32 v149, v130, v86
	s_nop 0
	v_pk_mul_f32 v[82:83], v[118:119], v[86:87] op_sel_hi:[1,0]
	v_pk_mul_f32 v[80:81], v[116:117], v[86:87] op_sel_hi:[1,0]
	v_mfma_f32_16x16x32_bf16 v[44:47], v[132:135], v[76:79], v[44:47]
	s_nop 0
	v_mfma_f32_16x16x32_bf16 v[104:107], v[140:143], v[40:43], v[80:83]
	s_nop 2
	v_mul_f32_e64 v82, v122, v84
	v_mul_f32_e64 v83, v123, v84
	v_pk_mul_f32 v[80:81], v[120:121], v[84:85] op_sel_hi:[1,0]
	v_mfma_f32_16x16x32_bf16 v[52:55], v[136:139], v[76:79], v[52:55]
	v_add_u32_e32 v84, s40, v240
	s_waitcnt lgkmcnt(4)
	v_mfma_f32_16x16x32_bf16 v[108:111], v[176:179], v[76:79], v[80:83]
	v_mul_f32_e64 v78, v126, v86
	v_mul_f32_e64 v79, v127, v86
	v_pk_mul_f32 v[76:77], v[124:125], v[86:87] op_sel_hi:[1,0]
	v_mfma_f32_16x16x32_bf16 v[48:51], v[132:135], v[40:43], v[48:51]
	s_nop 0
	v_mfma_f32_16x16x32_bf16 v[112:115], v[176:179], v[40:43], v[76:79]
	v_add_u32_e32 v40, s40, v235
	s_nop 1
	v_add_u32_e32 v76, s40, v236
	v_med3_i32 v40, v40, 0, s75
	v_med3_i32 v76, v76, 0, s75
	v_lshl_add_u32 v40, v40, 9, v152
	v_lshl_add_u32 v76, v76, 9, v152
	global_load_dwordx4 v[40:43], v40, s[98:99]
	s_nop 0
	global_load_dwordx4 v[116:119], v76, s[98:99]
	v_add_u32_e32 v76, s40, v237
	v_med3_i32 v76, v76, 0, s75
	v_lshl_add_u32 v76, v76, 9, v152
	global_load_dwordx4 v[120:123], v76, s[98:99]
	v_add_u32_e32 v76, s40, v238
	v_med3_i32 v76, v76, 0, s75
	v_lshl_add_u32 v76, v76, 9, v152
	global_load_dwordx4 v[124:127], v76, s[98:99]
	v_add_u32_e32 v76, s40, v239
	v_med3_i32 v76, v76, 0, s75
	v_med3_i32 v84, v84, 0, s75
	v_lshl_add_u32 v80, v76, 9, v158
	v_lshl_add_u32 v84, v84, 9, v158
	global_load_dwordx4 v[76:79], v80, s[100:101]
	s_nop 0
	global_load_dwordx4 v[80:83], v80, s[100:101] offset:64
	s_nop 0
	global_load_dwordx4 v[92:95], v84, s[100:101]
	s_nop 0
	global_load_dwordx4 v[84:87], v84, s[100:101] offset:64
	ds_read_b64_tr_b16 v[142:143], v169 offset:6912
	ds_read_b64_tr_b16 v[140:141], v169 offset:4608
	ds_read_b64_tr_b16 v[136:137], v169 offset:4640
	ds_read_b64_tr_b16 v[138:139], v169 offset:6944
	ds_read_b64_tr_b16 v[132:133], v169 offset:4672
	ds_read_b64_tr_b16 v[134:135], v169 offset:6976
	ds_read_b64_tr_b16 v[128:129], v169 offset:4704
	ds_read_b64_tr_b16 v[130:131], v169 offset:7008
	s_waitcnt vmcnt(15)
	ds_write_b128 v241, v[64:67]
	s_waitcnt vmcnt(14)
	ds_write_b128 v242, v[68:71]
	s_waitcnt vmcnt(13)
	ds_write_b128 v243, v[72:75]
	s_waitcnt vmcnt(12)
	ds_write_b128 v244, v[88:91]
	v_mfma_f32_16x16x32_bf16 v[16:19], v[16:19], v[12:15], 0
	v_mfma_f32_16x16x32_bf16 v[16:19], v[20:23], v[0:3], v[16:19]
	v_mfma_f32_16x16x32_bf16 v[20:23], v[56:59], v[12:15], 0
	s_nop 2
	v_sub_u32_e32 v56, v192, v145
	v_add_u32_e32 v59, 1, v56
	v_cmp_gt_u32_e64 s[0:1], v59, v144
	v_cmp_gt_u32_e32 vcc, v56, v144
	s_nop 0
	v_cndmask_b32_e64 v17, v17, v246, s[0:1]
	s_nop 0
	v_cndmask_b32_e32 v16, v16, v246, vcc
	v_mfma_f32_16x16x32_bf16 v[20:23], v[60:63], v[0:3], v[20:23]
	v_max_f32_e32 v58, v16, v17
	v_add_u32_e32 v59, 2, v56
	v_add_u32_e32 v60, 3, v56
	v_cmp_gt_u32_e64 s[22:23], v59, v144
	v_cmp_gt_u32_e64 s[24:25], v60, v144
	v_mov_b32_e32 v61, v153
	v_cndmask_b32_e64 v18, v18, v246, s[22:23]
	v_cndmask_b32_e64 v19, v19, v246, s[24:25]
	v_max3_f32 v58, v58, v18, v19
	v_add_u32_e32 v59, 16, v56
	v_add_u32_e32 v60, 17, v56
	v_cmp_gt_u32_e64 s[26:27], v59, v144
	v_cmp_gt_u32_e64 s[28:29], v60, v144
	v_mov_b32_e32 v63, v153
	v_cndmask_b32_e64 v20, v20, v246, s[26:27]
	v_cndmask_b32_e64 v60, v21, v246, s[28:29]
	v_max3_f32 v58, v58, v20, v60
	v_add_u32_e32 v59, 18, v56
	v_add_u32_e32 v56, 19, v56
	v_cmp_gt_u32_e64 s[30:31], v59, v144
	v_cmp_gt_u32_e64 s[34:35], v56, v144
	s_nop 0
	v_cndmask_b32_e64 v22, v22, v246, s[30:31]
	v_cndmask_b32_e64 v23, v23, v246, s[34:35]
	v_max3_f32 v56, v58, v22, v23
	s_nop 1
	v_mov_b32_e32 v58, v56
	s_nop 1
	v_permlane32_swap_b32_e32 v58, v56
	v_max_f32_e32 v56, v56, v58
	s_nop 1
	v_mov_b32_e32 v58, v56
	s_nop 1
	v_permlane16_swap_b32_e32 v58, v56
	v_max3_f32 v151, v148, v56, v58
	v_sub_f32_e32 v16, v16, v151
	v_exp_f32_e32 v16, v16
	v_sub_f32_e32 v17, v17, v151
	v_mov_b32_e32 v150, v146
	v_exp_f32_e32 v17, v17
	v_sub_f32_e32 v18, v18, v151
	v_exp_f32_e32 v18, v18
	v_sub_f32_e32 v19, v19, v151
	v_mov_b32_e32 v68, 1.0
	v_exp_f32_e32 v19, v19
	v_sub_f32_e32 v20, v20, v151
	v_sub_f32_e32 v56, v148, v151
	v_exp_f32_e32 v20, v20
	v_sub_f32_e32 v21, v21, v151
	v_exp_f32_e32 v72, v56
	v_exp_f32_e32 v21, v21
	v_sub_f32_e32 v22, v22, v151
	v_add_f32_e32 v56, v17, v16
	v_exp_f32_e32 v22, v22
	v_sub_f32_e32 v23, v23, v151
	v_add_f32_e32 v56, v18, v56
	v_exp_f32_e32 v23, v23
	v_mov_b32_e32 v57, 0
	v_add_f32_e32 v56, v19, v56
	v_mov_b32_e32 v59, 0
	v_add_f32_e32 v56, v20, v56
	v_cndmask_b32_e64 v21, v21, 0, s[28:29]
	v_add_f32_e32 v146, v59, v57
	v_add_f32_e32 v56, v21, v56
	v_fmac_f32_e32 v146, v147, v68
	v_cvt_pk_bf16_f32 v60, v57, 0
	v_cvt_pk_bf16_f32 v62, v59, 0
	v_add_f32_e32 v56, v22, v56
	v_cvt_pk_bf16_f32 v64, v16, v17
	v_cvt_pk_bf16_f32 v65, v18, v19
	v_pk_mul_f32 v[18:19], v[46:47], v[68:69] op_sel_hi:[1,0]
	v_pk_mul_f32 v[16:17], v[44:45], v[68:69] op_sel_hi:[1,0]
	v_pk_mul_f32 v[46:47], v[54:55], v[68:69] op_sel_hi:[1,0]
	v_pk_mul_f32 v[44:45], v[52:53], v[68:69] op_sel_hi:[1,0]
	v_pk_mul_f32 v[54:55], v[102:103], v[68:69] op_sel_hi:[1,0]
	v_pk_mul_f32 v[52:53], v[100:101], v[68:69] op_sel_hi:[1,0]
	v_pk_mul_f32 v[70:71], v[110:111], v[68:69] op_sel_hi:[1,0]
	v_pk_mul_f32 v[68:69], v[108:109], v[68:69] op_sel_hi:[1,0]
	v_add_f32_e32 v147, v23, v56
	v_cvt_pk_bf16_f32 v66, v20, v21
	v_cvt_pk_bf16_f32 v67, v22, v23
	s_waitcnt lgkmcnt(10)
	v_mfma_f32_16x16x32_bf16 v[16:19], v[140:143], v[60:63], v[16:19]
	v_mul_f32_e64 v22, v50, v72
	v_mul_f32_e64 v23, v51, v72
	v_pk_mul_f32 v[20:21], v[48:49], v[72:73] op_sel_hi:[1,0]
	v_pk_mul_f32 v[50:51], v[98:99], v[72:73] op_sel_hi:[1,0]
	s_waitcnt lgkmcnt(8)
	v_mfma_f32_16x16x32_bf16 v[44:47], v[136:139], v[60:63], v[44:47]
	v_mul_f32_e64 v48, v96, v72
	v_mul_f32_e64 v49, v97, v72
	v_pk_mul_f32 v[58:59], v[106:107], v[72:73] op_sel_hi:[1,0]
	v_pk_mul_f32 v[56:57], v[104:105], v[72:73] op_sel_hi:[1,0]
	s_waitcnt lgkmcnt(6)
	v_mfma_f32_16x16x32_bf16 v[52:55], v[132:135], v[60:63], v[52:55]
	v_fmac_f32_e32 v147, v149, v72
	s_waitcnt lgkmcnt(4)
	v_mfma_f32_16x16x32_bf16 v[60:63], v[128:131], v[60:63], v[68:71]
	s_nop 2
	v_mul_f32_e64 v70, v114, v72
	v_mul_f32_e64 v71, v115, v72
	v_pk_mul_f32 v[68:69], v[112:113], v[72:73] op_sel_hi:[1,0]
	v_mfma_f32_16x16x32_bf16 v[20:23], v[140:143], v[64:67], v[20:23]
	v_mfma_f32_16x16x32_bf16 v[48:51], v[136:139], v[64:67], v[48:51]
	v_mfma_f32_16x16x32_bf16 v[56:59], v[132:135], v[64:67], v[56:59]
	v_mfma_f32_16x16x32_bf16 v[64:67], v[128:131], v[64:67], v[68:71]
	ds_read_b64_tr_b16 v[98:99], v169 offset:2304
	ds_read_b64_tr_b16 v[96:97], v169
	ds_read_b64_tr_b16 v[88:89], v169 offset:32
	ds_read_b64_tr_b16 v[90:91], v169 offset:2336
	ds_read_b64_tr_b16 v[72:73], v169 offset:64
	ds_read_b64_tr_b16 v[74:75], v169 offset:2368
	ds_read_b64_tr_b16 v[68:69], v169 offset:96
	ds_read_b64_tr_b16 v[70:71], v169 offset:2400
	s_waitcnt vmcnt(7)
	ds_write_b128 v241, v[40:43] offset:4608
	s_waitcnt vmcnt(6)
	ds_write_b128 v242, v[116:119] offset:4608
	s_waitcnt vmcnt(5)
	ds_write_b128 v243, v[120:123] offset:4608
	s_waitcnt vmcnt(4)
	ds_write_b128 v244, v[124:127] offset:4608
	v_mfma_f32_16x16x32_bf16 v[24:27], v[24:27], v[12:15], 0
	v_mfma_f32_16x16x32_bf16 v[24:27], v[28:31], v[0:3], v[24:27]
	s_nop 5
	v_mov_b32_e32 v41, v153
	v_mov_b32_e32 v43, v153
	v_mfma_f32_16x16x32_bf16 v[28:31], v[32:35], v[12:15], 0
	v_sub_u32_e32 v32, v197, v145
	v_add_u32_e32 v35, 1, v32
	v_cmp_gt_u32_e64 s[0:1], v35, v144
	v_cmp_gt_u32_e32 vcc, v32, v144
	s_nop 0
	v_cndmask_b32_e64 v25, v25, v246, s[0:1]
	s_nop 0
	v_cndmask_b32_e32 v24, v24, v246, vcc
	v_mfma_f32_16x16x32_bf16 v[28:31], v[36:39], v[0:3], v[28:31]
	v_max_f32_e32 v34, v24, v25
	v_add_u32_e32 v35, 2, v32
	v_add_u32_e32 v36, 3, v32
	v_cmp_gt_u32_e64 s[22:23], v35, v144
	v_cmp_gt_u32_e64 s[24:25], v36, v144
	s_nop 0
	v_cndmask_b32_e64 v26, v26, v246, s[22:23]
	v_cndmask_b32_e64 v27, v27, v246, s[24:25]
	v_max3_f32 v34, v34, v26, v27
	v_add_u32_e32 v35, 16, v32
	v_add_u32_e32 v36, 17, v32
	v_cmp_gt_u32_e64 s[26:27], v35, v144
	v_cmp_gt_u32_e64 s[28:29], v36, v144
	s_nop 0
	v_cndmask_b32_e64 v28, v28, v246, s[26:27]
	v_cndmask_b32_e64 v29, v29, v246, s[28:29]
	v_max3_f32 v34, v34, v28, v29
	v_add_u32_e32 v35, 18, v32
	v_add_u32_e32 v32, 19, v32
	v_cmp_gt_u32_e64 s[30:31], v35, v144
	v_cmp_gt_u32_e64 s[34:35], v32, v144
	s_nop 0
	v_cndmask_b32_e64 v30, v30, v246, s[30:31]
	v_cndmask_b32_e64 v31, v31, v246, s[34:35]
	v_max3_f32 v32, v34, v30, v31
	s_nop 1
	v_mov_b32_e32 v34, v32
	s_nop 1
	v_permlane32_swap_b32_e32 v34, v32
	v_max_f32_e32 v32, v32, v34
	s_nop 1
	v_mov_b32_e32 v101, v150
	v_mov_b32_e32 v106, 1.0
	v_mov_b32_e32 v34, v32
	s_nop 0
	s_nop 0
	v_permlane16_swap_b32_e32 v34, v32
	v_mov_b32_e32 v107, 0
	v_max3_f32 v100, v151, v32, v34
	v_sub_f32_e32 v24, v24, v100
	v_exp_f32_e32 v24, v24
	v_sub_f32_e32 v32, v151, v100
	v_exp_f32_e32 v108, v32
	v_cndmask_b32_e64 v110, v24, 0, vcc
	v_sub_f32_e32 v24, v25, v100
	v_exp_f32_e32 v24, v24
	v_mov_b32_e32 v109, 0
	v_cvt_pk_bf16_f32 v40, v107, 0
	v_cvt_pk_bf16_f32 v42, v109, 0
	v_cndmask_b32_e64 v111, v24, 0, s[0:1]
	v_sub_f32_e32 v24, v26, v100
	v_exp_f32_e32 v24, v24
	v_pk_mul_f32 v[18:19], v[18:19], v[106:107] op_sel_hi:[1,0]
	v_pk_mul_f32 v[16:17], v[16:17], v[106:107] op_sel_hi:[1,0]
	v_pk_mul_f32 v[34:35], v[54:55], v[106:107] op_sel_hi:[1,0]
	v_cndmask_b32_e64 v112, v24, 0, s[22:23]
	v_sub_f32_e32 v24, v27, v100
	v_exp_f32_e32 v24, v24
	v_pk_mul_f32 v[26:27], v[46:47], v[106:107] op_sel_hi:[1,0]
	v_pk_mul_f32 v[32:33], v[52:53], v[106:107] op_sel_hi:[1,0]
	v_pk_mul_f32 v[46:47], v[62:63], v[106:107] op_sel_hi:[1,0]
	v_cndmask_b32_e64 v113, v24, 0, s[24:25]
	v_sub_f32_e32 v24, v28, v100
	v_exp_f32_e32 v24, v24
	s_waitcnt lgkmcnt(10)
	v_mfma_f32_16x16x32_bf16 v[16:19], v[96:99], v[40:43], v[16:19]
	v_cvt_pk_bf16_f32 v102, v110, v111
	v_cvt_pk_bf16_f32 v103, v112, v113
	v_cndmask_b32_e64 v114, v24, 0, s[26:27]
	v_sub_f32_e32 v24, v29, v100
	v_exp_f32_e32 v24, v24
	s_waitcnt lgkmcnt(6)
	v_mfma_f32_16x16x32_bf16 v[32:35], v[72:75], v[40:43], v[32:35]
	v_mul_f32_e64 v28, v48, v108
	v_mul_f32_e64 v29, v49, v108
	v_cndmask_b32_e64 v115, v24, 0, s[28:29]
	v_sub_f32_e32 v24, v30, v100
	v_exp_f32_e32 v24, v24
	v_add_f32_e32 v48, v111, v110
	v_add_f32_e32 v48, v112, v48
	v_add_f32_e32 v48, v113, v48
	v_cndmask_b32_e64 v116, v24, 0, s[30:31]
	v_sub_f32_e32 v24, v31, v100
	v_exp_f32_e32 v24, v24
	v_add_f32_e32 v48, v114, v48
	v_add_f32_e32 v48, v115, v48
	v_cvt_pk_bf16_f32 v104, v114, v115
	v_cndmask_b32_e64 v117, v24, 0, s[34:35]
	v_pk_mul_f32 v[24:25], v[44:45], v[106:107] op_sel_hi:[1,0]
	v_pk_mul_f32 v[44:45], v[60:61], v[106:107] op_sel_hi:[1,0]
	v_cvt_pk_bf16_f32 v105, v116, v117
	v_mfma_f32_16x16x32_bf16 v[24:27], v[88:91], v[40:43], v[24:27]
	v_add_f32_e32 v48, v116, v48
	v_pk_mul_f32 v[38:39], v[58:59], v[108:109] op_sel_hi:[1,0]
	v_pk_mul_f32 v[36:37], v[56:57], v[108:109] op_sel_hi:[1,0]
	s_waitcnt lgkmcnt(4)
	v_mfma_f32_16x16x32_bf16 v[40:43], v[68:71], v[40:43], v[44:47]
	v_mul_f32_e64 v30, v50, v108
	v_mul_f32_e64 v31, v51, v108
	v_pk_mul_f32 v[22:23], v[22:23], v[108:109] op_sel_hi:[1,0]
	v_pk_mul_f32 v[20:21], v[20:21], v[108:109] op_sel_hi:[1,0]
	v_pk_mul_f32 v[46:47], v[66:67], v[108:109] op_sel_hi:[1,0]
	v_pk_mul_f32 v[44:45], v[64:65], v[108:109] op_sel_hi:[1,0]
	s_waitcnt vmcnt(3)
	s_waitcnt vmcnt(1)
	s_waitcnt vmcnt(0)
	v_mfma_f32_16x16x32_bf16 v[4:7], v[76:79], v[12:15], 0
	v_mfma_f32_16x16x32_bf16 v[10:13], v[92:95], v[12:15], 0
	s_nop 5
	v_sub_u32_e32 v9, v198, v145
	v_cmp_gt_u32_e64 s[34:35], v9, v144
	v_mov_b32_e32 v15, v153
	v_mfma_f32_16x16x32_bf16 v[4:7], v[80:83], v[0:3], v[4:7]
	v_mfma_f32_16x16x32_bf16 v[0:3], v[84:87], v[0:3], v[10:13]
	s_nop 2
	v_add_u32_e32 v12, 1, v9
	v_cmp_gt_u32_e64 s[30:31], v12, v144
	s_nop 1
	v_cndmask_b32_e64 v4, v4, v246, s[34:35]
	s_nop 0
	v_cndmask_b32_e64 v5, v5, v246, s[30:31]
	v_max_f32_e32 v11, v4, v5
	v_add_u32_e32 v12, 2, v9
	v_add_u32_e32 v13, 3, v9
	v_cmp_gt_u32_e64 s[28:29], v12, v144
	v_cmp_gt_u32_e64 s[26:27], v13, v144
	v_mfma_f32_16x16x32_bf16 v[44:47], v[68:71], v[102:105], v[44:47]
	v_cndmask_b32_e64 v6, v6, v246, s[28:29]
	v_cndmask_b32_e64 v7, v7, v246, s[26:27]
	v_max3_f32 v11, v11, v6, v7
	v_add_u32_e32 v12, 16, v9
	v_add_u32_e32 v13, 17, v9
	v_cmp_gt_u32_e64 s[24:25], v12, v144
	v_cmp_gt_u32_e64 s[22:23], v13, v144
	v_add_f32_e32 v68, v117, v48
	v_cndmask_b32_e64 v0, v0, v246, s[24:25]
	v_cndmask_b32_e64 v13, v1, v246, s[22:23]
	v_max3_f32 v11, v11, v0, v13
	v_add_u32_e32 v12, 18, v9
	v_add_u32_e32 v9, 19, v9
	v_cmp_gt_u32_e64 s[0:1], v12, v144
	v_cmp_gt_u32_e32 vcc, v9, v144
	s_nop 0
	v_cndmask_b32_e64 v2, v2, v246, s[0:1]
	s_nop 0
	v_cndmask_b32_e64 v3, v3, v246, vcc
	v_max3_f32 v9, v11, v2, v3
	s_nop 1
	v_mov_b32_e32 v11, v9
	s_nop 1
	v_permlane32_swap_b32_e32 v11, v9
	v_max_f32_e32 v9, v9, v11
	s_nop 1
	v_mov_b32_e32 v11, v9
	s_nop 1
	v_permlane16_swap_b32_e32 v11, v9
	v_max_f32_e32 v9, v9, v11
	v_mov_b32_e32 v66, 1.0
	v_add_f32_e32 v69, v109, v107
	v_mov_b32_e32 v11, 0
	v_mov_b32_e32 v8, 0
	v_fmac_f32_e32 v69, v146, v106
	v_add_f32_e32 v65, v8, v11
	v_cvt_pk_bf16_f32 v14, v8, 0
	v_max_f32_e32 v8, v100, v9
	v_fmac_f32_e32 v65, v69, v66
	v_sub_f32_e32 v4, v4, v8
	v_cvt_pk_bf16_f32 v12, v11, 0
	v_exp_f32_e32 v4, v4
	v_sub_f32_e32 v5, v5, v8
	v_pk_mul_f32 v[10:11], v[34:35], v[66:67] op_sel_hi:[1,0]
	ds_bpermute_b32 v34, v170, v65
	v_exp_f32_e32 v5, v5
	v_sub_f32_e32 v6, v6, v8
	v_exp_f32_e32 v6, v6
	v_sub_f32_e32 v7, v7, v8
	v_exp_f32_e32 v7, v7
	v_sub_f32_e32 v0, v0, v8
	v_sub_f32_e32 v9, v100, v8
	v_exp_f32_e32 v0, v0
	v_sub_f32_e32 v1, v1, v8
	v_mfma_f32_16x16x32_bf16 v[36:39], v[72:75], v[102:105], v[36:39]
	v_exp_f32_e32 v72, v9
	v_exp_f32_e32 v1, v1
	v_sub_f32_e32 v2, v2, v8
	s_waitcnt lgkmcnt(0)
	v_add_f32_e32 v34, v65, v34
	v_add_f32_e32 v9, v5, v4
	v_exp_f32_e32 v2, v2
	v_sub_f32_e32 v3, v3, v8
	ds_bpermute_b32 v35, v171, v34
	v_add_f32_e32 v9, v6, v9
	v_exp_f32_e32 v3, v3
	v_add_f32_e32 v9, v7, v9
	v_add_f32_e32 v9, v0, v9
	v_cndmask_b32_e64 v1, v1, 0, s[22:23]
	ds_read_b64_tr_b16 v[62:63], v169 offset:6912
	ds_read_b64_tr_b16 v[60:61], v169 offset:4608
	ds_read_b64_tr_b16 v[56:57], v169 offset:4640
	ds_read_b64_tr_b16 v[58:59], v169 offset:6944
	ds_read_b64_tr_b16 v[52:53], v169 offset:4672
	ds_read_b64_tr_b16 v[54:55], v169 offset:6976
	ds_read_b64_tr_b16 v[48:49], v169 offset:4704
	ds_read_b64_tr_b16 v[50:51], v169 offset:7008
	v_add_f32_e32 v9, v1, v9
	v_add_f32_e32 v9, v2, v9
	s_waitcnt lgkmcnt(8)
	v_add_f32_e32 v34, v34, v35
	v_fmac_f32_e32 v68, v147, v108
	v_mov_b32_e32 v13, v153
	v_add_f32_e32 v64, v3, v9
	v_pk_mul_f32 v[8:9], v[32:33], v[66:67] op_sel_hi:[1,0]
	v_div_scale_f32 v35, s[0:1], v34, v34, 1.0
	v_fmac_f32_e32 v64, v68, v72
	v_cvt_pk_bf16_f32 v68, v4, v5
	v_cvt_pk_bf16_f32 v69, v6, v7
	v_pk_mul_f32 v[6:7], v[26:27], v[66:67] op_sel_hi:[1,0]
	v_pk_mul_f32 v[4:5], v[24:25], v[66:67] op_sel_hi:[1,0]
	s_waitcnt lgkmcnt(2)
	v_mfma_f32_16x16x32_bf16 v[24:27], v[52:55], v[12:15], v[8:11]
	v_cvt_pk_bf16_f32 v70, v0, v1
	v_cvt_pk_bf16_f32 v71, v2, v3
	v_pk_mul_f32 v[2:3], v[18:19], v[66:67] op_sel_hi:[1,0]
	v_pk_mul_f32 v[8:9], v[36:37], v[72:73] op_sel_hi:[1,0]
	v_rcp_f32_e32 v36, v35
	v_mfma_f32_16x16x32_bf16 v[20:23], v[96:99], v[102:105], v[20:23]
	v_mul_f32_e64 v10, v38, v72
	v_mul_f32_e64 v11, v39, v72
	v_pk_mul_f32 v[0:1], v[16:17], v[66:67] op_sel_hi:[1,0]
	v_fma_f32 v37, -v35, v36, 1.0
	v_fmac_f32_e32 v36, v37, v36
	v_div_scale_f32 v37, vcc, 1.0, v34, 1.0
	v_mul_f32_e32 v38, v37, v36
	v_fma_f32 v39, -v35, v38, v37
	v_mfma_f32_16x16x32_bf16 v[16:19], v[60:63], v[12:15], v[0:3]
	v_fmac_f32_e32 v38, v39, v36
	v_fma_f32 v35, -v35, v38, v37
	v_div_fmas_f32 v35, v35, v36, v38
	v_mfma_f32_16x16x32_bf16 v[28:31], v[88:91], v[102:105], v[28:31]
	v_mul_f32_e64 v2, v22, v72
	v_mul_f32_e64 v3, v23, v72
	v_pk_mul_f32 v[0:1], v[20:21], v[72:73] op_sel_hi:[1,0]
	v_div_fixup_f32 v34, v35, v34, 1.0
	v_mfma_f32_16x16x32_bf16 v[20:23], v[56:59], v[12:15], v[4:7]
	v_lshl_add_u64 v[32:33], v[156:157], 0, s[56:57]
	v_lshlrev_b64 v[36:37], 11, v[162:163]
	v_pk_mul_f32 v[16:17], v[16:17], v[34:35] op_sel_hi:[1,0]
	v_pk_mul_f32 v[18:19], v[18:19], v[34:35] op_sel_hi:[1,0]
	v_pk_mul_f32 v[6:7], v[30:31], v[72:73] op_sel_hi:[1,0]
	v_pk_mul_f32 v[4:5], v[28:29], v[72:73] op_sel_hi:[1,0]
	v_pk_mul_f32 v[30:31], v[42:43], v[66:67] op_sel_hi:[1,0]
	v_pk_mul_f32 v[28:29], v[40:41], v[66:67] op_sel_hi:[1,0]
	v_lshl_add_u64 v[36:37], v[32:33], 0, v[36:37]
	v_cvt_pk_bf16_f32 v16, v16, v17
	v_cvt_pk_bf16_f32 v17, v18, v19
	s_waitcnt lgkmcnt(0)
	v_mfma_f32_16x16x32_bf16 v[28:31], v[48:51], v[12:15], v[28:31]
	global_store_dwordx2 v[36:37], v[16:17], off
	v_pk_mul_f32 v[16:17], v[20:21], v[34:35] op_sel_hi:[1,0]
	v_pk_mul_f32 v[18:19], v[22:23], v[34:35] op_sel_hi:[1,0]
	v_cvt_pk_bf16_f32 v16, v16, v17
	v_cvt_pk_bf16_f32 v17, v18, v19
	global_store_dwordx2 v[36:37], v[16:17], off offset:32
	v_pk_mul_f32 v[16:17], v[24:25], v[34:35] op_sel_hi:[1,0]
	v_pk_mul_f32 v[18:19], v[26:27], v[34:35] op_sel_hi:[1,0]
	v_cvt_pk_bf16_f32 v16, v16, v17
	v_cvt_pk_bf16_f32 v17, v18, v19
	global_store_dwordx2 v[36:37], v[16:17], off offset:64
	v_pk_mul_f32 v[16:17], v[28:29], v[34:35] op_sel_hi:[1,0]
	v_pk_mul_f32 v[18:19], v[30:31], v[34:35] op_sel_hi:[1,0]
	v_cvt_pk_bf16_f32 v16, v16, v17
	v_cvt_pk_bf16_f32 v17, v18, v19
	global_store_dwordx2 v[36:37], v[16:17], off offset:96
	ds_bpermute_b32 v16, v170, v64
	v_mfma_f32_16x16x32_bf16 v[0:3], v[60:63], v[68:71], v[0:3]
	v_mul_f32_e64 v14, v46, v72
	v_mul_f32_e64 v15, v47, v72
	v_pk_mul_f32 v[12:13], v[44:45], v[72:73] op_sel_hi:[1,0]
	s_waitcnt lgkmcnt(0)
	v_add_f32_e32 v16, v64, v16
	ds_bpermute_b32 v17, v171, v16
	v_mfma_f32_16x16x32_bf16 v[4:7], v[56:59], v[68:71], v[4:7]
	s_waitcnt lgkmcnt(0)
	v_add_f32_e32 v16, v16, v17
	v_div_scale_f32 v17, s[0:1], v16, v16, 1.0
	v_rcp_f32_e32 v18, v17
	v_mfma_f32_16x16x32_bf16 v[8:11], v[52:55], v[68:71], v[8:11]
	v_fma_f32 v19, -v17, v18, 1.0
	v_fmac_f32_e32 v18, v19, v18
	v_div_scale_f32 v19, vcc, 1.0, v16, 1.0
	v_mul_f32_e32 v20, v19, v18
	v_fma_f32 v21, -v17, v20, v19
	v_fmac_f32_e32 v20, v21, v18
	v_fma_f32 v17, -v17, v20, v19
	v_div_fmas_f32 v17, v17, v18, v20
	v_div_fixup_f32 v16, v17, v16, 1.0
	v_lshlrev_b64 v[18:19], 11, v[160:161]
	v_pk_mul_f32 v[0:1], v[0:1], v[16:17] op_sel_hi:[1,0]
	v_pk_mul_f32 v[2:3], v[2:3], v[16:17] op_sel_hi:[1,0]
	v_lshl_add_u64 v[18:19], v[32:33], 0, v[18:19]
	v_cvt_pk_bf16_f32 v0, v0, v1
	v_cvt_pk_bf16_f32 v1, v2, v3
	v_mfma_f32_16x16x32_bf16 v[12:15], v[48:51], v[68:71], v[12:15]
	global_store_dwordx2 v[18:19], v[0:1], off
	v_pk_mul_f32 v[0:1], v[4:5], v[16:17] op_sel_hi:[1,0]
	v_pk_mul_f32 v[2:3], v[6:7], v[16:17] op_sel_hi:[1,0]
	v_cvt_pk_bf16_f32 v0, v0, v1
	v_cvt_pk_bf16_f32 v1, v2, v3
	global_store_dwordx2 v[18:19], v[0:1], off offset:32
	v_pk_mul_f32 v[0:1], v[8:9], v[16:17] op_sel_hi:[1,0]
	v_pk_mul_f32 v[2:3], v[10:11], v[16:17] op_sel_hi:[1,0]
	v_cvt_pk_bf16_f32 v0, v0, v1
	v_cvt_pk_bf16_f32 v1, v2, v3
	global_store_dwordx2 v[18:19], v[0:1], off offset:64
	v_pk_mul_f32 v[0:1], v[12:13], v[16:17] op_sel_hi:[1,0]
	v_pk_mul_f32 v[2:3], v[14:15], v[16:17] op_sel_hi:[1,0]
	v_cvt_pk_bf16_f32 v0, v0, v1
	v_cvt_pk_bf16_f32 v1, v2, v3
	global_store_dwordx2 v[18:19], v[0:1], off offset:96
	s_cbranch_scc1 .LBB0_246
	s_mov_b32 s76, s79
	v_readlane_b32 s72, v253, 43
	v_xor_b32_e32 v240, 32, v174
	v_xor_b32_e32 v241, 16, v174
	v_xor_b32_e32 v242, 8, v174
	v_xor_b32_e32 v243, 4, v174
	v_xor_b32_e32 v244, 2, v174
	v_xor_b32_e32 v245, 1, v174
	v_and_b32_e32 v246, 64, v174
